# MFMA order O9T: chained pairs along a Gray path over 2x2 tiles of the (A fragment, B fragment) grid
# baseline (speedup 1.0000x reference)
.LBB0_170:
	ds_read_b128 v[136:139], v191
	ds_read_b128 v[158:161], v191 offset:1024
	ds_read_b128 v[162:165], v191 offset:2048
	ds_read_b128 v[166:169], v191 offset:3072
	ds_read_b128 v[170:173], v192
	ds_read_b128 v[174:177], v192 offset:1024
	ds_read_b128 v[178:181], v192 offset:2048
	ds_read_b128 v[194:197], v192 offset:3072
	s_add_u32 s0, s42, 0xfff00080
	s_addc_u32 s50, s43, -1
	s_cmp_eq_u32 s70, 60
	s_cselect_b32 s53, s23, s50
	s_cselect_b32 s52, s41, s0
	s_cselect_b32 s51, s21, s68
	s_cselect_b32 s50, s66, s67
	s_add_i32 m0, s31, 0xc000
	ds_read_b128 v[198:201], v193
	ds_read_b128 v[202:205], v193 offset:1024
	ds_read_b128 v[206:209], v193 offset:2048
	ds_read_b128 v[210:213], v193 offset:3072
	ds_read_b128 v[214:217], v193 offset:4096
	ds_read_b128 v[218:221], v193 offset:5120
	ds_read_b128 v[222:225], v193 offset:6144
	ds_read_b128 v[226:229], v193 offset:7168
	global_load_lds_dwordx4 v152, s[42:43]
	s_add_i32 m0, s31, 0xe000
	s_nop 0
	global_load_lds_dwordx4 v154, s[42:43]
	s_waitcnt vmcnt(8)
	s_waitcnt lgkmcnt(0)
	s_setprio 1
	s_barrier
	v_mfma_f32_16x16x32_bf16 v[132:135], v[136:139], v[198:201], v[132:135]
	v_mfma_f32_16x16x32_bf16 v[132:135], v[158:161], v[202:205], v[132:135]
	v_mfma_f32_16x16x32_bf16 v[128:131], v[162:165], v[198:201], v[128:131]
	v_mfma_f32_16x16x32_bf16 v[128:131], v[166:169], v[202:205], v[128:131]
	v_mfma_f32_16x16x32_bf16 v[112:115], v[162:165], v[206:209], v[112:115]
	v_mfma_f32_16x16x32_bf16 v[112:115], v[166:169], v[210:213], v[112:115]
	v_mfma_f32_16x16x32_bf16 v[116:119], v[136:139], v[206:209], v[116:119]
	v_mfma_f32_16x16x32_bf16 v[116:119], v[158:161], v[210:213], v[116:119]
	v_mfma_f32_16x16x32_bf16 v[108:111], v[170:173], v[206:209], v[108:111]
	v_mfma_f32_16x16x32_bf16 v[108:111], v[174:177], v[210:213], v[108:111]
	v_mfma_f32_16x16x32_bf16 v[104:107], v[178:181], v[206:209], v[104:107]
	v_mfma_f32_16x16x32_bf16 v[104:107], v[194:197], v[210:213], v[104:107]
	v_mfma_f32_16x16x32_bf16 v[120:123], v[178:181], v[198:201], v[120:123]
	v_mfma_f32_16x16x32_bf16 v[120:123], v[194:197], v[202:205], v[120:123]
	v_mfma_f32_16x16x32_bf16 v[124:127], v[170:173], v[198:201], v[124:127]
	v_mfma_f32_16x16x32_bf16 v[124:127], v[174:177], v[202:205], v[124:127]
	v_mfma_f32_16x16x32_bf16 v[92:95], v[170:173], v[214:217], v[92:95]
	v_mfma_f32_16x16x32_bf16 v[92:95], v[174:177], v[218:221], v[92:95]
	v_mfma_f32_16x16x32_bf16 v[88:91], v[178:181], v[214:217], v[88:91]
	v_mfma_f32_16x16x32_bf16 v[88:91], v[194:197], v[218:221], v[88:91]
	v_mfma_f32_16x16x32_bf16 v[72:75], v[178:181], v[222:225], v[72:75]
	v_mfma_f32_16x16x32_bf16 v[72:75], v[194:197], v[226:229], v[72:75]
	v_mfma_f32_16x16x32_bf16 v[76:79], v[170:173], v[222:225], v[76:79]
	v_mfma_f32_16x16x32_bf16 v[76:79], v[174:177], v[226:229], v[76:79]
	v_mfma_f32_16x16x32_bf16 v[80:83], v[162:165], v[222:225], v[80:83]
	v_mfma_f32_16x16x32_bf16 v[80:83], v[166:169], v[226:229], v[80:83]
	v_mfma_f32_16x16x32_bf16 v[84:87], v[136:139], v[222:225], v[84:87]
	v_mfma_f32_16x16x32_bf16 v[84:87], v[158:161], v[226:229], v[84:87]
	v_mfma_f32_16x16x32_bf16 v[100:103], v[136:139], v[214:217], v[100:103]
	v_mfma_f32_16x16x32_bf16 v[100:103], v[158:161], v[218:221], v[100:103]
	v_mfma_f32_16x16x32_bf16 v[96:99], v[162:165], v[214:217], v[96:99]
	v_mfma_f32_16x16x32_bf16 v[96:99], v[166:169], v[218:221], v[96:99]
	s_setprio 0
	s_barrier
	s_add_i32 s0, s61, s19
	s_mov_b32 m0, s0
	ds_read_b128 v[198:201], v193 offset:16384
	ds_read_b128 v[202:205], v193 offset:17408
	ds_read_b128 v[206:209], v193 offset:18432
	ds_read_b128 v[210:213], v193 offset:19456
	ds_read_b128 v[214:217], v193 offset:20480
	ds_read_b128 v[218:221], v193 offset:21504
	ds_read_b128 v[222:225], v193 offset:22528
	ds_read_b128 v[226:229], v193 offset:23552
	global_load_lds_dwordx4 v142, s[50:51]
	s_add_i32 m0, s0, 0x2000
	s_add_u32 s72, s50, 0x100000
	s_addc_u32 s73, s51, 0
	s_add_i32 s0, s62, s19
	global_load_lds_dwordx4 v146, s[50:51]
	s_mov_b32 m0, s0
	s_nop 0
	global_load_lds_dwordx4 v142, s[72:73]
	s_add_i32 m0, s0, 0x2000
	s_nop 0
	global_load_lds_dwordx4 v146, s[72:73]
	s_mov_b32 m0, s31
	s_nop 0
	global_load_lds_dwordx4 v140, s[52:53]
	s_mov_b32 m0, s35
	s_nop 0
	global_load_lds_dwordx4 v144, s[52:53]
	s_waitcnt vmcnt(8)
	s_waitcnt lgkmcnt(0)
	s_setprio 1
	s_barrier
	v_mfma_f32_16x16x32_bf16 v[68:71], v[136:139], v[198:201], v[68:71]
	v_mfma_f32_16x16x32_bf16 v[68:71], v[158:161], v[202:205], v[68:71]
	v_mfma_f32_16x16x32_bf16 v[64:67], v[162:165], v[198:201], v[64:67]
	v_mfma_f32_16x16x32_bf16 v[64:67], v[166:169], v[202:205], v[64:67]
	v_mfma_f32_16x16x32_bf16 v[48:51], v[162:165], v[206:209], v[48:51]
	v_mfma_f32_16x16x32_bf16 v[48:51], v[166:169], v[210:213], v[48:51]
	v_mfma_f32_16x16x32_bf16 v[52:55], v[136:139], v[206:209], v[52:55]
	v_mfma_f32_16x16x32_bf16 v[52:55], v[158:161], v[210:213], v[52:55]
	v_mfma_f32_16x16x32_bf16 v[44:47], v[170:173], v[206:209], v[44:47]
	v_mfma_f32_16x16x32_bf16 v[44:47], v[174:177], v[210:213], v[44:47]
	v_mfma_f32_16x16x32_bf16 v[40:43], v[178:181], v[206:209], v[40:43]
	v_mfma_f32_16x16x32_bf16 v[40:43], v[194:197], v[210:213], v[40:43]
	v_mfma_f32_16x16x32_bf16 v[56:59], v[178:181], v[198:201], v[56:59]
	v_mfma_f32_16x16x32_bf16 v[56:59], v[194:197], v[202:205], v[56:59]
	v_mfma_f32_16x16x32_bf16 v[60:63], v[170:173], v[198:201], v[60:63]
	v_mfma_f32_16x16x32_bf16 v[60:63], v[174:177], v[202:205], v[60:63]
	v_mfma_f32_16x16x32_bf16 v[28:31], v[170:173], v[214:217], v[28:31]
	v_mfma_f32_16x16x32_bf16 v[28:31], v[174:177], v[218:221], v[28:31]
	v_mfma_f32_16x16x32_bf16 v[24:27], v[178:181], v[214:217], v[24:27]
	v_mfma_f32_16x16x32_bf16 v[24:27], v[194:197], v[218:221], v[24:27]
	v_mfma_f32_16x16x32_bf16 v[6:9], v[178:181], v[222:225], v[8:11]
	v_mfma_f32_16x16x32_bf16 v[6:9], v[194:197], v[226:229], v[6:9]
	v_mfma_f32_16x16x32_bf16 v[12:15], v[170:173], v[222:225], v[12:15]
	v_mfma_f32_16x16x32_bf16 v[12:15], v[174:177], v[226:229], v[12:15]
	v_mfma_f32_16x16x32_bf16 v[16:19], v[162:165], v[222:225], v[16:19]
	v_mfma_f32_16x16x32_bf16 v[16:19], v[166:169], v[226:229], v[16:19]
	v_mfma_f32_16x16x32_bf16 v[20:23], v[136:139], v[222:225], v[20:23]
	v_mfma_f32_16x16x32_bf16 v[20:23], v[158:161], v[226:229], v[20:23]
	v_mfma_f32_16x16x32_bf16 v[36:39], v[136:139], v[214:217], v[36:39]
	v_mfma_f32_16x16x32_bf16 v[36:39], v[158:161], v[218:221], v[36:39]
	v_mfma_f32_16x16x32_bf16 v[32:35], v[162:165], v[214:217], v[32:35]
	v_mfma_f32_16x16x32_bf16 v[32:35], v[166:169], v[218:221], v[32:35]
	s_setprio 0
	s_barrier
	s_add_i32 s0, 0, 0x18000
	v_add_u32_e32 v5, s0, v1
	s_add_i32 s71, 0, 0x1c000
	ds_read_b128 v[136:139], v5
	ds_read_b128 v[158:161], v5 offset:1024
	ds_read_b128 v[162:165], v5 offset:2048
	ds_read_b128 v[166:169], v5 offset:3072
	v_add_u32_e32 v5, s71, v1
	ds_read_b128 v[170:173], v5
	ds_read_b128 v[174:177], v5 offset:1024
	ds_read_b128 v[178:181], v5 offset:2048
	ds_read_b128 v[194:197], v5 offset:3072
	s_add_u32 s98, s52, 0x100000
	s_addc_u32 s99, s53, 0
	s_mov_b32 m0, s45
	ds_read_b128 v[198:201], v193 offset:32768
	ds_read_b128 v[202:205], v193 offset:33792
	ds_read_b128 v[206:209], v193 offset:34816
	ds_read_b128 v[210:213], v193 offset:35840
	ds_read_b128 v[214:217], v193 offset:36864
	ds_read_b128 v[218:221], v193 offset:37888
	ds_read_b128 v[222:225], v193 offset:38912
	ds_read_b128 v[226:229], v193 offset:39936
	global_load_lds_dwordx4 v140, s[98:99]
	s_mov_b32 m0, s46
	s_nop 0
	global_load_lds_dwordx4 v144, s[98:99]
	s_waitcnt vmcnt(8)
	s_waitcnt lgkmcnt(0)
	s_setprio 1
	s_barrier
	v_mfma_f32_16x16x32_bf16 v[132:135], v[136:139], v[198:201], v[132:135]
	v_mfma_f32_16x16x32_bf16 v[132:135], v[158:161], v[202:205], v[132:135]
	v_mfma_f32_16x16x32_bf16 v[128:131], v[162:165], v[198:201], v[128:131]
	v_mfma_f32_16x16x32_bf16 v[128:131], v[166:169], v[202:205], v[128:131]
	v_mfma_f32_16x16x32_bf16 v[112:115], v[162:165], v[206:209], v[112:115]
	v_mfma_f32_16x16x32_bf16 v[112:115], v[166:169], v[210:213], v[112:115]
	v_mfma_f32_16x16x32_bf16 v[116:119], v[136:139], v[206:209], v[116:119]
	v_mfma_f32_16x16x32_bf16 v[116:119], v[158:161], v[210:213], v[116:119]
	v_mfma_f32_16x16x32_bf16 v[108:111], v[170:173], v[206:209], v[108:111]
	v_mfma_f32_16x16x32_bf16 v[108:111], v[174:177], v[210:213], v[108:111]
	v_mfma_f32_16x16x32_bf16 v[104:107], v[178:181], v[206:209], v[104:107]
	v_mfma_f32_16x16x32_bf16 v[104:107], v[194:197], v[210:213], v[104:107]
	v_mfma_f32_16x16x32_bf16 v[120:123], v[178:181], v[198:201], v[120:123]
	v_mfma_f32_16x16x32_bf16 v[120:123], v[194:197], v[202:205], v[120:123]
	v_mfma_f32_16x16x32_bf16 v[124:127], v[170:173], v[198:201], v[124:127]
	v_mfma_f32_16x16x32_bf16 v[124:127], v[174:177], v[202:205], v[124:127]
	v_mfma_f32_16x16x32_bf16 v[92:95], v[170:173], v[214:217], v[92:95]
	v_mfma_f32_16x16x32_bf16 v[92:95], v[174:177], v[218:221], v[92:95]
	v_mfma_f32_16x16x32_bf16 v[88:91], v[178:181], v[214:217], v[88:91]
	v_mfma_f32_16x16x32_bf16 v[88:91], v[194:197], v[218:221], v[88:91]
	v_mfma_f32_16x16x32_bf16 v[72:75], v[178:181], v[222:225], v[72:75]
	v_mfma_f32_16x16x32_bf16 v[72:75], v[194:197], v[226:229], v[72:75]
	v_mfma_f32_16x16x32_bf16 v[76:79], v[170:173], v[222:225], v[76:79]
	v_mfma_f32_16x16x32_bf16 v[76:79], v[174:177], v[226:229], v[76:79]
	v_mfma_f32_16x16x32_bf16 v[80:83], v[162:165], v[222:225], v[80:83]
	v_mfma_f32_16x16x32_bf16 v[80:83], v[166:169], v[226:229], v[80:83]
	v_mfma_f32_16x16x32_bf16 v[84:87], v[136:139], v[222:225], v[84:87]
	v_mfma_f32_16x16x32_bf16 v[84:87], v[158:161], v[226:229], v[84:87]
	v_mfma_f32_16x16x32_bf16 v[100:103], v[136:139], v[214:217], v[100:103]
	v_mfma_f32_16x16x32_bf16 v[100:103], v[158:161], v[218:221], v[100:103]
	v_mfma_f32_16x16x32_bf16 v[96:99], v[162:165], v[214:217], v[96:99]
	v_mfma_f32_16x16x32_bf16 v[96:99], v[166:169], v[218:221], v[96:99]
	s_setprio 0
	s_barrier
	s_add_i32 s0, s0, s19
	s_add_i32 m0, s0, 0xffffff80
	ds_read_b128 v[198:201], v193 offset:49152
	ds_read_b128 v[202:205], v193 offset:50176
	ds_read_b128 v[206:209], v193 offset:51200
	ds_read_b128 v[210:213], v193 offset:52224
	ds_read_b128 v[214:217], v193 offset:53248
	ds_read_b128 v[218:221], v193 offset:54272
	ds_read_b128 v[222:225], v193 offset:55296
	ds_read_b128 v[226:229], v193 offset:56320
	global_load_lds_dwordx4 v142, s[50:51] offset:128
	s_add_i32 m0, s0, 0x1f80
	s_add_i32 s0, s71, s19
	global_load_lds_dwordx4 v146, s[50:51] offset:128
	s_add_u32 s50, s50, 0x100080
	s_addc_u32 s51, s51, 0
	s_mov_b32 m0, s0
	s_nop 0
	global_load_lds_dwordx4 v142, s[50:51]
	s_add_i32 m0, s0, 0x2000
	s_nop 0
	global_load_lds_dwordx4 v146, s[50:51]
	s_add_i32 m0, s56, 0xffffff80
	s_nop 0
	global_load_lds_dwordx4 v140, s[52:53] offset:128
	s_add_i32 m0, s57, 0xffffff80
	s_nop 0
	global_load_lds_dwordx4 v144, s[52:53] offset:128
	s_waitcnt vmcnt(8)
	s_waitcnt lgkmcnt(0)
	s_setprio 1
	s_barrier
	v_mfma_f32_16x16x32_bf16 v[68:71], v[136:139], v[198:201], v[68:71]
	v_mfma_f32_16x16x32_bf16 v[68:71], v[158:161], v[202:205], v[68:71]
	v_mfma_f32_16x16x32_bf16 v[64:67], v[162:165], v[198:201], v[64:67]
	v_mfma_f32_16x16x32_bf16 v[64:67], v[166:169], v[202:205], v[64:67]
	v_mfma_f32_16x16x32_bf16 v[60:63], v[170:173], v[198:201], v[60:63]
	v_mfma_f32_16x16x32_bf16 v[60:63], v[174:177], v[202:205], v[60:63]
	v_mfma_f32_16x16x32_bf16 v[56:59], v[178:181], v[198:201], v[56:59]
	v_mfma_f32_16x16x32_bf16 v[56:59], v[194:197], v[202:205], v[56:59]
	v_mfma_f32_16x16x32_bf16 v[52:55], v[136:139], v[206:209], v[52:55]
	v_mfma_f32_16x16x32_bf16 v[52:55], v[158:161], v[210:213], v[52:55]
	v_mfma_f32_16x16x32_bf16 v[48:51], v[162:165], v[206:209], v[48:51]
	v_mfma_f32_16x16x32_bf16 v[48:51], v[166:169], v[210:213], v[48:51]
	v_mfma_f32_16x16x32_bf16 v[44:47], v[170:173], v[206:209], v[44:47]
	v_mfma_f32_16x16x32_bf16 v[44:47], v[174:177], v[210:213], v[44:47]
	v_mfma_f32_16x16x32_bf16 v[40:43], v[178:181], v[206:209], v[40:43]
	v_mfma_f32_16x16x32_bf16 v[40:43], v[194:197], v[210:213], v[40:43]
	v_mfma_f32_16x16x32_bf16 v[36:39], v[136:139], v[214:217], v[36:39]
	v_mfma_f32_16x16x32_bf16 v[36:39], v[158:161], v[218:221], v[36:39]
	v_mfma_f32_16x16x32_bf16 v[32:35], v[162:165], v[214:217], v[32:35]
	v_mfma_f32_16x16x32_bf16 v[32:35], v[166:169], v[218:221], v[32:35]
	v_mfma_f32_16x16x32_bf16 v[28:31], v[170:173], v[214:217], v[28:31]
	v_mfma_f32_16x16x32_bf16 v[28:31], v[174:177], v[218:221], v[28:31]
	v_mfma_f32_16x16x32_bf16 v[24:27], v[178:181], v[214:217], v[24:27]
	v_mfma_f32_16x16x32_bf16 v[24:27], v[194:197], v[218:221], v[24:27]
	v_mfma_f32_16x16x32_bf16 v[20:23], v[136:139], v[222:225], v[20:23]
	v_mfma_f32_16x16x32_bf16 v[20:23], v[158:161], v[226:229], v[20:23]
	v_mfma_f32_16x16x32_bf16 v[16:19], v[162:165], v[222:225], v[16:19]
	v_mfma_f32_16x16x32_bf16 v[16:19], v[166:169], v[226:229], v[16:19]
	v_mfma_f32_16x16x32_bf16 v[10:13], v[170:173], v[222:225], v[12:15]
	v_mfma_f32_16x16x32_bf16 v[12:15], v[174:177], v[226:229], v[10:13]
	v_mfma_f32_16x16x32_bf16 v[6:9], v[178:181], v[222:225], v[6:9]
	v_mfma_f32_16x16x32_bf16 v[8:11], v[194:197], v[226:229], v[6:9]
	s_setprio 0
	s_barrier
	s_add_i32 s70, s70, 2
	s_add_u32 s42, s42, 0x100
	s_addc_u32 s43, s43, 0
	s_add_u32 s67, s67, 0x100
	s_addc_u32 s68, s68, 0
	s_cmp_gt_u32 s70, 61
	s_cbranch_scc0 .LBB0_170
	s_and_b64 vcc, exec, s[16:17]
	s_cbranch_vccz .LBB0_173
	s_barrier

.LBB0_342:
	ds_read_b128 v[132:135], v209
	ds_read_b128 v[136:139], v209 offset:1024
	ds_read_b128 v[140:143], v209 offset:2048
	ds_read_b128 v[144:147], v209 offset:3072
	ds_read_b128 v[148:151], v210
	ds_read_b128 v[152:155], v210 offset:1024
	ds_read_b128 v[156:159], v210 offset:2048
	ds_read_b128 v[160:163], v210 offset:3072
	s_add_u32 s0, s26, 0xffd50080
	s_addc_u32 s28, s27, -1
	s_cmpk_eq_i32 s62, 0xa8
	s_cselect_b32 s31, s7, s28
	s_cselect_b32 s30, s6, s0
	s_cselect_b32 s29, s25, s61
	s_cselect_b32 s28, s24, s60
	s_add_i32 m0, s43, 0xc000
	ds_read_b128 v[164:167], v211
	ds_read_b128 v[168:171], v211 offset:1024
	ds_read_b128 v[172:175], v211 offset:2048
	ds_read_b128 v[176:179], v211 offset:3072
	ds_read_b128 v[196:199], v211 offset:4096
	ds_read_b128 v[200:203], v211 offset:5120
	ds_read_b128 v[204:207], v211 offset:6144
	ds_read_b128 v[214:217], v211 offset:7168
	global_load_lds_dwordx4 v188, s[26:27]
	s_add_i32 m0, s43, 0xe000
	s_nop 0
	global_load_lds_dwordx4 v190, s[26:27]
	s_waitcnt vmcnt(8)
	s_waitcnt lgkmcnt(0)
	s_setprio 1
	s_barrier
	v_mfma_f32_16x16x32_bf16 v[128:131], v[132:135], v[164:167], v[128:131]
	v_mfma_f32_16x16x32_bf16 v[128:131], v[136:139], v[168:171], v[128:131]
	v_mfma_f32_16x16x32_bf16 v[124:127], v[140:143], v[164:167], v[124:127]
	v_mfma_f32_16x16x32_bf16 v[124:127], v[144:147], v[168:171], v[124:127]
	v_mfma_f32_16x16x32_bf16 v[108:111], v[140:143], v[172:175], v[108:111]
	v_mfma_f32_16x16x32_bf16 v[108:111], v[144:147], v[176:179], v[108:111]
	v_mfma_f32_16x16x32_bf16 v[112:115], v[132:135], v[172:175], v[112:115]
	v_mfma_f32_16x16x32_bf16 v[112:115], v[136:139], v[176:179], v[112:115]
	v_mfma_f32_16x16x32_bf16 v[104:107], v[148:151], v[172:175], v[104:107]
	v_mfma_f32_16x16x32_bf16 v[104:107], v[152:155], v[176:179], v[104:107]
	v_mfma_f32_16x16x32_bf16 v[100:103], v[156:159], v[172:175], v[100:103]
	v_mfma_f32_16x16x32_bf16 v[100:103], v[160:163], v[176:179], v[100:103]
	v_mfma_f32_16x16x32_bf16 v[116:119], v[156:159], v[164:167], v[116:119]
	v_mfma_f32_16x16x32_bf16 v[116:119], v[160:163], v[168:171], v[116:119]
	v_mfma_f32_16x16x32_bf16 v[120:123], v[148:151], v[164:167], v[120:123]
	v_mfma_f32_16x16x32_bf16 v[120:123], v[152:155], v[168:171], v[120:123]
	v_mfma_f32_16x16x32_bf16 v[88:91], v[148:151], v[196:199], v[88:91]
	v_mfma_f32_16x16x32_bf16 v[88:91], v[152:155], v[200:203], v[88:91]
	v_mfma_f32_16x16x32_bf16 v[84:87], v[156:159], v[196:199], v[84:87]
	v_mfma_f32_16x16x32_bf16 v[84:87], v[160:163], v[200:203], v[84:87]
	v_mfma_f32_16x16x32_bf16 v[68:71], v[156:159], v[204:207], v[68:71]
	v_mfma_f32_16x16x32_bf16 v[68:71], v[160:163], v[214:217], v[68:71]
	v_mfma_f32_16x16x32_bf16 v[72:75], v[148:151], v[204:207], v[72:75]
	v_mfma_f32_16x16x32_bf16 v[72:75], v[152:155], v[214:217], v[72:75]
	v_mfma_f32_16x16x32_bf16 v[76:79], v[140:143], v[204:207], v[76:79]
	v_mfma_f32_16x16x32_bf16 v[76:79], v[144:147], v[214:217], v[76:79]
	v_mfma_f32_16x16x32_bf16 v[80:83], v[132:135], v[204:207], v[80:83]
	v_mfma_f32_16x16x32_bf16 v[80:83], v[136:139], v[214:217], v[80:83]
	v_mfma_f32_16x16x32_bf16 v[96:99], v[132:135], v[196:199], v[96:99]
	v_mfma_f32_16x16x32_bf16 v[96:99], v[136:139], v[200:203], v[96:99]
	v_mfma_f32_16x16x32_bf16 v[92:95], v[140:143], v[196:199], v[92:95]
	v_mfma_f32_16x16x32_bf16 v[92:95], v[144:147], v[200:203], v[92:95]
	s_setprio 0
	s_barrier
	s_add_i32 s0, s53, s42
	s_mov_b32 m0, s0
	ds_read_b128 v[164:167], v211 offset:16384
	ds_read_b128 v[168:171], v211 offset:17408
	ds_read_b128 v[172:175], v211 offset:18432
	ds_read_b128 v[176:179], v211 offset:19456
	ds_read_b128 v[196:199], v211 offset:20480
	ds_read_b128 v[200:203], v211 offset:21504
	ds_read_b128 v[204:207], v211 offset:22528
	ds_read_b128 v[214:217], v211 offset:23552
	global_load_lds_dwordx4 v182, s[28:29]
	s_add_i32 m0, s0, 0x2000
	s_add_u32 s64, s28, 0x2b0000
	s_addc_u32 s65, s29, 0
	s_add_i32 s0, s54, s42
	global_load_lds_dwordx4 v186, s[28:29]
	s_mov_b32 m0, s0
	s_nop 0
	global_load_lds_dwordx4 v182, s[64:65]
	s_add_i32 m0, s0, 0x2000
	s_nop 0
	global_load_lds_dwordx4 v186, s[64:65]
	s_mov_b32 m0, s43
	s_nop 0
	global_load_lds_dwordx4 v180, s[30:31]
	s_mov_b32 m0, s45
	s_nop 0
	global_load_lds_dwordx4 v184, s[30:31]
	s_waitcnt vmcnt(8)
	s_waitcnt lgkmcnt(0)
	s_setprio 1
	s_barrier
	v_mfma_f32_16x16x32_bf16 v[64:67], v[132:135], v[164:167], v[64:67]
	v_mfma_f32_16x16x32_bf16 v[64:67], v[136:139], v[168:171], v[64:67]
	v_mfma_f32_16x16x32_bf16 v[60:63], v[140:143], v[164:167], v[60:63]
	v_mfma_f32_16x16x32_bf16 v[60:63], v[144:147], v[168:171], v[60:63]
	v_mfma_f32_16x16x32_bf16 v[44:47], v[140:143], v[172:175], v[44:47]
	v_mfma_f32_16x16x32_bf16 v[44:47], v[144:147], v[176:179], v[44:47]
	v_mfma_f32_16x16x32_bf16 v[48:51], v[132:135], v[172:175], v[48:51]
	v_mfma_f32_16x16x32_bf16 v[48:51], v[136:139], v[176:179], v[48:51]
	v_mfma_f32_16x16x32_bf16 v[40:43], v[148:151], v[172:175], v[40:43]
	v_mfma_f32_16x16x32_bf16 v[40:43], v[152:155], v[176:179], v[40:43]
	v_mfma_f32_16x16x32_bf16 v[36:39], v[156:159], v[172:175], v[36:39]
	v_mfma_f32_16x16x32_bf16 v[36:39], v[160:163], v[176:179], v[36:39]
	v_mfma_f32_16x16x32_bf16 v[52:55], v[156:159], v[164:167], v[52:55]
	v_mfma_f32_16x16x32_bf16 v[52:55], v[160:163], v[168:171], v[52:55]
	v_mfma_f32_16x16x32_bf16 v[56:59], v[148:151], v[164:167], v[56:59]
	v_mfma_f32_16x16x32_bf16 v[56:59], v[152:155], v[168:171], v[56:59]
	v_mfma_f32_16x16x32_bf16 v[24:27], v[148:151], v[196:199], v[24:27]
	v_mfma_f32_16x16x32_bf16 v[24:27], v[152:155], v[200:203], v[24:27]
	v_mfma_f32_16x16x32_bf16 v[20:23], v[156:159], v[196:199], v[20:23]
	v_mfma_f32_16x16x32_bf16 v[20:23], v[160:163], v[200:203], v[20:23]
	v_mfma_f32_16x16x32_bf16 v[4:7], v[156:159], v[204:207], v[4:7]
	v_mfma_f32_16x16x32_bf16 v[4:7], v[160:163], v[214:217], v[4:7]
	v_mfma_f32_16x16x32_bf16 v[8:11], v[148:151], v[204:207], v[8:11]
	v_mfma_f32_16x16x32_bf16 v[8:11], v[152:155], v[214:217], v[8:11]
	v_mfma_f32_16x16x32_bf16 v[12:15], v[140:143], v[204:207], v[12:15]
	v_mfma_f32_16x16x32_bf16 v[12:15], v[144:147], v[214:217], v[12:15]
	v_mfma_f32_16x16x32_bf16 v[16:19], v[132:135], v[204:207], v[16:19]
	v_mfma_f32_16x16x32_bf16 v[16:19], v[136:139], v[214:217], v[16:19]
	v_mfma_f32_16x16x32_bf16 v[32:35], v[132:135], v[196:199], v[32:35]
	v_mfma_f32_16x16x32_bf16 v[32:35], v[136:139], v[200:203], v[32:35]
	v_mfma_f32_16x16x32_bf16 v[28:31], v[140:143], v[196:199], v[28:31]
	v_mfma_f32_16x16x32_bf16 v[28:31], v[144:147], v[200:203], v[28:31]
	s_setprio 0
	s_barrier
	s_add_i32 s0, 0, 0x18000
	s_add_i32 s63, 0, 0x1c000
	v_add_u32_e32 v144, s0, v3
	v_add_u32_e32 v160, s63, v3
	ds_read_b128 v[132:135], v144
	ds_read_b128 v[136:139], v144 offset:1024
	ds_read_b128 v[140:143], v144 offset:2048
	ds_read_b128 v[144:147], v144 offset:3072
	ds_read_b128 v[148:151], v160
	ds_read_b128 v[152:155], v160 offset:1024
	ds_read_b128 v[156:159], v160 offset:2048
	ds_read_b128 v[160:163], v160 offset:3072
	s_add_u32 s98, s30, 0x2b0000
	s_addc_u32 s99, s31, 0
	s_mov_b32 m0, s46
	ds_read_b128 v[164:167], v211 offset:32768
	ds_read_b128 v[168:171], v211 offset:33792
	ds_read_b128 v[172:175], v211 offset:34816
	ds_read_b128 v[176:179], v211 offset:35840
	ds_read_b128 v[196:199], v211 offset:36864
	ds_read_b128 v[200:203], v211 offset:37888
	ds_read_b128 v[204:207], v211 offset:38912
	ds_read_b128 v[214:217], v211 offset:39936
	global_load_lds_dwordx4 v180, s[98:99]
	s_mov_b32 m0, s47
	s_nop 0
	global_load_lds_dwordx4 v184, s[98:99]
	s_waitcnt vmcnt(8)
	s_waitcnt lgkmcnt(0)
	s_setprio 1
	s_barrier
	v_mfma_f32_16x16x32_bf16 v[128:131], v[132:135], v[164:167], v[128:131]
	v_mfma_f32_16x16x32_bf16 v[128:131], v[136:139], v[168:171], v[128:131]
	v_mfma_f32_16x16x32_bf16 v[124:127], v[140:143], v[164:167], v[124:127]
	v_mfma_f32_16x16x32_bf16 v[124:127], v[144:147], v[168:171], v[124:127]
	v_mfma_f32_16x16x32_bf16 v[108:111], v[140:143], v[172:175], v[108:111]
	v_mfma_f32_16x16x32_bf16 v[108:111], v[144:147], v[176:179], v[108:111]
	v_mfma_f32_16x16x32_bf16 v[112:115], v[132:135], v[172:175], v[112:115]
	v_mfma_f32_16x16x32_bf16 v[112:115], v[136:139], v[176:179], v[112:115]
	v_mfma_f32_16x16x32_bf16 v[104:107], v[148:151], v[172:175], v[104:107]
	v_mfma_f32_16x16x32_bf16 v[104:107], v[152:155], v[176:179], v[104:107]
	v_mfma_f32_16x16x32_bf16 v[100:103], v[156:159], v[172:175], v[100:103]
	v_mfma_f32_16x16x32_bf16 v[100:103], v[160:163], v[176:179], v[100:103]
	v_mfma_f32_16x16x32_bf16 v[116:119], v[156:159], v[164:167], v[116:119]
	v_mfma_f32_16x16x32_bf16 v[116:119], v[160:163], v[168:171], v[116:119]
	v_mfma_f32_16x16x32_bf16 v[120:123], v[148:151], v[164:167], v[120:123]
	v_mfma_f32_16x16x32_bf16 v[120:123], v[152:155], v[168:171], v[120:123]
	v_mfma_f32_16x16x32_bf16 v[88:91], v[148:151], v[196:199], v[88:91]
	v_mfma_f32_16x16x32_bf16 v[88:91], v[152:155], v[200:203], v[88:91]
	v_mfma_f32_16x16x32_bf16 v[84:87], v[156:159], v[196:199], v[84:87]
	v_mfma_f32_16x16x32_bf16 v[84:87], v[160:163], v[200:203], v[84:87]
	v_mfma_f32_16x16x32_bf16 v[68:71], v[156:159], v[204:207], v[68:71]
	v_mfma_f32_16x16x32_bf16 v[68:71], v[160:163], v[214:217], v[68:71]
	v_mfma_f32_16x16x32_bf16 v[72:75], v[148:151], v[204:207], v[72:75]
	v_mfma_f32_16x16x32_bf16 v[72:75], v[152:155], v[214:217], v[72:75]
	v_mfma_f32_16x16x32_bf16 v[76:79], v[140:143], v[204:207], v[76:79]
	v_mfma_f32_16x16x32_bf16 v[76:79], v[144:147], v[214:217], v[76:79]
	v_mfma_f32_16x16x32_bf16 v[80:83], v[132:135], v[204:207], v[80:83]
	v_mfma_f32_16x16x32_bf16 v[80:83], v[136:139], v[214:217], v[80:83]
	v_mfma_f32_16x16x32_bf16 v[96:99], v[132:135], v[196:199], v[96:99]
	v_mfma_f32_16x16x32_bf16 v[96:99], v[136:139], v[200:203], v[96:99]
	v_mfma_f32_16x16x32_bf16 v[92:95], v[140:143], v[196:199], v[92:95]
	v_mfma_f32_16x16x32_bf16 v[92:95], v[144:147], v[200:203], v[92:95]
	s_setprio 0
	s_barrier
	s_add_i32 s0, s0, s42
	s_add_i32 m0, s0, 0xffffff80
	ds_read_b128 v[164:167], v211 offset:49152
	ds_read_b128 v[168:171], v211 offset:50176
	ds_read_b128 v[172:175], v211 offset:51200
	ds_read_b128 v[176:179], v211 offset:52224
	ds_read_b128 v[196:199], v211 offset:53248
	ds_read_b128 v[200:203], v211 offset:54272
	ds_read_b128 v[204:207], v211 offset:55296
	ds_read_b128 v[214:217], v211 offset:56320
	global_load_lds_dwordx4 v182, s[28:29] offset:128
	s_add_i32 m0, s0, 0x1f80
	s_add_i32 s0, s63, s42
	global_load_lds_dwordx4 v186, s[28:29] offset:128
	s_add_u32 s28, s28, 0x2b0080
	s_addc_u32 s29, s29, 0
	s_mov_b32 m0, s0
	s_nop 0
	global_load_lds_dwordx4 v182, s[28:29]
	s_add_i32 m0, s0, 0x2000
	s_nop 0
	global_load_lds_dwordx4 v186, s[28:29]
	s_add_i32 m0, s51, 0xffffff80
	s_nop 0
	global_load_lds_dwordx4 v180, s[30:31] offset:128
	s_add_i32 m0, s52, 0xffffff80
	s_nop 0
	global_load_lds_dwordx4 v184, s[30:31] offset:128
	s_waitcnt vmcnt(8)
	s_waitcnt lgkmcnt(0)
	s_setprio 1
	s_barrier
	v_mfma_f32_16x16x32_bf16 v[64:67], v[132:135], v[164:167], v[64:67]
	v_mfma_f32_16x16x32_bf16 v[64:67], v[136:139], v[168:171], v[64:67]
	v_mfma_f32_16x16x32_bf16 v[60:63], v[140:143], v[164:167], v[60:63]
	v_mfma_f32_16x16x32_bf16 v[60:63], v[144:147], v[168:171], v[60:63]
	v_mfma_f32_16x16x32_bf16 v[44:47], v[140:143], v[172:175], v[44:47]
	v_mfma_f32_16x16x32_bf16 v[44:47], v[144:147], v[176:179], v[44:47]
	v_mfma_f32_16x16x32_bf16 v[48:51], v[132:135], v[172:175], v[48:51]
	v_mfma_f32_16x16x32_bf16 v[48:51], v[136:139], v[176:179], v[48:51]
	v_mfma_f32_16x16x32_bf16 v[40:43], v[148:151], v[172:175], v[40:43]
	v_mfma_f32_16x16x32_bf16 v[40:43], v[152:155], v[176:179], v[40:43]
	v_mfma_f32_16x16x32_bf16 v[36:39], v[156:159], v[172:175], v[36:39]
	v_mfma_f32_16x16x32_bf16 v[36:39], v[160:163], v[176:179], v[36:39]
	v_mfma_f32_16x16x32_bf16 v[52:55], v[156:159], v[164:167], v[52:55]
	v_mfma_f32_16x16x32_bf16 v[52:55], v[160:163], v[168:171], v[52:55]
	v_mfma_f32_16x16x32_bf16 v[56:59], v[148:151], v[164:167], v[56:59]
	v_mfma_f32_16x16x32_bf16 v[56:59], v[152:155], v[168:171], v[56:59]
	v_mfma_f32_16x16x32_bf16 v[24:27], v[148:151], v[196:199], v[24:27]
	v_mfma_f32_16x16x32_bf16 v[24:27], v[152:155], v[200:203], v[24:27]
	v_mfma_f32_16x16x32_bf16 v[20:23], v[156:159], v[196:199], v[20:23]
	v_mfma_f32_16x16x32_bf16 v[20:23], v[160:163], v[200:203], v[20:23]
	v_mfma_f32_16x16x32_bf16 v[4:7], v[156:159], v[204:207], v[4:7]
	v_mfma_f32_16x16x32_bf16 v[4:7], v[160:163], v[214:217], v[4:7]
	v_mfma_f32_16x16x32_bf16 v[8:11], v[148:151], v[204:207], v[8:11]
	v_mfma_f32_16x16x32_bf16 v[8:11], v[152:155], v[214:217], v[8:11]
	v_mfma_f32_16x16x32_bf16 v[12:15], v[140:143], v[204:207], v[12:15]
	v_mfma_f32_16x16x32_bf16 v[12:15], v[144:147], v[214:217], v[12:15]
	v_mfma_f32_16x16x32_bf16 v[16:19], v[132:135], v[204:207], v[16:19]
	v_mfma_f32_16x16x32_bf16 v[16:19], v[136:139], v[214:217], v[16:19]
	v_mfma_f32_16x16x32_bf16 v[32:35], v[132:135], v[196:199], v[32:35]
	v_mfma_f32_16x16x32_bf16 v[32:35], v[136:139], v[200:203], v[32:35]
	v_mfma_f32_16x16x32_bf16 v[28:31], v[140:143], v[196:199], v[28:31]
	v_mfma_f32_16x16x32_bf16 v[28:31], v[144:147], v[200:203], v[28:31]
	s_setprio 0
	s_barrier
	s_add_i32 s62, s62, 2
	s_add_u32 s26, s26, 0x100
	s_addc_u32 s27, s27, 0
	s_add_u32 s60, s60, 0x100
	s_addc_u32 s61, s61, 0
	s_cmpk_gt_u32 s62, 0xa9
	s_cbranch_scc0 .LBB0_342
	s_and_b64 vcc, exec, s[22:23]
	s_cbranch_vccz .LBB0_345
	s_barrier

.LBB0_429:
	ds_read_b128 v[150:153], v156
	ds_read_b128 v[162:165], v156 offset:1024
	ds_read_b128 v[166:169], v156 offset:2048
	ds_read_b128 v[170:173], v156 offset:3072
	ds_read_b128 v[174:177], v157
	ds_read_b128 v[178:181], v157 offset:1024
	ds_read_b128 v[182:185], v157 offset:2048
	ds_read_b128 v[186:189], v157 offset:3072
	s_add_u32 s0, s50, 0xfff00080
	s_addc_u32 s52, s51, -1
	s_cmp_eq_u32 s72, 60
	s_cselect_b32 s55, s27, s52
	s_cselect_b32 s54, s67, s0
	s_cselect_b32 s53, s25, s71
	s_cselect_b32 s52, s68, s70
	s_add_i32 m0, s43, 0xc000
	ds_read_b128 v[190:193], v158
	ds_read_b128 v[194:197], v158 offset:1024
	ds_read_b128 v[198:201], v158 offset:2048
	ds_read_b128 v[202:205], v158 offset:3072
	ds_read_b128 v[206:209], v158 offset:4096
	ds_read_b128 v[210:213], v158 offset:5120
	ds_read_b128 v[214:217], v158 offset:6144
	ds_read_b128 v[218:221], v158 offset:7168
	global_load_lds_dwordx4 v142, s[50:51]
	s_add_i32 m0, s43, 0xe000
	s_nop 0
	global_load_lds_dwordx4 v144, s[50:51]
	s_waitcnt vmcnt(8)
	s_waitcnt lgkmcnt(0)
	s_setprio 1
	s_barrier
	v_mfma_f32_16x16x32_bf16 v[128:131], v[150:153], v[190:193], v[128:131]
	v_mfma_f32_16x16x32_bf16 v[128:131], v[162:165], v[194:197], v[128:131]
	v_mfma_f32_16x16x32_bf16 v[124:127], v[166:169], v[190:193], v[124:127]
	v_mfma_f32_16x16x32_bf16 v[124:127], v[170:173], v[194:197], v[124:127]
	v_mfma_f32_16x16x32_bf16 v[108:111], v[166:169], v[198:201], v[108:111]
	v_mfma_f32_16x16x32_bf16 v[108:111], v[170:173], v[202:205], v[108:111]
	v_mfma_f32_16x16x32_bf16 v[112:115], v[150:153], v[198:201], v[112:115]
	v_mfma_f32_16x16x32_bf16 v[112:115], v[162:165], v[202:205], v[112:115]
	v_mfma_f32_16x16x32_bf16 v[104:107], v[174:177], v[198:201], v[104:107]
	v_mfma_f32_16x16x32_bf16 v[104:107], v[178:181], v[202:205], v[104:107]
	v_mfma_f32_16x16x32_bf16 v[100:103], v[182:185], v[198:201], v[100:103]
	v_mfma_f32_16x16x32_bf16 v[100:103], v[186:189], v[202:205], v[100:103]
	v_mfma_f32_16x16x32_bf16 v[116:119], v[182:185], v[190:193], v[116:119]
	v_mfma_f32_16x16x32_bf16 v[116:119], v[186:189], v[194:197], v[116:119]
	v_mfma_f32_16x16x32_bf16 v[120:123], v[174:177], v[190:193], v[120:123]
	v_mfma_f32_16x16x32_bf16 v[120:123], v[178:181], v[194:197], v[120:123]
	v_mfma_f32_16x16x32_bf16 v[88:91], v[174:177], v[206:209], v[88:91]
	v_mfma_f32_16x16x32_bf16 v[88:91], v[178:181], v[210:213], v[88:91]
	v_mfma_f32_16x16x32_bf16 v[84:87], v[182:185], v[206:209], v[84:87]
	v_mfma_f32_16x16x32_bf16 v[84:87], v[186:189], v[210:213], v[84:87]
	v_mfma_f32_16x16x32_bf16 v[68:71], v[182:185], v[214:217], v[68:71]
	v_mfma_f32_16x16x32_bf16 v[68:71], v[186:189], v[218:221], v[68:71]
	v_mfma_f32_16x16x32_bf16 v[72:75], v[174:177], v[214:217], v[72:75]
	v_mfma_f32_16x16x32_bf16 v[72:75], v[178:181], v[218:221], v[72:75]
	v_mfma_f32_16x16x32_bf16 v[76:79], v[166:169], v[214:217], v[76:79]
	v_mfma_f32_16x16x32_bf16 v[76:79], v[170:173], v[218:221], v[76:79]
	v_mfma_f32_16x16x32_bf16 v[80:83], v[150:153], v[214:217], v[80:83]
	v_mfma_f32_16x16x32_bf16 v[80:83], v[162:165], v[218:221], v[80:83]
	v_mfma_f32_16x16x32_bf16 v[96:99], v[150:153], v[206:209], v[96:99]
	v_mfma_f32_16x16x32_bf16 v[96:99], v[162:165], v[210:213], v[96:99]
	v_mfma_f32_16x16x32_bf16 v[92:95], v[166:169], v[206:209], v[92:95]
	v_mfma_f32_16x16x32_bf16 v[92:95], v[170:173], v[210:213], v[92:95]
	s_setprio 0
	s_barrier
	s_add_i32 s0, s62, s41
	s_mov_b32 m0, s0
	ds_read_b128 v[190:193], v158 offset:16384
	ds_read_b128 v[194:197], v158 offset:17408
	ds_read_b128 v[198:201], v158 offset:18432
	ds_read_b128 v[202:205], v158 offset:19456
	ds_read_b128 v[206:209], v158 offset:20480
	ds_read_b128 v[210:213], v158 offset:21504
	ds_read_b128 v[214:217], v158 offset:22528
	ds_read_b128 v[218:221], v158 offset:23552
	global_load_lds_dwordx4 v136, s[52:53]
	s_add_i32 m0, s0, 0x2000
	s_add_u32 s74, s52, 0x100000
	s_addc_u32 s75, s53, 0
	s_add_i32 s0, s63, s41
	global_load_lds_dwordx4 v140, s[52:53]
	s_mov_b32 m0, s0
	s_nop 0
	global_load_lds_dwordx4 v136, s[74:75]
	s_add_i32 m0, s0, 0x2000
	s_nop 0
	global_load_lds_dwordx4 v140, s[74:75]
	s_mov_b32 m0, s43
	s_nop 0
	global_load_lds_dwordx4 v134, s[54:55]
	s_mov_b32 m0, s48
	s_nop 0
	global_load_lds_dwordx4 v138, s[54:55]
	s_waitcnt vmcnt(8)
	s_waitcnt lgkmcnt(0)
	s_setprio 1
	s_barrier
	v_mfma_f32_16x16x32_bf16 v[64:67], v[150:153], v[190:193], v[64:67]
	v_mfma_f32_16x16x32_bf16 v[64:67], v[162:165], v[194:197], v[64:67]
	v_mfma_f32_16x16x32_bf16 v[60:63], v[166:169], v[190:193], v[60:63]
	v_mfma_f32_16x16x32_bf16 v[60:63], v[170:173], v[194:197], v[60:63]
	v_mfma_f32_16x16x32_bf16 v[44:47], v[166:169], v[198:201], v[44:47]
	v_mfma_f32_16x16x32_bf16 v[44:47], v[170:173], v[202:205], v[44:47]
	v_mfma_f32_16x16x32_bf16 v[48:51], v[150:153], v[198:201], v[48:51]
	v_mfma_f32_16x16x32_bf16 v[48:51], v[162:165], v[202:205], v[48:51]
	v_mfma_f32_16x16x32_bf16 v[40:43], v[174:177], v[198:201], v[40:43]
	v_mfma_f32_16x16x32_bf16 v[40:43], v[178:181], v[202:205], v[40:43]
	v_mfma_f32_16x16x32_bf16 v[36:39], v[182:185], v[198:201], v[36:39]
	v_mfma_f32_16x16x32_bf16 v[36:39], v[186:189], v[202:205], v[36:39]
	v_mfma_f32_16x16x32_bf16 v[52:55], v[182:185], v[190:193], v[52:55]
	v_mfma_f32_16x16x32_bf16 v[52:55], v[186:189], v[194:197], v[52:55]
	v_mfma_f32_16x16x32_bf16 v[56:59], v[174:177], v[190:193], v[56:59]
	v_mfma_f32_16x16x32_bf16 v[56:59], v[178:181], v[194:197], v[56:59]
	v_mfma_f32_16x16x32_bf16 v[24:27], v[174:177], v[206:209], v[24:27]
	v_mfma_f32_16x16x32_bf16 v[24:27], v[178:181], v[210:213], v[24:27]
	v_mfma_f32_16x16x32_bf16 v[20:23], v[182:185], v[206:209], v[20:23]
	v_mfma_f32_16x16x32_bf16 v[20:23], v[186:189], v[210:213], v[20:23]
	v_mfma_f32_16x16x32_bf16 v[4:7], v[182:185], v[214:217], v[4:7]
	v_mfma_f32_16x16x32_bf16 v[4:7], v[186:189], v[218:221], v[4:7]
	v_mfma_f32_16x16x32_bf16 v[8:11], v[174:177], v[214:217], v[8:11]
	v_mfma_f32_16x16x32_bf16 v[8:11], v[178:181], v[218:221], v[8:11]
	v_mfma_f32_16x16x32_bf16 v[12:15], v[166:169], v[214:217], v[12:15]
	v_mfma_f32_16x16x32_bf16 v[12:15], v[170:173], v[218:221], v[12:15]
	v_mfma_f32_16x16x32_bf16 v[16:19], v[150:153], v[214:217], v[16:19]
	v_mfma_f32_16x16x32_bf16 v[16:19], v[162:165], v[218:221], v[16:19]
	v_mfma_f32_16x16x32_bf16 v[32:35], v[150:153], v[206:209], v[32:35]
	v_mfma_f32_16x16x32_bf16 v[32:35], v[162:165], v[210:213], v[32:35]
	v_mfma_f32_16x16x32_bf16 v[28:31], v[166:169], v[206:209], v[28:31]
	v_mfma_f32_16x16x32_bf16 v[28:31], v[170:173], v[210:213], v[28:31]
	s_setprio 0
	s_barrier
	s_add_i32 s0, 0, 0x18000
	v_add_u32_e32 v161, s0, v133
	s_add_i32 s73, 0, 0x1c000
	ds_read_b128 v[150:153], v161
	ds_read_b128 v[162:165], v161 offset:1024
	ds_read_b128 v[166:169], v161 offset:2048
	ds_read_b128 v[170:173], v161 offset:3072
	v_add_u32_e32 v161, s73, v133
	ds_read_b128 v[174:177], v161
	ds_read_b128 v[178:181], v161 offset:1024
	ds_read_b128 v[182:185], v161 offset:2048
	ds_read_b128 v[186:189], v161 offset:3072
	s_add_u32 s98, s54, 0x100000
	s_addc_u32 s99, s55, 0
	s_mov_b32 m0, s49
	ds_read_b128 v[190:193], v158 offset:32768
	ds_read_b128 v[194:197], v158 offset:33792
	ds_read_b128 v[198:201], v158 offset:34816
	ds_read_b128 v[202:205], v158 offset:35840
	ds_read_b128 v[206:209], v158 offset:36864
	ds_read_b128 v[210:213], v158 offset:37888
	ds_read_b128 v[214:217], v158 offset:38912
	ds_read_b128 v[218:221], v158 offset:39936
	global_load_lds_dwordx4 v134, s[98:99]
	s_mov_b32 m0, s56
	s_nop 0
	global_load_lds_dwordx4 v138, s[98:99]
	s_waitcnt vmcnt(8)
	s_waitcnt lgkmcnt(0)
	s_setprio 1
	s_barrier
	v_mfma_f32_16x16x32_bf16 v[128:131], v[150:153], v[190:193], v[128:131]
	v_mfma_f32_16x16x32_bf16 v[128:131], v[162:165], v[194:197], v[128:131]
	v_mfma_f32_16x16x32_bf16 v[124:127], v[166:169], v[190:193], v[124:127]
	v_mfma_f32_16x16x32_bf16 v[124:127], v[170:173], v[194:197], v[124:127]
	v_mfma_f32_16x16x32_bf16 v[108:111], v[166:169], v[198:201], v[108:111]
	v_mfma_f32_16x16x32_bf16 v[108:111], v[170:173], v[202:205], v[108:111]
	v_mfma_f32_16x16x32_bf16 v[112:115], v[150:153], v[198:201], v[112:115]
	v_mfma_f32_16x16x32_bf16 v[112:115], v[162:165], v[202:205], v[112:115]
	v_mfma_f32_16x16x32_bf16 v[104:107], v[174:177], v[198:201], v[104:107]
	v_mfma_f32_16x16x32_bf16 v[104:107], v[178:181], v[202:205], v[104:107]
	v_mfma_f32_16x16x32_bf16 v[100:103], v[182:185], v[198:201], v[100:103]
	v_mfma_f32_16x16x32_bf16 v[100:103], v[186:189], v[202:205], v[100:103]
	v_mfma_f32_16x16x32_bf16 v[116:119], v[182:185], v[190:193], v[116:119]
	v_mfma_f32_16x16x32_bf16 v[116:119], v[186:189], v[194:197], v[116:119]
	v_mfma_f32_16x16x32_bf16 v[120:123], v[174:177], v[190:193], v[120:123]
	v_mfma_f32_16x16x32_bf16 v[120:123], v[178:181], v[194:197], v[120:123]
	v_mfma_f32_16x16x32_bf16 v[88:91], v[174:177], v[206:209], v[88:91]
	v_mfma_f32_16x16x32_bf16 v[88:91], v[178:181], v[210:213], v[88:91]
	v_mfma_f32_16x16x32_bf16 v[84:87], v[182:185], v[206:209], v[84:87]
	v_mfma_f32_16x16x32_bf16 v[84:87], v[186:189], v[210:213], v[84:87]
	v_mfma_f32_16x16x32_bf16 v[68:71], v[182:185], v[214:217], v[68:71]
	v_mfma_f32_16x16x32_bf16 v[68:71], v[186:189], v[218:221], v[68:71]
	v_mfma_f32_16x16x32_bf16 v[72:75], v[174:177], v[214:217], v[72:75]
	v_mfma_f32_16x16x32_bf16 v[72:75], v[178:181], v[218:221], v[72:75]
	v_mfma_f32_16x16x32_bf16 v[76:79], v[166:169], v[214:217], v[76:79]
	v_mfma_f32_16x16x32_bf16 v[76:79], v[170:173], v[218:221], v[76:79]
	v_mfma_f32_16x16x32_bf16 v[80:83], v[150:153], v[214:217], v[80:83]
	v_mfma_f32_16x16x32_bf16 v[80:83], v[162:165], v[218:221], v[80:83]
	v_mfma_f32_16x16x32_bf16 v[96:99], v[150:153], v[206:209], v[96:99]
	v_mfma_f32_16x16x32_bf16 v[96:99], v[162:165], v[210:213], v[96:99]
	v_mfma_f32_16x16x32_bf16 v[92:95], v[166:169], v[206:209], v[92:95]
	v_mfma_f32_16x16x32_bf16 v[92:95], v[170:173], v[210:213], v[92:95]
	s_setprio 0
	s_barrier
	s_add_i32 s0, s0, s41
	s_add_i32 m0, s0, 0xffffff80
	ds_read_b128 v[190:193], v158 offset:49152
	ds_read_b128 v[194:197], v158 offset:50176
	ds_read_b128 v[198:201], v158 offset:51200
	ds_read_b128 v[202:205], v158 offset:52224
	ds_read_b128 v[206:209], v158 offset:53248
	ds_read_b128 v[210:213], v158 offset:54272
	ds_read_b128 v[214:217], v158 offset:55296
	ds_read_b128 v[218:221], v158 offset:56320
	global_load_lds_dwordx4 v136, s[52:53] offset:128
	s_add_i32 m0, s0, 0x1f80
	s_add_i32 s0, s73, s41
	global_load_lds_dwordx4 v140, s[52:53] offset:128
	s_add_u32 s52, s52, 0x100080
	s_addc_u32 s53, s53, 0
	s_mov_b32 m0, s0
	s_nop 0
	global_load_lds_dwordx4 v136, s[52:53]
	s_add_i32 m0, s0, 0x2000
	s_nop 0
	global_load_lds_dwordx4 v140, s[52:53]
	s_add_i32 m0, s59, 0xffffff80
	s_nop 0
	global_load_lds_dwordx4 v134, s[54:55] offset:128
	s_add_i32 m0, s60, 0xffffff80
	s_nop 0
	global_load_lds_dwordx4 v138, s[54:55] offset:128
	s_waitcnt vmcnt(8)
	s_waitcnt lgkmcnt(0)
	s_setprio 1
	s_barrier
	v_mfma_f32_16x16x32_bf16 v[64:67], v[150:153], v[190:193], v[64:67]
	v_mfma_f32_16x16x32_bf16 v[64:67], v[162:165], v[194:197], v[64:67]
	v_mfma_f32_16x16x32_bf16 v[60:63], v[166:169], v[190:193], v[60:63]
	v_mfma_f32_16x16x32_bf16 v[60:63], v[170:173], v[194:197], v[60:63]
	v_mfma_f32_16x16x32_bf16 v[44:47], v[166:169], v[198:201], v[44:47]
	v_mfma_f32_16x16x32_bf16 v[44:47], v[170:173], v[202:205], v[44:47]
	v_mfma_f32_16x16x32_bf16 v[48:51], v[150:153], v[198:201], v[48:51]
	v_mfma_f32_16x16x32_bf16 v[48:51], v[162:165], v[202:205], v[48:51]
	v_mfma_f32_16x16x32_bf16 v[40:43], v[174:177], v[198:201], v[40:43]
	v_mfma_f32_16x16x32_bf16 v[40:43], v[178:181], v[202:205], v[40:43]
	v_mfma_f32_16x16x32_bf16 v[36:39], v[182:185], v[198:201], v[36:39]
	v_mfma_f32_16x16x32_bf16 v[36:39], v[186:189], v[202:205], v[36:39]
	v_mfma_f32_16x16x32_bf16 v[52:55], v[182:185], v[190:193], v[52:55]
	v_mfma_f32_16x16x32_bf16 v[52:55], v[186:189], v[194:197], v[52:55]
	v_mfma_f32_16x16x32_bf16 v[56:59], v[174:177], v[190:193], v[56:59]
	v_mfma_f32_16x16x32_bf16 v[56:59], v[178:181], v[194:197], v[56:59]
	v_mfma_f32_16x16x32_bf16 v[24:27], v[174:177], v[206:209], v[24:27]
	v_mfma_f32_16x16x32_bf16 v[24:27], v[178:181], v[210:213], v[24:27]
	v_mfma_f32_16x16x32_bf16 v[20:23], v[182:185], v[206:209], v[20:23]
	v_mfma_f32_16x16x32_bf16 v[20:23], v[186:189], v[210:213], v[20:23]
	v_mfma_f32_16x16x32_bf16 v[4:7], v[182:185], v[214:217], v[4:7]
	v_mfma_f32_16x16x32_bf16 v[4:7], v[186:189], v[218:221], v[4:7]
	v_mfma_f32_16x16x32_bf16 v[8:11], v[174:177], v[214:217], v[8:11]
	v_mfma_f32_16x16x32_bf16 v[8:11], v[178:181], v[218:221], v[8:11]
	v_mfma_f32_16x16x32_bf16 v[12:15], v[166:169], v[214:217], v[12:15]
	v_mfma_f32_16x16x32_bf16 v[12:15], v[170:173], v[218:221], v[12:15]
	v_mfma_f32_16x16x32_bf16 v[16:19], v[150:153], v[214:217], v[16:19]
	v_mfma_f32_16x16x32_bf16 v[16:19], v[162:165], v[218:221], v[16:19]
	v_mfma_f32_16x16x32_bf16 v[32:35], v[150:153], v[206:209], v[32:35]
	v_mfma_f32_16x16x32_bf16 v[32:35], v[162:165], v[210:213], v[32:35]
	v_mfma_f32_16x16x32_bf16 v[28:31], v[166:169], v[206:209], v[28:31]
	v_mfma_f32_16x16x32_bf16 v[28:31], v[170:173], v[210:213], v[28:31]
	s_setprio 0
	s_barrier
	s_add_i32 s72, s72, 2
	s_add_u32 s50, s50, 0x100
	s_addc_u32 s51, s51, 0
	s_add_u32 s70, s70, 0x100
	s_addc_u32 s71, s71, 0
	s_cmp_gt_u32 s72, 61
	s_cbranch_scc0 .LBB0_429
	s_and_b64 vcc, exec, s[22:23]
	s_cbranch_vccz .LBB0_432
	s_barrier

.LBB0_1032:
	v_add_u32_e32 v5, s60, v3
	ds_read_b128 v[140:143], v5
	ds_read_b128 v[144:147], v5 offset:1024
	ds_read_b128 v[148:151], v5 offset:2048
	ds_read_b128 v[152:155], v5 offset:3072
	v_add_u32_e32 v5, s61, v3
	ds_read_b128 v[156:159], v5
	ds_read_b128 v[160:163], v5 offset:1024
	ds_read_b128 v[164:167], v5 offset:2048
	ds_read_b128 v[168:171], v5 offset:3072
	s_add_u32 s42, s40, 0xfff80080
	s_addc_u32 s43, s41, -1
	s_cmp_eq_u32 s67, 28
	s_cselect_b32 s51, s5, s43
	s_cselect_b32 s50, s7, s42
	s_cselect_b32 s43, s25, s66
	s_cselect_b32 s42, s27, s65
	s_add_i32 m0, s47, 0xc000
	ds_read_b128 v[172:175], v246
	ds_read_b128 v[176:179], v246 offset:1024
	ds_read_b128 v[180:183], v246 offset:2048
	ds_read_b128 v[184:187], v246 offset:3072
	ds_read_b128 v[188:191], v246 offset:4096
	ds_read_b128 v[192:195], v246 offset:5120
	ds_read_b128 v[196:199], v246 offset:6144
	ds_read_b128 v[200:203], v246 offset:7168
	global_load_lds_dwordx4 v216, s[40:41]
	s_add_i32 m0, s47, 0xe000
	s_nop 0
	global_load_lds_dwordx4 v218, s[40:41]
	s_waitcnt vmcnt(8)
	s_waitcnt lgkmcnt(0)
	s_setprio 1
	s_barrier
	v_mfma_f32_16x16x32_bf16 v[136:139], v[140:143], v[172:175], v[136:139]
	v_mfma_f32_16x16x32_bf16 v[136:139], v[144:147], v[176:179], v[136:139]
	v_mfma_f32_16x16x32_bf16 v[132:135], v[148:151], v[172:175], v[132:135]
	v_mfma_f32_16x16x32_bf16 v[132:135], v[152:155], v[176:179], v[132:135]
	v_mfma_f32_16x16x32_bf16 v[124:127], v[148:151], v[180:183], v[124:127]
	v_mfma_f32_16x16x32_bf16 v[124:127], v[152:155], v[184:187], v[124:127]
	v_mfma_f32_16x16x32_bf16 v[128:131], v[140:143], v[180:183], v[128:131]
	v_mfma_f32_16x16x32_bf16 v[128:131], v[144:147], v[184:187], v[128:131]
	v_mfma_f32_16x16x32_bf16 v[96:99], v[156:159], v[180:183], v[96:99]
	v_mfma_f32_16x16x32_bf16 v[96:99], v[160:163], v[184:187], v[96:99]
	v_mfma_f32_16x16x32_bf16 v[92:95], v[164:167], v[180:183], v[92:95]
	v_mfma_f32_16x16x32_bf16 v[92:95], v[168:171], v[184:187], v[92:95]
	v_mfma_f32_16x16x32_bf16 v[100:103], v[164:167], v[172:175], v[100:103]
	v_mfma_f32_16x16x32_bf16 v[100:103], v[168:171], v[176:179], v[100:103]
	v_mfma_f32_16x16x32_bf16 v[104:107], v[156:159], v[172:175], v[104:107]
	v_mfma_f32_16x16x32_bf16 v[104:107], v[160:163], v[176:179], v[104:107]
	v_mfma_f32_16x16x32_bf16 v[88:91], v[156:159], v[188:191], v[88:91]
	v_mfma_f32_16x16x32_bf16 v[88:91], v[160:163], v[192:195], v[88:91]
	v_mfma_f32_16x16x32_bf16 v[84:87], v[164:167], v[188:191], v[84:87]
	v_mfma_f32_16x16x32_bf16 v[84:87], v[168:171], v[192:195], v[84:87]
	v_mfma_f32_16x16x32_bf16 v[76:79], v[164:167], v[196:199], v[76:79]
	v_mfma_f32_16x16x32_bf16 v[76:79], v[168:171], v[200:203], v[76:79]
	v_mfma_f32_16x16x32_bf16 v[80:83], v[156:159], v[196:199], v[80:83]
	v_mfma_f32_16x16x32_bf16 v[80:83], v[160:163], v[200:203], v[80:83]
	v_mfma_f32_16x16x32_bf16 v[108:111], v[148:151], v[196:199], v[108:111]
	v_mfma_f32_16x16x32_bf16 v[108:111], v[152:155], v[200:203], v[108:111]
	v_mfma_f32_16x16x32_bf16 v[112:115], v[140:143], v[196:199], v[112:115]
	v_mfma_f32_16x16x32_bf16 v[112:115], v[144:147], v[200:203], v[112:115]
	v_mfma_f32_16x16x32_bf16 v[120:123], v[140:143], v[188:191], v[120:123]
	v_mfma_f32_16x16x32_bf16 v[120:123], v[144:147], v[192:195], v[120:123]
	v_mfma_f32_16x16x32_bf16 v[116:119], v[148:151], v[188:191], v[116:119]
	v_mfma_f32_16x16x32_bf16 v[116:119], v[152:155], v[192:195], v[116:119]
	s_setprio 0
	s_barrier
	s_add_i32 s68, s60, s46
	s_mov_b32 m0, s68
	ds_read_b128 v[172:175], v246 offset:16384
	ds_read_b128 v[176:179], v246 offset:17408
	ds_read_b128 v[180:183], v246 offset:18432
	ds_read_b128 v[184:187], v246 offset:19456
	ds_read_b128 v[188:191], v246 offset:20480
	ds_read_b128 v[192:195], v246 offset:21504
	ds_read_b128 v[196:199], v246 offset:22528
	ds_read_b128 v[200:203], v246 offset:23552
	global_load_lds_dwordx4 v210, s[42:43]
	s_add_i32 m0, s68, 0x2000
	s_add_u32 s70, s42, 0x80000
	s_addc_u32 s71, s43, 0
	s_add_i32 s68, s61, s46
	global_load_lds_dwordx4 v214, s[42:43]
	s_mov_b32 m0, s68
	s_nop 0
	global_load_lds_dwordx4 v210, s[70:71]
	s_add_i32 m0, s68, 0x2000
	s_nop 0
	global_load_lds_dwordx4 v214, s[70:71]
	s_mov_b32 m0, s47
	s_nop 0
	global_load_lds_dwordx4 v208, s[50:51]
	s_mov_b32 m0, s48
	s_nop 0
	global_load_lds_dwordx4 v212, s[50:51]
	s_waitcnt vmcnt(8)
	s_waitcnt lgkmcnt(0)
	s_setprio 1
	s_barrier
	v_mfma_f32_16x16x32_bf16 v[72:75], v[140:143], v[172:175], v[72:75]
	v_mfma_f32_16x16x32_bf16 v[72:75], v[144:147], v[176:179], v[72:75]
	v_mfma_f32_16x16x32_bf16 v[68:71], v[148:151], v[172:175], v[68:71]
	v_mfma_f32_16x16x32_bf16 v[68:71], v[152:155], v[176:179], v[68:71]
	v_mfma_f32_16x16x32_bf16 v[60:63], v[148:151], v[180:183], v[60:63]
	v_mfma_f32_16x16x32_bf16 v[60:63], v[152:155], v[184:187], v[60:63]
	v_mfma_f32_16x16x32_bf16 v[64:67], v[140:143], v[180:183], v[64:67]
	v_mfma_f32_16x16x32_bf16 v[64:67], v[144:147], v[184:187], v[64:67]
	v_mfma_f32_16x16x32_bf16 v[32:35], v[156:159], v[180:183], v[32:35]
	v_mfma_f32_16x16x32_bf16 v[32:35], v[160:163], v[184:187], v[32:35]
	v_mfma_f32_16x16x32_bf16 v[28:31], v[164:167], v[180:183], v[28:31]
	v_mfma_f32_16x16x32_bf16 v[28:31], v[168:171], v[184:187], v[28:31]
	v_mfma_f32_16x16x32_bf16 v[36:39], v[164:167], v[172:175], v[36:39]
	v_mfma_f32_16x16x32_bf16 v[36:39], v[168:171], v[176:179], v[36:39]
	v_mfma_f32_16x16x32_bf16 v[40:43], v[156:159], v[172:175], v[40:43]
	v_mfma_f32_16x16x32_bf16 v[40:43], v[160:163], v[176:179], v[40:43]
	v_mfma_f32_16x16x32_bf16 v[24:27], v[156:159], v[188:191], v[24:27]
	v_mfma_f32_16x16x32_bf16 v[24:27], v[160:163], v[192:195], v[24:27]
	v_mfma_f32_16x16x32_bf16 v[20:23], v[164:167], v[188:191], v[20:23]
	v_mfma_f32_16x16x32_bf16 v[20:23], v[168:171], v[192:195], v[20:23]
	v_mfma_f32_16x16x32_bf16 v[12:15], v[164:167], v[196:199], v[12:15]
	v_mfma_f32_16x16x32_bf16 v[12:15], v[168:171], v[200:203], v[12:15]
	v_mfma_f32_16x16x32_bf16 v[16:19], v[156:159], v[196:199], v[16:19]
	v_mfma_f32_16x16x32_bf16 v[16:19], v[160:163], v[200:203], v[16:19]
	v_mfma_f32_16x16x32_bf16 v[44:47], v[148:151], v[196:199], v[44:47]
	v_mfma_f32_16x16x32_bf16 v[44:47], v[152:155], v[200:203], v[44:47]
	v_mfma_f32_16x16x32_bf16 v[48:51], v[140:143], v[196:199], v[48:51]
	v_mfma_f32_16x16x32_bf16 v[48:51], v[144:147], v[200:203], v[48:51]
	v_mfma_f32_16x16x32_bf16 v[56:59], v[140:143], v[188:191], v[56:59]
	v_mfma_f32_16x16x32_bf16 v[56:59], v[144:147], v[192:195], v[56:59]
	v_mfma_f32_16x16x32_bf16 v[52:55], v[148:151], v[188:191], v[52:55]
	v_mfma_f32_16x16x32_bf16 v[52:55], v[152:155], v[192:195], v[52:55]
	s_setprio 0
	s_barrier
	s_add_i32 s68, 0, 0x18000
	v_add_u32_e32 v5, s68, v3
	s_add_i32 s70, 0, 0x1c000
	ds_read_b128 v[140:143], v5
	ds_read_b128 v[144:147], v5 offset:1024
	ds_read_b128 v[148:151], v5 offset:2048
	ds_read_b128 v[152:155], v5 offset:3072
	v_add_u32_e32 v5, s70, v3
	ds_read_b128 v[156:159], v5
	ds_read_b128 v[160:163], v5 offset:1024
	ds_read_b128 v[164:167], v5 offset:2048
	ds_read_b128 v[168:171], v5 offset:3072
	s_add_u32 s98, s50, 0x80000
	s_addc_u32 s99, s51, 0
	s_mov_b64 s[100:101], s[50:51]
	s_mov_b32 m0, s49
	ds_read_b128 v[172:175], v246 offset:32768
	ds_read_b128 v[176:179], v246 offset:33792
	ds_read_b128 v[180:183], v246 offset:34816
	ds_read_b128 v[184:187], v246 offset:35840
	ds_read_b128 v[188:191], v246 offset:36864
	ds_read_b128 v[192:195], v246 offset:37888
	ds_read_b128 v[196:199], v246 offset:38912
	ds_read_b128 v[200:203], v246 offset:39936
	global_load_lds_dwordx4 v208, s[98:99]
	s_mov_b32 m0, s52
	s_nop 0
	global_load_lds_dwordx4 v212, s[98:99]
	s_waitcnt vmcnt(8)
	s_waitcnt lgkmcnt(0)
	s_setprio 1
	s_barrier
	v_mfma_f32_16x16x32_bf16 v[136:139], v[140:143], v[172:175], v[136:139]
	v_mfma_f32_16x16x32_bf16 v[136:139], v[144:147], v[176:179], v[136:139]
	v_mfma_f32_16x16x32_bf16 v[132:135], v[148:151], v[172:175], v[132:135]
	v_mfma_f32_16x16x32_bf16 v[132:135], v[152:155], v[176:179], v[132:135]
	v_mfma_f32_16x16x32_bf16 v[124:127], v[148:151], v[180:183], v[124:127]
	v_mfma_f32_16x16x32_bf16 v[124:127], v[152:155], v[184:187], v[124:127]
	v_mfma_f32_16x16x32_bf16 v[128:131], v[140:143], v[180:183], v[128:131]
	v_mfma_f32_16x16x32_bf16 v[128:131], v[144:147], v[184:187], v[128:131]
	v_mfma_f32_16x16x32_bf16 v[96:99], v[156:159], v[180:183], v[96:99]
	v_mfma_f32_16x16x32_bf16 v[96:99], v[160:163], v[184:187], v[96:99]
	v_mfma_f32_16x16x32_bf16 v[92:95], v[164:167], v[180:183], v[92:95]
	v_mfma_f32_16x16x32_bf16 v[92:95], v[168:171], v[184:187], v[92:95]
	v_mfma_f32_16x16x32_bf16 v[100:103], v[164:167], v[172:175], v[100:103]
	v_mfma_f32_16x16x32_bf16 v[100:103], v[168:171], v[176:179], v[100:103]
	v_mfma_f32_16x16x32_bf16 v[104:107], v[156:159], v[172:175], v[104:107]
	v_mfma_f32_16x16x32_bf16 v[104:107], v[160:163], v[176:179], v[104:107]
	v_mfma_f32_16x16x32_bf16 v[88:91], v[156:159], v[188:191], v[88:91]
	v_mfma_f32_16x16x32_bf16 v[88:91], v[160:163], v[192:195], v[88:91]
	v_mfma_f32_16x16x32_bf16 v[84:87], v[164:167], v[188:191], v[84:87]
	v_mfma_f32_16x16x32_bf16 v[84:87], v[168:171], v[192:195], v[84:87]
	v_mfma_f32_16x16x32_bf16 v[76:79], v[164:167], v[196:199], v[76:79]
	v_mfma_f32_16x16x32_bf16 v[76:79], v[168:171], v[200:203], v[76:79]
	v_mfma_f32_16x16x32_bf16 v[80:83], v[156:159], v[196:199], v[80:83]
	v_mfma_f32_16x16x32_bf16 v[80:83], v[160:163], v[200:203], v[80:83]
	v_mfma_f32_16x16x32_bf16 v[108:111], v[148:151], v[196:199], v[108:111]
	v_mfma_f32_16x16x32_bf16 v[108:111], v[152:155], v[200:203], v[108:111]
	v_mfma_f32_16x16x32_bf16 v[112:115], v[140:143], v[196:199], v[112:115]
	v_mfma_f32_16x16x32_bf16 v[112:115], v[144:147], v[200:203], v[112:115]
	v_mfma_f32_16x16x32_bf16 v[120:123], v[140:143], v[188:191], v[120:123]
	v_mfma_f32_16x16x32_bf16 v[120:123], v[144:147], v[192:195], v[120:123]
	v_mfma_f32_16x16x32_bf16 v[116:119], v[148:151], v[188:191], v[116:119]
	v_mfma_f32_16x16x32_bf16 v[116:119], v[152:155], v[192:195], v[116:119]
	s_setprio 0
	s_barrier
	s_add_i32 s50, s68, s46
	s_add_i32 m0, s50, 0xffffff80
	ds_read_b128 v[172:175], v246 offset:49152
	ds_read_b128 v[176:179], v246 offset:50176
	ds_read_b128 v[180:183], v246 offset:51200
	ds_read_b128 v[184:187], v246 offset:52224
	ds_read_b128 v[188:191], v246 offset:53248
	ds_read_b128 v[192:195], v246 offset:54272
	ds_read_b128 v[196:199], v246 offset:55296
	ds_read_b128 v[200:203], v246 offset:56320
	global_load_lds_dwordx4 v210, s[42:43] offset:128
	s_add_i32 m0, s50, 0x1f80
	s_add_i32 s50, s70, s46
	global_load_lds_dwordx4 v214, s[42:43] offset:128
	s_add_u32 s42, s42, 0x80080
	s_addc_u32 s43, s43, 0
	s_mov_b32 m0, s50
	s_nop 0
	global_load_lds_dwordx4 v210, s[42:43]
	s_add_i32 m0, s50, 0x2000
	s_nop 0
	global_load_lds_dwordx4 v214, s[42:43]
	s_add_i32 m0, s58, 0xffffff80
	s_nop 0
	global_load_lds_dwordx4 v208, s[100:101] offset:128
	s_add_i32 m0, s59, 0xffffff80
	s_nop 0
	global_load_lds_dwordx4 v212, s[100:101] offset:128
	s_waitcnt vmcnt(8)
	s_waitcnt lgkmcnt(0)
	s_setprio 1
	s_barrier
	v_mfma_f32_16x16x32_bf16 v[72:75], v[140:143], v[172:175], v[72:75]
	v_mfma_f32_16x16x32_bf16 v[72:75], v[144:147], v[176:179], v[72:75]
	v_mfma_f32_16x16x32_bf16 v[68:71], v[148:151], v[172:175], v[68:71]
	v_mfma_f32_16x16x32_bf16 v[68:71], v[152:155], v[176:179], v[68:71]
	v_mfma_f32_16x16x32_bf16 v[60:63], v[148:151], v[180:183], v[60:63]
	v_mfma_f32_16x16x32_bf16 v[60:63], v[152:155], v[184:187], v[60:63]
	v_mfma_f32_16x16x32_bf16 v[64:67], v[140:143], v[180:183], v[64:67]
	v_mfma_f32_16x16x32_bf16 v[64:67], v[144:147], v[184:187], v[64:67]
	v_mfma_f32_16x16x32_bf16 v[32:35], v[156:159], v[180:183], v[32:35]
	v_mfma_f32_16x16x32_bf16 v[32:35], v[160:163], v[184:187], v[32:35]
	v_mfma_f32_16x16x32_bf16 v[28:31], v[164:167], v[180:183], v[28:31]
	v_mfma_f32_16x16x32_bf16 v[28:31], v[168:171], v[184:187], v[28:31]
	v_mfma_f32_16x16x32_bf16 v[36:39], v[164:167], v[172:175], v[36:39]
	v_mfma_f32_16x16x32_bf16 v[36:39], v[168:171], v[176:179], v[36:39]
	v_mfma_f32_16x16x32_bf16 v[40:43], v[156:159], v[172:175], v[40:43]
	v_mfma_f32_16x16x32_bf16 v[40:43], v[160:163], v[176:179], v[40:43]
	v_mfma_f32_16x16x32_bf16 v[24:27], v[156:159], v[188:191], v[24:27]
	v_mfma_f32_16x16x32_bf16 v[24:27], v[160:163], v[192:195], v[24:27]
	v_mfma_f32_16x16x32_bf16 v[20:23], v[164:167], v[188:191], v[20:23]
	v_mfma_f32_16x16x32_bf16 v[20:23], v[168:171], v[192:195], v[20:23]
	v_mfma_f32_16x16x32_bf16 v[12:15], v[164:167], v[196:199], v[12:15]
	v_mfma_f32_16x16x32_bf16 v[12:15], v[168:171], v[200:203], v[12:15]
	v_mfma_f32_16x16x32_bf16 v[16:19], v[156:159], v[196:199], v[16:19]
	v_mfma_f32_16x16x32_bf16 v[16:19], v[160:163], v[200:203], v[16:19]
	v_mfma_f32_16x16x32_bf16 v[44:47], v[148:151], v[196:199], v[44:47]
	v_mfma_f32_16x16x32_bf16 v[44:47], v[152:155], v[200:203], v[44:47]
	v_mfma_f32_16x16x32_bf16 v[48:51], v[140:143], v[196:199], v[48:51]
	v_mfma_f32_16x16x32_bf16 v[48:51], v[144:147], v[200:203], v[48:51]
	v_mfma_f32_16x16x32_bf16 v[56:59], v[140:143], v[188:191], v[56:59]
	v_mfma_f32_16x16x32_bf16 v[56:59], v[144:147], v[192:195], v[56:59]
	v_mfma_f32_16x16x32_bf16 v[52:55], v[148:151], v[188:191], v[52:55]
	v_mfma_f32_16x16x32_bf16 v[52:55], v[152:155], v[192:195], v[52:55]
	s_setprio 0
	s_barrier
	s_add_i32 s67, s67, 2
	s_add_u32 s40, s40, 0x100
	s_addc_u32 s41, s41, 0
	s_add_u32 s65, s65, 0x100
	s_addc_u32 s66, s66, 0
	s_cmp_gt_u32 s67, 29
	s_cbranch_scc0 .LBB0_1032
	s_and_b64 vcc, exec, s[22:23]
	s_cbranch_vccz .LBB0_1035
	s_barrier

.LBB0_1203:
	ds_read_b128 v[132:135], v187
	ds_read_b128 v[136:139], v187 offset:1024
	ds_read_b128 v[140:143], v187 offset:2048
	ds_read_b128 v[144:147], v187 offset:3072
	ds_read_b128 v[148:151], v188
	ds_read_b128 v[152:155], v188 offset:1024
	ds_read_b128 v[172:175], v188 offset:2048
	ds_read_b128 v[176:179], v188 offset:3072
	s_add_u32 s0, s42, 0xfff00080
	s_addc_u32 s50, s43, -1
	s_cmp_eq_u32 s65, 60
	s_cselect_b32 s53, s25, s50
	s_cselect_b32 s52, s31, s0
	s_cselect_b32 s51, s23, s64
	s_cselect_b32 s50, s62, s63
	s_add_i32 m0, s41, 0xc000
	ds_read_b128 v[180:183], v189
	ds_read_b128 v[192:195], v189 offset:1024
	ds_read_b128 v[196:199], v189 offset:2048
	ds_read_b128 v[200:203], v189 offset:3072
	ds_read_b128 v[204:207], v189 offset:4096
	ds_read_b128 v[208:211], v189 offset:5120
	ds_read_b128 v[212:215], v189 offset:6144
	ds_read_b128 v[216:219], v189 offset:7168
	global_load_lds_dwordx4 v164, s[42:43]
	s_add_i32 m0, s41, 0xe000
	s_nop 0
	global_load_lds_dwordx4 v166, s[42:43]
	s_waitcnt vmcnt(8)
	s_waitcnt lgkmcnt(0)
	s_setprio 1
	s_barrier
	v_mfma_f32_16x16x32_bf16 v[128:131], v[132:135], v[180:183], v[128:131]
	v_mfma_f32_16x16x32_bf16 v[128:131], v[136:139], v[192:195], v[128:131]
	v_mfma_f32_16x16x32_bf16 v[124:127], v[140:143], v[180:183], v[124:127]
	v_mfma_f32_16x16x32_bf16 v[124:127], v[144:147], v[192:195], v[124:127]
	v_mfma_f32_16x16x32_bf16 v[108:111], v[140:143], v[196:199], v[108:111]
	v_mfma_f32_16x16x32_bf16 v[108:111], v[144:147], v[200:203], v[108:111]
	v_mfma_f32_16x16x32_bf16 v[112:115], v[132:135], v[196:199], v[112:115]
	v_mfma_f32_16x16x32_bf16 v[112:115], v[136:139], v[200:203], v[112:115]
	v_mfma_f32_16x16x32_bf16 v[104:107], v[148:151], v[196:199], v[104:107]
	v_mfma_f32_16x16x32_bf16 v[104:107], v[152:155], v[200:203], v[104:107]
	v_mfma_f32_16x16x32_bf16 v[100:103], v[172:175], v[196:199], v[100:103]
	v_mfma_f32_16x16x32_bf16 v[100:103], v[176:179], v[200:203], v[100:103]
	v_mfma_f32_16x16x32_bf16 v[116:119], v[172:175], v[180:183], v[116:119]
	v_mfma_f32_16x16x32_bf16 v[116:119], v[176:179], v[192:195], v[116:119]
	v_mfma_f32_16x16x32_bf16 v[120:123], v[148:151], v[180:183], v[120:123]
	v_mfma_f32_16x16x32_bf16 v[120:123], v[152:155], v[192:195], v[120:123]
	v_mfma_f32_16x16x32_bf16 v[88:91], v[148:151], v[204:207], v[88:91]
	v_mfma_f32_16x16x32_bf16 v[88:91], v[152:155], v[208:211], v[88:91]
	v_mfma_f32_16x16x32_bf16 v[84:87], v[172:175], v[204:207], v[84:87]
	v_mfma_f32_16x16x32_bf16 v[84:87], v[176:179], v[208:211], v[84:87]
	v_mfma_f32_16x16x32_bf16 v[68:71], v[172:175], v[212:215], v[68:71]
	v_mfma_f32_16x16x32_bf16 v[68:71], v[176:179], v[216:219], v[68:71]
	v_mfma_f32_16x16x32_bf16 v[72:75], v[148:151], v[212:215], v[72:75]
	v_mfma_f32_16x16x32_bf16 v[72:75], v[152:155], v[216:219], v[72:75]
	v_mfma_f32_16x16x32_bf16 v[76:79], v[140:143], v[212:215], v[76:79]
	v_mfma_f32_16x16x32_bf16 v[76:79], v[144:147], v[216:219], v[76:79]
	v_mfma_f32_16x16x32_bf16 v[80:83], v[132:135], v[212:215], v[80:83]
	v_mfma_f32_16x16x32_bf16 v[80:83], v[136:139], v[216:219], v[80:83]
	v_mfma_f32_16x16x32_bf16 v[96:99], v[132:135], v[204:207], v[96:99]
	v_mfma_f32_16x16x32_bf16 v[96:99], v[136:139], v[208:211], v[96:99]
	v_mfma_f32_16x16x32_bf16 v[92:95], v[140:143], v[204:207], v[92:95]
	v_mfma_f32_16x16x32_bf16 v[92:95], v[144:147], v[208:211], v[92:95]
	s_setprio 0
	s_barrier
	s_add_i32 s0, s59, s46
	s_mov_b32 m0, s0
	ds_read_b128 v[180:183], v189 offset:16384
	ds_read_b128 v[192:195], v189 offset:17408
	ds_read_b128 v[196:199], v189 offset:18432
	ds_read_b128 v[200:203], v189 offset:19456
	ds_read_b128 v[204:207], v189 offset:20480
	ds_read_b128 v[208:211], v189 offset:21504
	ds_read_b128 v[212:215], v189 offset:22528
	ds_read_b128 v[216:219], v189 offset:23552
	global_load_lds_dwordx4 v158, s[50:51]
	s_add_i32 m0, s0, 0x2000
	s_add_u32 s66, s50, 0x100000
	s_addc_u32 s67, s51, 0
	s_add_i32 s0, s60, s46
	global_load_lds_dwordx4 v162, s[50:51]
	s_mov_b32 m0, s0
	s_nop 0
	global_load_lds_dwordx4 v158, s[66:67]
	s_add_i32 m0, s0, 0x2000
	s_nop 0
	global_load_lds_dwordx4 v162, s[66:67]
	s_mov_b32 m0, s41
	s_nop 0
	global_load_lds_dwordx4 v156, s[52:53]
	s_mov_b32 m0, s47
	s_nop 0
	global_load_lds_dwordx4 v160, s[52:53]
	s_waitcnt vmcnt(8)
	s_waitcnt lgkmcnt(0)
	s_setprio 1
	s_barrier
	v_mfma_f32_16x16x32_bf16 v[64:67], v[132:135], v[180:183], v[64:67]
	v_mfma_f32_16x16x32_bf16 v[64:67], v[136:139], v[192:195], v[64:67]
	v_mfma_f32_16x16x32_bf16 v[60:63], v[140:143], v[180:183], v[60:63]
	v_mfma_f32_16x16x32_bf16 v[60:63], v[144:147], v[192:195], v[60:63]
	v_mfma_f32_16x16x32_bf16 v[44:47], v[140:143], v[196:199], v[44:47]
	v_mfma_f32_16x16x32_bf16 v[44:47], v[144:147], v[200:203], v[44:47]
	v_mfma_f32_16x16x32_bf16 v[48:51], v[132:135], v[196:199], v[48:51]
	v_mfma_f32_16x16x32_bf16 v[48:51], v[136:139], v[200:203], v[48:51]
	v_mfma_f32_16x16x32_bf16 v[40:43], v[148:151], v[196:199], v[40:43]
	v_mfma_f32_16x16x32_bf16 v[40:43], v[152:155], v[200:203], v[40:43]
	v_mfma_f32_16x16x32_bf16 v[36:39], v[172:175], v[196:199], v[36:39]
	v_mfma_f32_16x16x32_bf16 v[36:39], v[176:179], v[200:203], v[36:39]
	v_mfma_f32_16x16x32_bf16 v[52:55], v[172:175], v[180:183], v[52:55]
	v_mfma_f32_16x16x32_bf16 v[52:55], v[176:179], v[192:195], v[52:55]
	v_mfma_f32_16x16x32_bf16 v[56:59], v[148:151], v[180:183], v[56:59]
	v_mfma_f32_16x16x32_bf16 v[56:59], v[152:155], v[192:195], v[56:59]
	v_mfma_f32_16x16x32_bf16 v[24:27], v[148:151], v[204:207], v[24:27]
	v_mfma_f32_16x16x32_bf16 v[24:27], v[152:155], v[208:211], v[24:27]
	v_mfma_f32_16x16x32_bf16 v[20:23], v[172:175], v[204:207], v[20:23]
	v_mfma_f32_16x16x32_bf16 v[20:23], v[176:179], v[208:211], v[20:23]
	v_mfma_f32_16x16x32_bf16 v[4:7], v[172:175], v[212:215], v[4:7]
	v_mfma_f32_16x16x32_bf16 v[4:7], v[176:179], v[216:219], v[4:7]
	v_mfma_f32_16x16x32_bf16 v[8:11], v[148:151], v[212:215], v[8:11]
	v_mfma_f32_16x16x32_bf16 v[8:11], v[152:155], v[216:219], v[8:11]
	v_mfma_f32_16x16x32_bf16 v[12:15], v[140:143], v[212:215], v[12:15]
	v_mfma_f32_16x16x32_bf16 v[12:15], v[144:147], v[216:219], v[12:15]
	v_mfma_f32_16x16x32_bf16 v[16:19], v[132:135], v[212:215], v[16:19]
	v_mfma_f32_16x16x32_bf16 v[16:19], v[136:139], v[216:219], v[16:19]
	v_mfma_f32_16x16x32_bf16 v[32:35], v[132:135], v[204:207], v[32:35]
	v_mfma_f32_16x16x32_bf16 v[32:35], v[136:139], v[208:211], v[32:35]
	v_mfma_f32_16x16x32_bf16 v[28:31], v[140:143], v[204:207], v[28:31]
	v_mfma_f32_16x16x32_bf16 v[28:31], v[144:147], v[208:211], v[28:31]
	s_setprio 0
	s_barrier
	s_add_i32 s0, 0, 0x18000
	s_add_i32 s66, 0, 0x1c000
	v_add_u32_e32 v144, s0, v3
	v_add_u32_e32 v176, s66, v3
	ds_read_b128 v[132:135], v144
	ds_read_b128 v[136:139], v144 offset:1024
	ds_read_b128 v[140:143], v144 offset:2048
	ds_read_b128 v[144:147], v144 offset:3072
	ds_read_b128 v[148:151], v176
	ds_read_b128 v[152:155], v176 offset:1024
	ds_read_b128 v[172:175], v176 offset:2048
	ds_read_b128 v[176:179], v176 offset:3072
	s_add_u32 s98, s52, 0x100000
	s_addc_u32 s99, s53, 0
	s_mov_b32 m0, s48
	ds_read_b128 v[180:183], v189 offset:32768
	ds_read_b128 v[192:195], v189 offset:33792
	ds_read_b128 v[196:199], v189 offset:34816
	ds_read_b128 v[200:203], v189 offset:35840
	ds_read_b128 v[204:207], v189 offset:36864
	ds_read_b128 v[208:211], v189 offset:37888
	ds_read_b128 v[212:215], v189 offset:38912
	ds_read_b128 v[216:219], v189 offset:39936
	global_load_lds_dwordx4 v156, s[98:99]
	s_mov_b32 m0, s49
	s_nop 0
	global_load_lds_dwordx4 v160, s[98:99]
	s_waitcnt vmcnt(8)
	s_waitcnt lgkmcnt(0)
	s_setprio 1
	s_barrier
	v_mfma_f32_16x16x32_bf16 v[128:131], v[132:135], v[180:183], v[128:131]
	v_mfma_f32_16x16x32_bf16 v[128:131], v[136:139], v[192:195], v[128:131]
	v_mfma_f32_16x16x32_bf16 v[124:127], v[140:143], v[180:183], v[124:127]
	v_mfma_f32_16x16x32_bf16 v[124:127], v[144:147], v[192:195], v[124:127]
	v_mfma_f32_16x16x32_bf16 v[108:111], v[140:143], v[196:199], v[108:111]
	v_mfma_f32_16x16x32_bf16 v[108:111], v[144:147], v[200:203], v[108:111]
	v_mfma_f32_16x16x32_bf16 v[112:115], v[132:135], v[196:199], v[112:115]
	v_mfma_f32_16x16x32_bf16 v[112:115], v[136:139], v[200:203], v[112:115]
	v_mfma_f32_16x16x32_bf16 v[104:107], v[148:151], v[196:199], v[104:107]
	v_mfma_f32_16x16x32_bf16 v[104:107], v[152:155], v[200:203], v[104:107]
	v_mfma_f32_16x16x32_bf16 v[100:103], v[172:175], v[196:199], v[100:103]
	v_mfma_f32_16x16x32_bf16 v[100:103], v[176:179], v[200:203], v[100:103]
	v_mfma_f32_16x16x32_bf16 v[116:119], v[172:175], v[180:183], v[116:119]
	v_mfma_f32_16x16x32_bf16 v[116:119], v[176:179], v[192:195], v[116:119]
	v_mfma_f32_16x16x32_bf16 v[120:123], v[148:151], v[180:183], v[120:123]
	v_mfma_f32_16x16x32_bf16 v[120:123], v[152:155], v[192:195], v[120:123]
	v_mfma_f32_16x16x32_bf16 v[88:91], v[148:151], v[204:207], v[88:91]
	v_mfma_f32_16x16x32_bf16 v[88:91], v[152:155], v[208:211], v[88:91]
	v_mfma_f32_16x16x32_bf16 v[84:87], v[172:175], v[204:207], v[84:87]
	v_mfma_f32_16x16x32_bf16 v[84:87], v[176:179], v[208:211], v[84:87]
	v_mfma_f32_16x16x32_bf16 v[68:71], v[172:175], v[212:215], v[68:71]
	v_mfma_f32_16x16x32_bf16 v[68:71], v[176:179], v[216:219], v[68:71]
	v_mfma_f32_16x16x32_bf16 v[72:75], v[148:151], v[212:215], v[72:75]
	v_mfma_f32_16x16x32_bf16 v[72:75], v[152:155], v[216:219], v[72:75]
	v_mfma_f32_16x16x32_bf16 v[76:79], v[140:143], v[212:215], v[76:79]
	v_mfma_f32_16x16x32_bf16 v[76:79], v[144:147], v[216:219], v[76:79]
	v_mfma_f32_16x16x32_bf16 v[80:83], v[132:135], v[212:215], v[80:83]
	v_mfma_f32_16x16x32_bf16 v[80:83], v[136:139], v[216:219], v[80:83]
	v_mfma_f32_16x16x32_bf16 v[96:99], v[132:135], v[204:207], v[96:99]
	v_mfma_f32_16x16x32_bf16 v[96:99], v[136:139], v[208:211], v[96:99]
	v_mfma_f32_16x16x32_bf16 v[92:95], v[140:143], v[204:207], v[92:95]
	v_mfma_f32_16x16x32_bf16 v[92:95], v[144:147], v[208:211], v[92:95]
	s_setprio 0
	s_barrier
	s_add_i32 s0, s0, s46
	s_add_i32 m0, s0, 0xffffff80
	ds_read_b128 v[180:183], v189 offset:49152
	ds_read_b128 v[192:195], v189 offset:50176
	ds_read_b128 v[196:199], v189 offset:51200
	ds_read_b128 v[200:203], v189 offset:52224
	ds_read_b128 v[204:207], v189 offset:53248
	ds_read_b128 v[208:211], v189 offset:54272
	ds_read_b128 v[212:215], v189 offset:55296
	ds_read_b128 v[216:219], v189 offset:56320
	global_load_lds_dwordx4 v158, s[50:51] offset:128
	s_add_i32 m0, s0, 0x1f80
	s_add_i32 s0, s66, s46
	global_load_lds_dwordx4 v162, s[50:51] offset:128
	s_add_u32 s50, s50, 0x100080
	s_addc_u32 s51, s51, 0
	s_mov_b32 m0, s0
	s_nop 0
	global_load_lds_dwordx4 v158, s[50:51]
	s_add_i32 m0, s0, 0x2000
	s_nop 0
	global_load_lds_dwordx4 v162, s[50:51]
	s_add_i32 m0, s57, 0xffffff80
	s_nop 0
	global_load_lds_dwordx4 v156, s[52:53] offset:128
	s_add_i32 m0, s58, 0xffffff80
	s_nop 0
	global_load_lds_dwordx4 v160, s[52:53] offset:128
	s_waitcnt vmcnt(8)
	s_waitcnt lgkmcnt(0)
	s_setprio 1
	s_barrier
	v_mfma_f32_16x16x32_bf16 v[64:67], v[132:135], v[180:183], v[64:67]
	v_mfma_f32_16x16x32_bf16 v[64:67], v[136:139], v[192:195], v[64:67]
	v_mfma_f32_16x16x32_bf16 v[60:63], v[140:143], v[180:183], v[60:63]
	v_mfma_f32_16x16x32_bf16 v[60:63], v[144:147], v[192:195], v[60:63]
	v_mfma_f32_16x16x32_bf16 v[44:47], v[140:143], v[196:199], v[44:47]
	v_mfma_f32_16x16x32_bf16 v[44:47], v[144:147], v[200:203], v[44:47]
	v_mfma_f32_16x16x32_bf16 v[48:51], v[132:135], v[196:199], v[48:51]
	v_mfma_f32_16x16x32_bf16 v[48:51], v[136:139], v[200:203], v[48:51]
	v_mfma_f32_16x16x32_bf16 v[40:43], v[148:151], v[196:199], v[40:43]
	v_mfma_f32_16x16x32_bf16 v[40:43], v[152:155], v[200:203], v[40:43]
	v_mfma_f32_16x16x32_bf16 v[36:39], v[172:175], v[196:199], v[36:39]
	v_mfma_f32_16x16x32_bf16 v[36:39], v[176:179], v[200:203], v[36:39]
	v_mfma_f32_16x16x32_bf16 v[52:55], v[172:175], v[180:183], v[52:55]
	v_mfma_f32_16x16x32_bf16 v[52:55], v[176:179], v[192:195], v[52:55]
	v_mfma_f32_16x16x32_bf16 v[56:59], v[148:151], v[180:183], v[56:59]
	v_mfma_f32_16x16x32_bf16 v[56:59], v[152:155], v[192:195], v[56:59]
	v_mfma_f32_16x16x32_bf16 v[24:27], v[148:151], v[204:207], v[24:27]
	v_mfma_f32_16x16x32_bf16 v[24:27], v[152:155], v[208:211], v[24:27]
	v_mfma_f32_16x16x32_bf16 v[20:23], v[172:175], v[204:207], v[20:23]
	v_mfma_f32_16x16x32_bf16 v[20:23], v[176:179], v[208:211], v[20:23]
	v_mfma_f32_16x16x32_bf16 v[4:7], v[172:175], v[212:215], v[4:7]
	v_mfma_f32_16x16x32_bf16 v[4:7], v[176:179], v[216:219], v[4:7]
	v_mfma_f32_16x16x32_bf16 v[8:11], v[148:151], v[212:215], v[8:11]
	v_mfma_f32_16x16x32_bf16 v[8:11], v[152:155], v[216:219], v[8:11]
	v_mfma_f32_16x16x32_bf16 v[12:15], v[140:143], v[212:215], v[12:15]
	v_mfma_f32_16x16x32_bf16 v[12:15], v[144:147], v[216:219], v[12:15]
	v_mfma_f32_16x16x32_bf16 v[16:19], v[132:135], v[212:215], v[16:19]
	v_mfma_f32_16x16x32_bf16 v[16:19], v[136:139], v[216:219], v[16:19]
	v_mfma_f32_16x16x32_bf16 v[32:35], v[132:135], v[204:207], v[32:35]
	v_mfma_f32_16x16x32_bf16 v[32:35], v[136:139], v[208:211], v[32:35]
	v_mfma_f32_16x16x32_bf16 v[28:31], v[140:143], v[204:207], v[28:31]
	v_mfma_f32_16x16x32_bf16 v[28:31], v[144:147], v[208:211], v[28:31]
	s_setprio 0
	s_barrier
	s_add_i32 s65, s65, 2
	s_add_u32 s42, s42, 0x100
	s_addc_u32 s43, s43, 0
	s_add_u32 s63, s63, 0x100
	s_addc_u32 s64, s64, 0
	s_cmp_gt_u32 s65, 61
	s_cbranch_scc0 .LBB0_1203
	s_and_b64 vcc, exec, s[20:21]
	s_cbranch_vccz .LBB0_1206
	s_barrier

.LBB0_1288:
	ds_read_b128 v[154:157], v150
	ds_read_b128 v[158:161], v150 offset:1024
	ds_read_b128 v[162:165], v150 offset:2048
	ds_read_b128 v[166:169], v150 offset:3072
	ds_read_b128 v[170:173], v151
	ds_read_b128 v[174:177], v151 offset:1024
	ds_read_b128 v[178:181], v151 offset:2048
	ds_read_b128 v[182:185], v151 offset:3072
	s_add_u32 s0, s42, 0xfff00080
	s_addc_u32 s50, s43, -1
	s_cmp_eq_u32 s70, 12
	s_cselect_b32 s53, s29, s50
	s_cselect_b32 s52, s28, s0
	s_cselect_b32 s51, s5, s41
	s_cselect_b32 s50, s4, s31
	s_add_i32 m0, s17, 0xc000
	ds_read_b128 v[186:189], v152
	ds_read_b128 v[190:193], v152 offset:1024
	ds_read_b128 v[194:197], v152 offset:2048
	ds_read_b128 v[198:201], v152 offset:3072
	ds_read_b128 v[202:205], v152 offset:4096
	ds_read_b128 v[206:209], v152 offset:5120
	ds_read_b128 v[210:213], v152 offset:6144
	ds_read_b128 v[214:217], v152 offset:7168
	global_load_lds_dwordx4 v142, s[42:43]
	s_add_i32 m0, s17, 0xe000
	s_nop 0
	global_load_lds_dwordx4 v144, s[42:43]
	s_waitcnt vmcnt(8)
	s_waitcnt lgkmcnt(0)
	s_setprio 1
	s_barrier
	v_mfma_f32_16x16x32_bf16 v[128:131], v[154:157], v[186:189], v[128:131]
	v_mfma_f32_16x16x32_bf16 v[128:131], v[158:161], v[190:193], v[128:131]
	v_mfma_f32_16x16x32_bf16 v[124:127], v[162:165], v[186:189], v[124:127]
	v_mfma_f32_16x16x32_bf16 v[124:127], v[166:169], v[190:193], v[124:127]
	v_mfma_f32_16x16x32_bf16 v[116:119], v[162:165], v[194:197], v[116:119]
	v_mfma_f32_16x16x32_bf16 v[116:119], v[166:169], v[198:201], v[116:119]
	v_mfma_f32_16x16x32_bf16 v[120:123], v[154:157], v[194:197], v[120:123]
	v_mfma_f32_16x16x32_bf16 v[120:123], v[158:161], v[198:201], v[120:123]
	v_mfma_f32_16x16x32_bf16 v[96:99], v[170:173], v[194:197], v[96:99]
	v_mfma_f32_16x16x32_bf16 v[96:99], v[174:177], v[198:201], v[96:99]
	v_mfma_f32_16x16x32_bf16 v[92:95], v[178:181], v[194:197], v[92:95]
	v_mfma_f32_16x16x32_bf16 v[92:95], v[182:185], v[198:201], v[92:95]
	v_mfma_f32_16x16x32_bf16 v[108:111], v[178:181], v[186:189], v[108:111]
	v_mfma_f32_16x16x32_bf16 v[108:111], v[182:185], v[190:193], v[108:111]
	v_mfma_f32_16x16x32_bf16 v[112:115], v[170:173], v[186:189], v[112:115]
	v_mfma_f32_16x16x32_bf16 v[112:115], v[174:177], v[190:193], v[112:115]
	v_mfma_f32_16x16x32_bf16 v[80:83], v[170:173], v[202:205], v[80:83]
	v_mfma_f32_16x16x32_bf16 v[80:83], v[174:177], v[206:209], v[80:83]
	v_mfma_f32_16x16x32_bf16 v[76:79], v[178:181], v[202:205], v[76:79]
	v_mfma_f32_16x16x32_bf16 v[76:79], v[182:185], v[206:209], v[76:79]
	v_mfma_f32_16x16x32_bf16 v[68:71], v[178:181], v[210:213], v[68:71]
	v_mfma_f32_16x16x32_bf16 v[68:71], v[182:185], v[214:217], v[68:71]
	v_mfma_f32_16x16x32_bf16 v[72:75], v[170:173], v[210:213], v[72:75]
	v_mfma_f32_16x16x32_bf16 v[72:75], v[174:177], v[214:217], v[72:75]
	v_mfma_f32_16x16x32_bf16 v[84:87], v[162:165], v[210:213], v[84:87]
	v_mfma_f32_16x16x32_bf16 v[84:87], v[166:169], v[214:217], v[84:87]
	v_mfma_f32_16x16x32_bf16 v[88:91], v[154:157], v[210:213], v[88:91]
	v_mfma_f32_16x16x32_bf16 v[88:91], v[158:161], v[214:217], v[88:91]
	v_mfma_f32_16x16x32_bf16 v[104:107], v[154:157], v[202:205], v[104:107]
	v_mfma_f32_16x16x32_bf16 v[104:107], v[158:161], v[206:209], v[104:107]
	v_mfma_f32_16x16x32_bf16 v[100:103], v[162:165], v[202:205], v[100:103]
	v_mfma_f32_16x16x32_bf16 v[100:103], v[166:169], v[206:209], v[100:103]
	s_setprio 0
	s_barrier
	s_add_i32 s0, s60, s46
	s_mov_b32 m0, s0
	ds_read_b128 v[186:189], v152 offset:16384
	ds_read_b128 v[190:193], v152 offset:17408
	ds_read_b128 v[194:197], v152 offset:18432
	ds_read_b128 v[198:201], v152 offset:19456
	ds_read_b128 v[202:205], v152 offset:20480
	ds_read_b128 v[206:209], v152 offset:21504
	ds_read_b128 v[210:213], v152 offset:22528
	ds_read_b128 v[214:217], v152 offset:23552
	global_load_lds_dwordx4 v136, s[50:51]
	s_add_i32 m0, s0, 0x2000
	s_add_u32 s72, s50, 0x100000
	s_addc_u32 s73, s51, 0
	s_add_i32 s0, s61, s46
	global_load_lds_dwordx4 v132, s[50:51]
	s_mov_b32 m0, s0
	s_nop 0
	global_load_lds_dwordx4 v136, s[72:73]
	s_add_i32 m0, s0, 0x2000
	s_nop 0
	global_load_lds_dwordx4 v132, s[72:73]
	s_mov_b32 m0, s17
	s_nop 0
	global_load_lds_dwordx4 v138, s[52:53]
	s_mov_b32 m0, s47
	s_nop 0
	global_load_lds_dwordx4 v134, s[52:53]
	s_waitcnt vmcnt(8)
	s_waitcnt lgkmcnt(0)
	s_setprio 1
	s_barrier
	v_mfma_f32_16x16x32_bf16 v[64:67], v[154:157], v[186:189], v[64:67]
	v_mfma_f32_16x16x32_bf16 v[64:67], v[158:161], v[190:193], v[64:67]
	v_mfma_f32_16x16x32_bf16 v[60:63], v[162:165], v[186:189], v[60:63]
	v_mfma_f32_16x16x32_bf16 v[60:63], v[166:169], v[190:193], v[60:63]
	v_mfma_f32_16x16x32_bf16 v[52:55], v[162:165], v[194:197], v[52:55]
	v_mfma_f32_16x16x32_bf16 v[52:55], v[166:169], v[198:201], v[52:55]
	v_mfma_f32_16x16x32_bf16 v[56:59], v[154:157], v[194:197], v[56:59]
	v_mfma_f32_16x16x32_bf16 v[56:59], v[158:161], v[198:201], v[56:59]
	v_mfma_f32_16x16x32_bf16 v[32:35], v[170:173], v[194:197], v[32:35]
	v_mfma_f32_16x16x32_bf16 v[32:35], v[174:177], v[198:201], v[32:35]
	v_mfma_f32_16x16x32_bf16 v[28:31], v[178:181], v[194:197], v[28:31]
	v_mfma_f32_16x16x32_bf16 v[28:31], v[182:185], v[198:201], v[28:31]
	v_mfma_f32_16x16x32_bf16 v[44:47], v[178:181], v[186:189], v[44:47]
	v_mfma_f32_16x16x32_bf16 v[44:47], v[182:185], v[190:193], v[44:47]
	v_mfma_f32_16x16x32_bf16 v[48:51], v[170:173], v[186:189], v[48:51]
	v_mfma_f32_16x16x32_bf16 v[48:51], v[174:177], v[190:193], v[48:51]
	v_mfma_f32_16x16x32_bf16 v[16:19], v[170:173], v[202:205], v[16:19]
	v_mfma_f32_16x16x32_bf16 v[16:19], v[174:177], v[206:209], v[16:19]
	v_mfma_f32_16x16x32_bf16 v[12:15], v[178:181], v[202:205], v[12:15]
	v_mfma_f32_16x16x32_bf16 v[12:15], v[182:185], v[206:209], v[12:15]
	v_mfma_f32_16x16x32_bf16 v[4:7], v[178:181], v[210:213], v[4:7]
	v_mfma_f32_16x16x32_bf16 v[4:7], v[182:185], v[214:217], v[4:7]
	v_mfma_f32_16x16x32_bf16 v[8:11], v[170:173], v[210:213], v[8:11]
	v_mfma_f32_16x16x32_bf16 v[8:11], v[174:177], v[214:217], v[8:11]
	v_mfma_f32_16x16x32_bf16 v[20:23], v[162:165], v[210:213], v[20:23]
	v_mfma_f32_16x16x32_bf16 v[20:23], v[166:169], v[214:217], v[20:23]
	v_mfma_f32_16x16x32_bf16 v[24:27], v[154:157], v[210:213], v[24:27]
	v_mfma_f32_16x16x32_bf16 v[24:27], v[158:161], v[214:217], v[24:27]
	v_mfma_f32_16x16x32_bf16 v[40:43], v[154:157], v[202:205], v[40:43]
	v_mfma_f32_16x16x32_bf16 v[40:43], v[158:161], v[206:209], v[40:43]
	v_mfma_f32_16x16x32_bf16 v[36:39], v[162:165], v[202:205], v[36:39]
	v_mfma_f32_16x16x32_bf16 v[36:39], v[166:169], v[206:209], v[36:39]
	s_setprio 0
	s_barrier
	s_add_i32 s0, 0, 0x18000
	v_add_u32_e32 v140, s0, v3
	s_add_i32 s71, 0, 0x1c000
	ds_read_b128 v[154:157], v140
	ds_read_b128 v[158:161], v140 offset:1024
	ds_read_b128 v[162:165], v140 offset:2048
	ds_read_b128 v[166:169], v140 offset:3072
	v_add_u32_e32 v140, s71, v3
	ds_read_b128 v[170:173], v140
	ds_read_b128 v[174:177], v140 offset:1024
	ds_read_b128 v[178:181], v140 offset:2048
	ds_read_b128 v[182:185], v140 offset:3072
	s_add_u32 s98, s52, 0x100000
	s_addc_u32 s99, s53, 0
	s_mov_b32 m0, s48
	ds_read_b128 v[186:189], v152 offset:32768
	ds_read_b128 v[190:193], v152 offset:33792
	ds_read_b128 v[194:197], v152 offset:34816
	ds_read_b128 v[198:201], v152 offset:35840
	ds_read_b128 v[202:205], v152 offset:36864
	ds_read_b128 v[206:209], v152 offset:37888
	ds_read_b128 v[210:213], v152 offset:38912
	ds_read_b128 v[214:217], v152 offset:39936
	global_load_lds_dwordx4 v138, s[98:99]
	s_mov_b32 m0, s49
	s_nop 0
	global_load_lds_dwordx4 v134, s[98:99]
	s_waitcnt vmcnt(8)
	s_waitcnt lgkmcnt(0)
	s_setprio 1
	s_barrier
	v_mfma_f32_16x16x32_bf16 v[128:131], v[154:157], v[186:189], v[128:131]
	v_mfma_f32_16x16x32_bf16 v[128:131], v[158:161], v[190:193], v[128:131]
	v_mfma_f32_16x16x32_bf16 v[124:127], v[162:165], v[186:189], v[124:127]
	v_mfma_f32_16x16x32_bf16 v[124:127], v[166:169], v[190:193], v[124:127]
	v_mfma_f32_16x16x32_bf16 v[116:119], v[162:165], v[194:197], v[116:119]
	v_mfma_f32_16x16x32_bf16 v[116:119], v[166:169], v[198:201], v[116:119]
	v_mfma_f32_16x16x32_bf16 v[120:123], v[154:157], v[194:197], v[120:123]
	v_mfma_f32_16x16x32_bf16 v[120:123], v[158:161], v[198:201], v[120:123]
	v_mfma_f32_16x16x32_bf16 v[96:99], v[170:173], v[194:197], v[96:99]
	v_mfma_f32_16x16x32_bf16 v[96:99], v[174:177], v[198:201], v[96:99]
	v_mfma_f32_16x16x32_bf16 v[92:95], v[178:181], v[194:197], v[92:95]
	v_mfma_f32_16x16x32_bf16 v[92:95], v[182:185], v[198:201], v[92:95]
	v_mfma_f32_16x16x32_bf16 v[108:111], v[178:181], v[186:189], v[108:111]
	v_mfma_f32_16x16x32_bf16 v[108:111], v[182:185], v[190:193], v[108:111]
	v_mfma_f32_16x16x32_bf16 v[112:115], v[170:173], v[186:189], v[112:115]
	v_mfma_f32_16x16x32_bf16 v[112:115], v[174:177], v[190:193], v[112:115]
	v_mfma_f32_16x16x32_bf16 v[80:83], v[170:173], v[202:205], v[80:83]
	v_mfma_f32_16x16x32_bf16 v[80:83], v[174:177], v[206:209], v[80:83]
	v_mfma_f32_16x16x32_bf16 v[76:79], v[178:181], v[202:205], v[76:79]
	v_mfma_f32_16x16x32_bf16 v[76:79], v[182:185], v[206:209], v[76:79]
	v_mfma_f32_16x16x32_bf16 v[68:71], v[178:181], v[210:213], v[68:71]
	v_mfma_f32_16x16x32_bf16 v[68:71], v[182:185], v[214:217], v[68:71]
	v_mfma_f32_16x16x32_bf16 v[72:75], v[170:173], v[210:213], v[72:75]
	v_mfma_f32_16x16x32_bf16 v[72:75], v[174:177], v[214:217], v[72:75]
	v_mfma_f32_16x16x32_bf16 v[84:87], v[162:165], v[210:213], v[84:87]
	v_mfma_f32_16x16x32_bf16 v[84:87], v[166:169], v[214:217], v[84:87]
	v_mfma_f32_16x16x32_bf16 v[88:91], v[154:157], v[210:213], v[88:91]
	v_mfma_f32_16x16x32_bf16 v[88:91], v[158:161], v[214:217], v[88:91]
	v_mfma_f32_16x16x32_bf16 v[104:107], v[154:157], v[202:205], v[104:107]
	v_mfma_f32_16x16x32_bf16 v[104:107], v[158:161], v[206:209], v[104:107]
	v_mfma_f32_16x16x32_bf16 v[100:103], v[162:165], v[202:205], v[100:103]
	v_mfma_f32_16x16x32_bf16 v[100:103], v[166:169], v[206:209], v[100:103]
	s_setprio 0
	s_barrier
	s_add_i32 s0, s0, s46
	s_add_i32 m0, s0, 0xffffff80
	ds_read_b128 v[186:189], v152 offset:49152
	ds_read_b128 v[190:193], v152 offset:50176
	ds_read_b128 v[194:197], v152 offset:51200
	ds_read_b128 v[198:201], v152 offset:52224
	ds_read_b128 v[202:205], v152 offset:53248
	ds_read_b128 v[206:209], v152 offset:54272
	ds_read_b128 v[210:213], v152 offset:55296
	ds_read_b128 v[214:217], v152 offset:56320
	global_load_lds_dwordx4 v136, s[50:51] offset:128
	s_add_i32 m0, s0, 0x1f80
	s_add_i32 s0, s71, s46
	global_load_lds_dwordx4 v132, s[50:51] offset:128
	s_add_u32 s50, s50, 0x100080
	s_addc_u32 s51, s51, 0
	s_mov_b32 m0, s0
	s_nop 0
	global_load_lds_dwordx4 v136, s[50:51]
	s_add_i32 m0, s0, 0x2000
	s_nop 0
	global_load_lds_dwordx4 v132, s[50:51]
	s_add_i32 m0, s58, 0xffffff80
	s_nop 0
	global_load_lds_dwordx4 v138, s[52:53] offset:128
	s_add_i32 m0, s59, 0xffffff80
	s_nop 0
	global_load_lds_dwordx4 v134, s[52:53] offset:128
	s_waitcnt vmcnt(8)
	s_waitcnt lgkmcnt(0)
	s_setprio 1
	s_barrier
	v_mfma_f32_16x16x32_bf16 v[64:67], v[154:157], v[186:189], v[64:67]
	v_mfma_f32_16x16x32_bf16 v[64:67], v[158:161], v[190:193], v[64:67]
	v_mfma_f32_16x16x32_bf16 v[60:63], v[162:165], v[186:189], v[60:63]
	v_mfma_f32_16x16x32_bf16 v[60:63], v[166:169], v[190:193], v[60:63]
	v_mfma_f32_16x16x32_bf16 v[52:55], v[162:165], v[194:197], v[52:55]
	v_mfma_f32_16x16x32_bf16 v[52:55], v[166:169], v[198:201], v[52:55]
	v_mfma_f32_16x16x32_bf16 v[56:59], v[154:157], v[194:197], v[56:59]
	v_mfma_f32_16x16x32_bf16 v[56:59], v[158:161], v[198:201], v[56:59]
	v_mfma_f32_16x16x32_bf16 v[32:35], v[170:173], v[194:197], v[32:35]
	v_mfma_f32_16x16x32_bf16 v[32:35], v[174:177], v[198:201], v[32:35]
	v_mfma_f32_16x16x32_bf16 v[28:31], v[178:181], v[194:197], v[28:31]
	v_mfma_f32_16x16x32_bf16 v[28:31], v[182:185], v[198:201], v[28:31]
	v_mfma_f32_16x16x32_bf16 v[44:47], v[178:181], v[186:189], v[44:47]
	v_mfma_f32_16x16x32_bf16 v[44:47], v[182:185], v[190:193], v[44:47]
	v_mfma_f32_16x16x32_bf16 v[48:51], v[170:173], v[186:189], v[48:51]
	v_mfma_f32_16x16x32_bf16 v[48:51], v[174:177], v[190:193], v[48:51]
	v_mfma_f32_16x16x32_bf16 v[16:19], v[170:173], v[202:205], v[16:19]
	v_mfma_f32_16x16x32_bf16 v[16:19], v[174:177], v[206:209], v[16:19]
	v_mfma_f32_16x16x32_bf16 v[12:15], v[178:181], v[202:205], v[12:15]
	v_mfma_f32_16x16x32_bf16 v[12:15], v[182:185], v[206:209], v[12:15]
	v_mfma_f32_16x16x32_bf16 v[4:7], v[178:181], v[210:213], v[4:7]
	v_mfma_f32_16x16x32_bf16 v[4:7], v[182:185], v[214:217], v[4:7]
	v_mfma_f32_16x16x32_bf16 v[8:11], v[170:173], v[210:213], v[8:11]
	v_mfma_f32_16x16x32_bf16 v[8:11], v[174:177], v[214:217], v[8:11]
	v_mfma_f32_16x16x32_bf16 v[20:23], v[162:165], v[210:213], v[20:23]
	v_mfma_f32_16x16x32_bf16 v[20:23], v[166:169], v[214:217], v[20:23]
	v_mfma_f32_16x16x32_bf16 v[24:27], v[154:157], v[210:213], v[24:27]
	v_mfma_f32_16x16x32_bf16 v[24:27], v[158:161], v[214:217], v[24:27]
	v_mfma_f32_16x16x32_bf16 v[40:43], v[154:157], v[202:205], v[40:43]
	v_mfma_f32_16x16x32_bf16 v[40:43], v[158:161], v[206:209], v[40:43]
	v_mfma_f32_16x16x32_bf16 v[36:39], v[162:165], v[202:205], v[36:39]
	v_mfma_f32_16x16x32_bf16 v[36:39], v[166:169], v[206:209], v[36:39]
	s_setprio 0
	s_barrier
	s_add_i32 s70, s70, 2
	s_add_u32 s42, s42, 0x100
	s_addc_u32 s43, s43, 0
	s_add_u32 s31, s31, 0x100
	s_addc_u32 s41, s41, 0
	s_cmp_gt_u32 s70, 13
	s_cbranch_scc0 .LBB0_1288
	s_and_b64 vcc, exec, s[14:15]
	s_cbranch_vccz .LBB0_1291
	s_barrier

.LBB0_1415:
	ds_read_b128 v[132:135], v187
	ds_read_b128 v[136:139], v187 offset:1024
	ds_read_b128 v[140:143], v187 offset:2048
	ds_read_b128 v[144:147], v187 offset:3072
	ds_read_b128 v[148:151], v188
	ds_read_b128 v[152:155], v188 offset:1024
	ds_read_b128 v[172:175], v188 offset:2048
	ds_read_b128 v[176:179], v188 offset:3072
	s_add_u32 s0, s42, 0xfffe0080
	s_addc_u32 s50, s43, -1
	s_cmp_eq_u32 s64, 4
	s_cselect_b32 s53, s25, s50
	s_cselect_b32 s52, s31, s0
	s_cselect_b32 s51, s23, s63
	s_cselect_b32 s50, s61, s62
	s_add_i32 m0, s41, 0xc000
	ds_read_b128 v[180:183], v189
	ds_read_b128 v[192:195], v189 offset:1024
	ds_read_b128 v[196:199], v189 offset:2048
	ds_read_b128 v[200:203], v189 offset:3072
	ds_read_b128 v[204:207], v189 offset:4096
	ds_read_b128 v[208:211], v189 offset:5120
	ds_read_b128 v[212:215], v189 offset:6144
	ds_read_b128 v[216:219], v189 offset:7168
	global_load_lds_dwordx4 v164, s[42:43]
	s_add_i32 m0, s41, 0xe000
	s_nop 0
	global_load_lds_dwordx4 v166, s[42:43]
	s_waitcnt vmcnt(8)
	s_waitcnt lgkmcnt(0)
	s_setprio 1
	s_barrier
	v_mfma_f32_16x16x32_bf16 v[128:131], v[132:135], v[180:183], v[128:131]
	v_mfma_f32_16x16x32_bf16 v[128:131], v[136:139], v[192:195], v[128:131]
	v_mfma_f32_16x16x32_bf16 v[124:127], v[140:143], v[180:183], v[124:127]
	v_mfma_f32_16x16x32_bf16 v[124:127], v[144:147], v[192:195], v[124:127]
	v_mfma_f32_16x16x32_bf16 v[108:111], v[140:143], v[196:199], v[108:111]
	v_mfma_f32_16x16x32_bf16 v[108:111], v[144:147], v[200:203], v[108:111]
	v_mfma_f32_16x16x32_bf16 v[112:115], v[132:135], v[196:199], v[112:115]
	v_mfma_f32_16x16x32_bf16 v[112:115], v[136:139], v[200:203], v[112:115]
	v_mfma_f32_16x16x32_bf16 v[104:107], v[148:151], v[196:199], v[104:107]
	v_mfma_f32_16x16x32_bf16 v[104:107], v[152:155], v[200:203], v[104:107]
	v_mfma_f32_16x16x32_bf16 v[100:103], v[172:175], v[196:199], v[100:103]
	v_mfma_f32_16x16x32_bf16 v[100:103], v[176:179], v[200:203], v[100:103]
	v_mfma_f32_16x16x32_bf16 v[116:119], v[172:175], v[180:183], v[116:119]
	v_mfma_f32_16x16x32_bf16 v[116:119], v[176:179], v[192:195], v[116:119]
	v_mfma_f32_16x16x32_bf16 v[120:123], v[148:151], v[180:183], v[120:123]
	v_mfma_f32_16x16x32_bf16 v[120:123], v[152:155], v[192:195], v[120:123]
	v_mfma_f32_16x16x32_bf16 v[88:91], v[148:151], v[204:207], v[88:91]
	v_mfma_f32_16x16x32_bf16 v[88:91], v[152:155], v[208:211], v[88:91]
	v_mfma_f32_16x16x32_bf16 v[84:87], v[172:175], v[204:207], v[84:87]
	v_mfma_f32_16x16x32_bf16 v[84:87], v[176:179], v[208:211], v[84:87]
	v_mfma_f32_16x16x32_bf16 v[68:71], v[172:175], v[212:215], v[68:71]
	v_mfma_f32_16x16x32_bf16 v[68:71], v[176:179], v[216:219], v[68:71]
	v_mfma_f32_16x16x32_bf16 v[72:75], v[148:151], v[212:215], v[72:75]
	v_mfma_f32_16x16x32_bf16 v[72:75], v[152:155], v[216:219], v[72:75]
	v_mfma_f32_16x16x32_bf16 v[76:79], v[140:143], v[212:215], v[76:79]
	v_mfma_f32_16x16x32_bf16 v[76:79], v[144:147], v[216:219], v[76:79]
	v_mfma_f32_16x16x32_bf16 v[80:83], v[132:135], v[212:215], v[80:83]
	v_mfma_f32_16x16x32_bf16 v[80:83], v[136:139], v[216:219], v[80:83]
	v_mfma_f32_16x16x32_bf16 v[96:99], v[132:135], v[204:207], v[96:99]
	v_mfma_f32_16x16x32_bf16 v[96:99], v[136:139], v[208:211], v[96:99]
	v_mfma_f32_16x16x32_bf16 v[92:95], v[140:143], v[204:207], v[92:95]
	v_mfma_f32_16x16x32_bf16 v[92:95], v[144:147], v[208:211], v[92:95]
	s_setprio 0
	s_barrier
	s_add_i32 s0, s58, s45
	s_mov_b32 m0, s0
	ds_read_b128 v[180:183], v189 offset:16384
	ds_read_b128 v[192:195], v189 offset:17408
	ds_read_b128 v[196:199], v189 offset:18432
	ds_read_b128 v[200:203], v189 offset:19456
	ds_read_b128 v[204:207], v189 offset:20480
	ds_read_b128 v[208:211], v189 offset:21504
	ds_read_b128 v[212:215], v189 offset:22528
	ds_read_b128 v[216:219], v189 offset:23552
	global_load_lds_dwordx4 v158, s[50:51]
	s_add_i32 m0, s0, 0x2000
	s_add_u32 s66, s50, 0x20000
	s_addc_u32 s67, s51, 0
	s_add_i32 s0, s59, s45
	global_load_lds_dwordx4 v162, s[50:51]
	s_mov_b32 m0, s0
	s_nop 0
	global_load_lds_dwordx4 v158, s[66:67]
	s_add_i32 m0, s0, 0x2000
	s_nop 0
	global_load_lds_dwordx4 v162, s[66:67]
	s_mov_b32 m0, s41
	s_nop 0
	global_load_lds_dwordx4 v156, s[52:53]
	s_mov_b32 m0, s46
	s_nop 0
	global_load_lds_dwordx4 v160, s[52:53]
	s_waitcnt vmcnt(8)
	s_waitcnt lgkmcnt(0)
	s_setprio 1
	s_barrier
	v_mfma_f32_16x16x32_bf16 v[64:67], v[132:135], v[180:183], v[64:67]
	v_mfma_f32_16x16x32_bf16 v[64:67], v[136:139], v[192:195], v[64:67]
	v_mfma_f32_16x16x32_bf16 v[60:63], v[140:143], v[180:183], v[60:63]
	v_mfma_f32_16x16x32_bf16 v[60:63], v[144:147], v[192:195], v[60:63]
	v_mfma_f32_16x16x32_bf16 v[44:47], v[140:143], v[196:199], v[44:47]
	v_mfma_f32_16x16x32_bf16 v[44:47], v[144:147], v[200:203], v[44:47]
	v_mfma_f32_16x16x32_bf16 v[48:51], v[132:135], v[196:199], v[48:51]
	v_mfma_f32_16x16x32_bf16 v[48:51], v[136:139], v[200:203], v[48:51]
	v_mfma_f32_16x16x32_bf16 v[40:43], v[148:151], v[196:199], v[40:43]
	v_mfma_f32_16x16x32_bf16 v[40:43], v[152:155], v[200:203], v[40:43]
	v_mfma_f32_16x16x32_bf16 v[36:39], v[172:175], v[196:199], v[36:39]
	v_mfma_f32_16x16x32_bf16 v[36:39], v[176:179], v[200:203], v[36:39]
	v_mfma_f32_16x16x32_bf16 v[52:55], v[172:175], v[180:183], v[52:55]
	v_mfma_f32_16x16x32_bf16 v[52:55], v[176:179], v[192:195], v[52:55]
	v_mfma_f32_16x16x32_bf16 v[56:59], v[148:151], v[180:183], v[56:59]
	v_mfma_f32_16x16x32_bf16 v[56:59], v[152:155], v[192:195], v[56:59]
	v_mfma_f32_16x16x32_bf16 v[24:27], v[148:151], v[204:207], v[24:27]
	v_mfma_f32_16x16x32_bf16 v[24:27], v[152:155], v[208:211], v[24:27]
	v_mfma_f32_16x16x32_bf16 v[20:23], v[172:175], v[204:207], v[20:23]
	v_mfma_f32_16x16x32_bf16 v[20:23], v[176:179], v[208:211], v[20:23]
	v_mfma_f32_16x16x32_bf16 v[4:7], v[172:175], v[212:215], v[4:7]
	v_mfma_f32_16x16x32_bf16 v[4:7], v[176:179], v[216:219], v[4:7]
	v_mfma_f32_16x16x32_bf16 v[8:11], v[148:151], v[212:215], v[8:11]
	v_mfma_f32_16x16x32_bf16 v[8:11], v[152:155], v[216:219], v[8:11]
	v_mfma_f32_16x16x32_bf16 v[12:15], v[140:143], v[212:215], v[12:15]
	v_mfma_f32_16x16x32_bf16 v[12:15], v[144:147], v[216:219], v[12:15]
	v_mfma_f32_16x16x32_bf16 v[16:19], v[132:135], v[212:215], v[16:19]
	v_mfma_f32_16x16x32_bf16 v[16:19], v[136:139], v[216:219], v[16:19]
	v_mfma_f32_16x16x32_bf16 v[32:35], v[132:135], v[204:207], v[32:35]
	v_mfma_f32_16x16x32_bf16 v[32:35], v[136:139], v[208:211], v[32:35]
	v_mfma_f32_16x16x32_bf16 v[28:31], v[140:143], v[204:207], v[28:31]
	v_mfma_f32_16x16x32_bf16 v[28:31], v[144:147], v[208:211], v[28:31]
	s_setprio 0
	s_barrier
	s_add_i32 s0, 0, 0x18000
	s_add_i32 s65, 0, 0x1c000
	v_add_u32_e32 v144, s0, v3
	v_add_u32_e32 v176, s65, v3
	ds_read_b128 v[132:135], v144
	ds_read_b128 v[136:139], v144 offset:1024
	ds_read_b128 v[140:143], v144 offset:2048
	ds_read_b128 v[144:147], v144 offset:3072
	ds_read_b128 v[148:151], v176
	ds_read_b128 v[152:155], v176 offset:1024
	ds_read_b128 v[172:175], v176 offset:2048
	ds_read_b128 v[176:179], v176 offset:3072
	s_add_u32 s98, s52, 0x20000
	s_addc_u32 s99, s53, 0
	s_mov_b32 m0, s47
	ds_read_b128 v[180:183], v189 offset:32768
	ds_read_b128 v[192:195], v189 offset:33792
	ds_read_b128 v[196:199], v189 offset:34816
	ds_read_b128 v[200:203], v189 offset:35840
	ds_read_b128 v[204:207], v189 offset:36864
	ds_read_b128 v[208:211], v189 offset:37888
	ds_read_b128 v[212:215], v189 offset:38912
	ds_read_b128 v[216:219], v189 offset:39936
	global_load_lds_dwordx4 v156, s[98:99]
	s_mov_b32 m0, s48
	s_nop 0
	global_load_lds_dwordx4 v160, s[98:99]
	s_waitcnt vmcnt(8)
	s_waitcnt lgkmcnt(0)
	s_setprio 1
	s_barrier
	v_mfma_f32_16x16x32_bf16 v[128:131], v[132:135], v[180:183], v[128:131]
	v_mfma_f32_16x16x32_bf16 v[128:131], v[136:139], v[192:195], v[128:131]
	v_mfma_f32_16x16x32_bf16 v[124:127], v[140:143], v[180:183], v[124:127]
	v_mfma_f32_16x16x32_bf16 v[124:127], v[144:147], v[192:195], v[124:127]
	v_mfma_f32_16x16x32_bf16 v[108:111], v[140:143], v[196:199], v[108:111]
	v_mfma_f32_16x16x32_bf16 v[108:111], v[144:147], v[200:203], v[108:111]
	v_mfma_f32_16x16x32_bf16 v[112:115], v[132:135], v[196:199], v[112:115]
	v_mfma_f32_16x16x32_bf16 v[112:115], v[136:139], v[200:203], v[112:115]
	v_mfma_f32_16x16x32_bf16 v[104:107], v[148:151], v[196:199], v[104:107]
	v_mfma_f32_16x16x32_bf16 v[104:107], v[152:155], v[200:203], v[104:107]
	v_mfma_f32_16x16x32_bf16 v[100:103], v[172:175], v[196:199], v[100:103]
	v_mfma_f32_16x16x32_bf16 v[100:103], v[176:179], v[200:203], v[100:103]
	v_mfma_f32_16x16x32_bf16 v[116:119], v[172:175], v[180:183], v[116:119]
	v_mfma_f32_16x16x32_bf16 v[116:119], v[176:179], v[192:195], v[116:119]
	v_mfma_f32_16x16x32_bf16 v[120:123], v[148:151], v[180:183], v[120:123]
	v_mfma_f32_16x16x32_bf16 v[120:123], v[152:155], v[192:195], v[120:123]
	v_mfma_f32_16x16x32_bf16 v[88:91], v[148:151], v[204:207], v[88:91]
	v_mfma_f32_16x16x32_bf16 v[88:91], v[152:155], v[208:211], v[88:91]
	v_mfma_f32_16x16x32_bf16 v[84:87], v[172:175], v[204:207], v[84:87]
	v_mfma_f32_16x16x32_bf16 v[84:87], v[176:179], v[208:211], v[84:87]
	v_mfma_f32_16x16x32_bf16 v[68:71], v[172:175], v[212:215], v[68:71]
	v_mfma_f32_16x16x32_bf16 v[68:71], v[176:179], v[216:219], v[68:71]
	v_mfma_f32_16x16x32_bf16 v[72:75], v[148:151], v[212:215], v[72:75]
	v_mfma_f32_16x16x32_bf16 v[72:75], v[152:155], v[216:219], v[72:75]
	v_mfma_f32_16x16x32_bf16 v[76:79], v[140:143], v[212:215], v[76:79]
	v_mfma_f32_16x16x32_bf16 v[76:79], v[144:147], v[216:219], v[76:79]
	v_mfma_f32_16x16x32_bf16 v[80:83], v[132:135], v[212:215], v[80:83]
	v_mfma_f32_16x16x32_bf16 v[80:83], v[136:139], v[216:219], v[80:83]
	v_mfma_f32_16x16x32_bf16 v[96:99], v[132:135], v[204:207], v[96:99]
	v_mfma_f32_16x16x32_bf16 v[96:99], v[136:139], v[208:211], v[96:99]
	v_mfma_f32_16x16x32_bf16 v[92:95], v[140:143], v[204:207], v[92:95]
	v_mfma_f32_16x16x32_bf16 v[92:95], v[144:147], v[208:211], v[92:95]
	s_setprio 0
	s_barrier
	s_add_i32 s0, s0, s45
	s_add_i32 m0, s0, 0xffffff80
	ds_read_b128 v[180:183], v189 offset:49152
	ds_read_b128 v[192:195], v189 offset:50176
	ds_read_b128 v[196:199], v189 offset:51200
	ds_read_b128 v[200:203], v189 offset:52224
	ds_read_b128 v[204:207], v189 offset:53248
	ds_read_b128 v[208:211], v189 offset:54272
	ds_read_b128 v[212:215], v189 offset:55296
	ds_read_b128 v[216:219], v189 offset:56320
	global_load_lds_dwordx4 v158, s[50:51] offset:128
	s_add_i32 m0, s0, 0x1f80
	s_add_i32 s0, s65, s45
	global_load_lds_dwordx4 v162, s[50:51] offset:128
	s_add_u32 s50, s50, 0x20080
	s_addc_u32 s51, s51, 0
	s_mov_b32 m0, s0
	s_nop 0
	global_load_lds_dwordx4 v158, s[50:51]
	s_add_i32 m0, s0, 0x2000
	s_nop 0
	global_load_lds_dwordx4 v162, s[50:51]
	s_add_i32 m0, s56, 0xffffff80
	s_nop 0
	global_load_lds_dwordx4 v156, s[52:53] offset:128
	s_add_i32 m0, s57, 0xffffff80
	s_nop 0
	global_load_lds_dwordx4 v160, s[52:53] offset:128
	s_waitcnt vmcnt(8)
	s_waitcnt lgkmcnt(0)
	s_setprio 1
	s_barrier
	v_mfma_f32_16x16x32_bf16 v[64:67], v[132:135], v[180:183], v[64:67]
	v_mfma_f32_16x16x32_bf16 v[64:67], v[136:139], v[192:195], v[64:67]
	v_mfma_f32_16x16x32_bf16 v[60:63], v[140:143], v[180:183], v[60:63]
	v_mfma_f32_16x16x32_bf16 v[60:63], v[144:147], v[192:195], v[60:63]
	v_mfma_f32_16x16x32_bf16 v[44:47], v[140:143], v[196:199], v[44:47]
	v_mfma_f32_16x16x32_bf16 v[44:47], v[144:147], v[200:203], v[44:47]
	v_mfma_f32_16x16x32_bf16 v[48:51], v[132:135], v[196:199], v[48:51]
	v_mfma_f32_16x16x32_bf16 v[48:51], v[136:139], v[200:203], v[48:51]
	v_mfma_f32_16x16x32_bf16 v[40:43], v[148:151], v[196:199], v[40:43]
	v_mfma_f32_16x16x32_bf16 v[40:43], v[152:155], v[200:203], v[40:43]
	v_mfma_f32_16x16x32_bf16 v[36:39], v[172:175], v[196:199], v[36:39]
	v_mfma_f32_16x16x32_bf16 v[36:39], v[176:179], v[200:203], v[36:39]
	v_mfma_f32_16x16x32_bf16 v[52:55], v[172:175], v[180:183], v[52:55]
	v_mfma_f32_16x16x32_bf16 v[52:55], v[176:179], v[192:195], v[52:55]
	v_mfma_f32_16x16x32_bf16 v[56:59], v[148:151], v[180:183], v[56:59]
	v_mfma_f32_16x16x32_bf16 v[56:59], v[152:155], v[192:195], v[56:59]
	v_mfma_f32_16x16x32_bf16 v[24:27], v[148:151], v[204:207], v[24:27]
	v_mfma_f32_16x16x32_bf16 v[24:27], v[152:155], v[208:211], v[24:27]
	v_mfma_f32_16x16x32_bf16 v[20:23], v[172:175], v[204:207], v[20:23]
	v_mfma_f32_16x16x32_bf16 v[20:23], v[176:179], v[208:211], v[20:23]
	v_mfma_f32_16x16x32_bf16 v[4:7], v[172:175], v[212:215], v[4:7]
	v_mfma_f32_16x16x32_bf16 v[4:7], v[176:179], v[216:219], v[4:7]
	v_mfma_f32_16x16x32_bf16 v[8:11], v[148:151], v[212:215], v[8:11]
	v_mfma_f32_16x16x32_bf16 v[8:11], v[152:155], v[216:219], v[8:11]
	v_mfma_f32_16x16x32_bf16 v[12:15], v[140:143], v[212:215], v[12:15]
	v_mfma_f32_16x16x32_bf16 v[12:15], v[144:147], v[216:219], v[12:15]
	v_mfma_f32_16x16x32_bf16 v[16:19], v[132:135], v[212:215], v[16:19]
	v_mfma_f32_16x16x32_bf16 v[16:19], v[136:139], v[216:219], v[16:19]
	v_mfma_f32_16x16x32_bf16 v[32:35], v[132:135], v[204:207], v[32:35]
	v_mfma_f32_16x16x32_bf16 v[32:35], v[136:139], v[208:211], v[32:35]
	v_mfma_f32_16x16x32_bf16 v[28:31], v[140:143], v[204:207], v[28:31]
	v_mfma_f32_16x16x32_bf16 v[28:31], v[144:147], v[208:211], v[28:31]
	s_setprio 0
	s_barrier
	s_add_i32 s64, s64, 2
	s_add_u32 s42, s42, 0x100
	s_addc_u32 s43, s43, 0
	s_add_u32 s62, s62, 0x100
	s_addc_u32 s63, s63, 0
	s_cmp_gt_u32 s64, 5
	s_cbranch_scc0 .LBB0_1415
	s_and_b64 vcc, exec, s[16:17]
	s_cbranch_vccz .LBB0_1418
	s_barrier

.LBB0_1503:
	ds_read_b128 v[132:135], v159
	ds_read_b128 v[164:167], v159 offset:1024
	ds_read_b128 v[168:171], v159 offset:2048
	ds_read_b128 v[172:175], v159 offset:3072
	ds_read_b128 v[176:179], v160
	ds_read_b128 v[180:183], v160 offset:1024
	ds_read_b128 v[184:187], v160 offset:2048
	ds_read_b128 v[188:191], v160 offset:3072
	s_add_u32 s0, s54, 0xfff00080
	s_addc_u32 s56, s55, -1
	s_cmp_eq_u32 s75, 60
	s_cselect_b32 s59, s31, s56
	s_cselect_b32 s58, s71, s0
	s_cselect_b32 s57, s29, s74
	s_cselect_b32 s56, s72, s73
	s_add_i32 m0, s48, 0xc000
	ds_read_b128 v[192:195], v161
	ds_read_b128 v[196:199], v161 offset:1024
	ds_read_b128 v[200:203], v161 offset:2048
	ds_read_b128 v[204:207], v161 offset:3072
	ds_read_b128 v[208:211], v161 offset:4096
	ds_read_b128 v[212:215], v161 offset:5120
	ds_read_b128 v[216:219], v161 offset:6144
	ds_read_b128 v[220:223], v161 offset:7168
	global_load_lds_dwordx4 v148, s[54:55]
	s_add_i32 m0, s48, 0xe000
	s_nop 0
	global_load_lds_dwordx4 v150, s[54:55]
	s_waitcnt vmcnt(8)
	s_waitcnt lgkmcnt(0)
	s_setprio 1
	s_barrier
	v_mfma_f32_16x16x32_bf16 v[136:139], v[132:135], v[192:195], v[136:139]
	v_mfma_f32_16x16x32_bf16 v[136:139], v[164:167], v[196:199], v[136:139]
	v_mfma_f32_16x16x32_bf16 v[128:131], v[168:171], v[192:195], v[128:131]
	v_mfma_f32_16x16x32_bf16 v[128:131], v[172:175], v[196:199], v[128:131]
	v_mfma_f32_16x16x32_bf16 v[112:115], v[168:171], v[200:203], v[112:115]
	v_mfma_f32_16x16x32_bf16 v[112:115], v[172:175], v[204:207], v[112:115]
	v_mfma_f32_16x16x32_bf16 v[116:119], v[132:135], v[200:203], v[116:119]
	v_mfma_f32_16x16x32_bf16 v[116:119], v[164:167], v[204:207], v[116:119]
	v_mfma_f32_16x16x32_bf16 v[108:111], v[176:179], v[200:203], v[108:111]
	v_mfma_f32_16x16x32_bf16 v[108:111], v[180:183], v[204:207], v[108:111]
	v_mfma_f32_16x16x32_bf16 v[104:107], v[184:187], v[200:203], v[104:107]
	v_mfma_f32_16x16x32_bf16 v[104:107], v[188:191], v[204:207], v[104:107]
	v_mfma_f32_16x16x32_bf16 v[120:123], v[184:187], v[192:195], v[120:123]
	v_mfma_f32_16x16x32_bf16 v[120:123], v[188:191], v[196:199], v[120:123]
	v_mfma_f32_16x16x32_bf16 v[124:127], v[176:179], v[192:195], v[124:127]
	v_mfma_f32_16x16x32_bf16 v[124:127], v[180:183], v[196:199], v[124:127]
	v_mfma_f32_16x16x32_bf16 v[92:95], v[176:179], v[208:211], v[92:95]
	v_mfma_f32_16x16x32_bf16 v[92:95], v[180:183], v[212:215], v[92:95]
	v_mfma_f32_16x16x32_bf16 v[88:91], v[184:187], v[208:211], v[88:91]
	v_mfma_f32_16x16x32_bf16 v[88:91], v[188:191], v[212:215], v[88:91]
	v_mfma_f32_16x16x32_bf16 v[72:75], v[184:187], v[216:219], v[72:75]
	v_mfma_f32_16x16x32_bf16 v[72:75], v[188:191], v[220:223], v[72:75]
	v_mfma_f32_16x16x32_bf16 v[76:79], v[176:179], v[216:219], v[76:79]
	v_mfma_f32_16x16x32_bf16 v[76:79], v[180:183], v[220:223], v[76:79]
	v_mfma_f32_16x16x32_bf16 v[80:83], v[168:171], v[216:219], v[80:83]
	v_mfma_f32_16x16x32_bf16 v[80:83], v[172:175], v[220:223], v[80:83]
	v_mfma_f32_16x16x32_bf16 v[84:87], v[132:135], v[216:219], v[84:87]
	v_mfma_f32_16x16x32_bf16 v[84:87], v[164:167], v[220:223], v[84:87]
	v_mfma_f32_16x16x32_bf16 v[100:103], v[132:135], v[208:211], v[100:103]
	v_mfma_f32_16x16x32_bf16 v[100:103], v[164:167], v[212:215], v[100:103]
	v_mfma_f32_16x16x32_bf16 v[96:99], v[168:171], v[208:211], v[96:99]
	v_mfma_f32_16x16x32_bf16 v[96:99], v[172:175], v[212:215], v[96:99]
	s_setprio 0
	s_barrier
	s_add_i32 s0, s65, s47
	s_mov_b32 m0, s0
	ds_read_b128 v[192:195], v161 offset:16384
	ds_read_b128 v[196:199], v161 offset:17408
	ds_read_b128 v[200:203], v161 offset:18432
	ds_read_b128 v[204:207], v161 offset:19456
	ds_read_b128 v[208:211], v161 offset:20480
	ds_read_b128 v[212:215], v161 offset:21504
	ds_read_b128 v[216:219], v161 offset:22528
	ds_read_b128 v[220:223], v161 offset:23552
	global_load_lds_dwordx4 v142, s[56:57]
	s_add_i32 m0, s0, 0x2000
	s_add_u32 s76, s56, 0x100000
	s_addc_u32 s77, s57, 0
	s_add_i32 s0, s66, s47
	global_load_lds_dwordx4 v146, s[56:57]
	s_mov_b32 m0, s0
	s_nop 0
	global_load_lds_dwordx4 v142, s[76:77]
	s_add_i32 m0, s0, 0x2000
	s_nop 0
	global_load_lds_dwordx4 v146, s[76:77]
	s_mov_b32 m0, s48
	s_nop 0
	global_load_lds_dwordx4 v140, s[58:59]
	s_mov_b32 m0, s49
	s_nop 0
	global_load_lds_dwordx4 v144, s[58:59]
	s_waitcnt vmcnt(8)
	s_waitcnt lgkmcnt(0)
	s_setprio 1
	s_barrier
	v_mfma_f32_16x16x32_bf16 v[68:71], v[132:135], v[192:195], v[68:71]
	v_mfma_f32_16x16x32_bf16 v[68:71], v[164:167], v[196:199], v[68:71]
	v_mfma_f32_16x16x32_bf16 v[64:67], v[168:171], v[192:195], v[64:67]
	v_mfma_f32_16x16x32_bf16 v[64:67], v[172:175], v[196:199], v[64:67]
	v_mfma_f32_16x16x32_bf16 v[48:51], v[168:171], v[200:203], v[48:51]
	v_mfma_f32_16x16x32_bf16 v[48:51], v[172:175], v[204:207], v[48:51]
	v_mfma_f32_16x16x32_bf16 v[52:55], v[132:135], v[200:203], v[52:55]
	v_mfma_f32_16x16x32_bf16 v[52:55], v[164:167], v[204:207], v[52:55]
	v_mfma_f32_16x16x32_bf16 v[44:47], v[176:179], v[200:203], v[44:47]
	v_mfma_f32_16x16x32_bf16 v[44:47], v[180:183], v[204:207], v[44:47]
	v_mfma_f32_16x16x32_bf16 v[40:43], v[184:187], v[200:203], v[40:43]
	v_mfma_f32_16x16x32_bf16 v[40:43], v[188:191], v[204:207], v[40:43]
	v_mfma_f32_16x16x32_bf16 v[56:59], v[184:187], v[192:195], v[56:59]
	v_mfma_f32_16x16x32_bf16 v[56:59], v[188:191], v[196:199], v[56:59]
	v_mfma_f32_16x16x32_bf16 v[60:63], v[176:179], v[192:195], v[60:63]
	v_mfma_f32_16x16x32_bf16 v[60:63], v[180:183], v[196:199], v[60:63]
	v_mfma_f32_16x16x32_bf16 v[28:31], v[176:179], v[208:211], v[28:31]
	v_mfma_f32_16x16x32_bf16 v[28:31], v[180:183], v[212:215], v[28:31]
	v_mfma_f32_16x16x32_bf16 v[24:27], v[184:187], v[208:211], v[24:27]
	v_mfma_f32_16x16x32_bf16 v[24:27], v[188:191], v[212:215], v[24:27]
	v_mfma_f32_16x16x32_bf16 v[8:11], v[184:187], v[216:219], v[8:11]
	v_mfma_f32_16x16x32_bf16 v[8:11], v[188:191], v[220:223], v[8:11]
	v_mfma_f32_16x16x32_bf16 v[12:15], v[176:179], v[216:219], v[12:15]
	v_mfma_f32_16x16x32_bf16 v[12:15], v[180:183], v[220:223], v[12:15]
	v_mfma_f32_16x16x32_bf16 v[16:19], v[168:171], v[216:219], v[16:19]
	v_mfma_f32_16x16x32_bf16 v[16:19], v[172:175], v[220:223], v[16:19]
	v_mfma_f32_16x16x32_bf16 v[20:23], v[132:135], v[216:219], v[20:23]
	v_mfma_f32_16x16x32_bf16 v[20:23], v[164:167], v[220:223], v[20:23]
	v_mfma_f32_16x16x32_bf16 v[36:39], v[132:135], v[208:211], v[36:39]
	v_mfma_f32_16x16x32_bf16 v[36:39], v[164:167], v[212:215], v[36:39]
	v_mfma_f32_16x16x32_bf16 v[32:35], v[168:171], v[208:211], v[32:35]
	v_mfma_f32_16x16x32_bf16 v[32:35], v[172:175], v[212:215], v[32:35]
	s_setprio 0
	s_barrier
	s_add_i32 s0, 0, 0x18000
	s_add_i32 s76, 0, 0x1c000
	v_add_u32_e32 v172, s0, v156
	v_add_u32_e32 v188, s76, v156
	ds_read_b128 v[132:135], v172
	ds_read_b128 v[164:167], v172 offset:1024
	ds_read_b128 v[168:171], v172 offset:2048
	ds_read_b128 v[172:175], v172 offset:3072
	ds_read_b128 v[176:179], v188
	ds_read_b128 v[180:183], v188 offset:1024
	ds_read_b128 v[184:187], v188 offset:2048
	ds_read_b128 v[188:191], v188 offset:3072
	s_add_u32 s98, s58, 0x100000
	s_addc_u32 s99, s59, 0
	s_mov_b32 m0, s51
	ds_read_b128 v[192:195], v161 offset:32768
	ds_read_b128 v[196:199], v161 offset:33792
	ds_read_b128 v[200:203], v161 offset:34816
	ds_read_b128 v[204:207], v161 offset:35840
	ds_read_b128 v[208:211], v161 offset:36864
	ds_read_b128 v[212:215], v161 offset:37888
	ds_read_b128 v[216:219], v161 offset:38912
	ds_read_b128 v[220:223], v161 offset:39936
	global_load_lds_dwordx4 v140, s[98:99]
	s_mov_b32 m0, s53
	s_nop 0
	global_load_lds_dwordx4 v144, s[98:99]
	s_waitcnt vmcnt(8)
	s_waitcnt lgkmcnt(0)
	s_setprio 1
	s_barrier
	v_mfma_f32_16x16x32_bf16 v[136:139], v[132:135], v[192:195], v[136:139]
	v_mfma_f32_16x16x32_bf16 v[136:139], v[164:167], v[196:199], v[136:139]
	v_mfma_f32_16x16x32_bf16 v[128:131], v[168:171], v[192:195], v[128:131]
	v_mfma_f32_16x16x32_bf16 v[128:131], v[172:175], v[196:199], v[128:131]
	v_mfma_f32_16x16x32_bf16 v[112:115], v[168:171], v[200:203], v[112:115]
	v_mfma_f32_16x16x32_bf16 v[112:115], v[172:175], v[204:207], v[112:115]
	v_mfma_f32_16x16x32_bf16 v[116:119], v[132:135], v[200:203], v[116:119]
	v_mfma_f32_16x16x32_bf16 v[116:119], v[164:167], v[204:207], v[116:119]
	v_mfma_f32_16x16x32_bf16 v[108:111], v[176:179], v[200:203], v[108:111]
	v_mfma_f32_16x16x32_bf16 v[108:111], v[180:183], v[204:207], v[108:111]
	v_mfma_f32_16x16x32_bf16 v[104:107], v[184:187], v[200:203], v[104:107]
	v_mfma_f32_16x16x32_bf16 v[104:107], v[188:191], v[204:207], v[104:107]
	v_mfma_f32_16x16x32_bf16 v[120:123], v[184:187], v[192:195], v[120:123]
	v_mfma_f32_16x16x32_bf16 v[120:123], v[188:191], v[196:199], v[120:123]
	v_mfma_f32_16x16x32_bf16 v[124:127], v[176:179], v[192:195], v[124:127]
	v_mfma_f32_16x16x32_bf16 v[124:127], v[180:183], v[196:199], v[124:127]
	v_mfma_f32_16x16x32_bf16 v[92:95], v[176:179], v[208:211], v[92:95]
	v_mfma_f32_16x16x32_bf16 v[92:95], v[180:183], v[212:215], v[92:95]
	v_mfma_f32_16x16x32_bf16 v[88:91], v[184:187], v[208:211], v[88:91]
	v_mfma_f32_16x16x32_bf16 v[88:91], v[188:191], v[212:215], v[88:91]
	v_mfma_f32_16x16x32_bf16 v[72:75], v[184:187], v[216:219], v[72:75]
	v_mfma_f32_16x16x32_bf16 v[72:75], v[188:191], v[220:223], v[72:75]
	v_mfma_f32_16x16x32_bf16 v[76:79], v[176:179], v[216:219], v[76:79]
	v_mfma_f32_16x16x32_bf16 v[76:79], v[180:183], v[220:223], v[76:79]
	v_mfma_f32_16x16x32_bf16 v[80:83], v[168:171], v[216:219], v[80:83]
	v_mfma_f32_16x16x32_bf16 v[80:83], v[172:175], v[220:223], v[80:83]
	v_mfma_f32_16x16x32_bf16 v[84:87], v[132:135], v[216:219], v[84:87]
	v_mfma_f32_16x16x32_bf16 v[84:87], v[164:167], v[220:223], v[84:87]
	v_mfma_f32_16x16x32_bf16 v[100:103], v[132:135], v[208:211], v[100:103]
	v_mfma_f32_16x16x32_bf16 v[100:103], v[164:167], v[212:215], v[100:103]
	v_mfma_f32_16x16x32_bf16 v[96:99], v[168:171], v[208:211], v[96:99]
	v_mfma_f32_16x16x32_bf16 v[96:99], v[172:175], v[212:215], v[96:99]
	s_setprio 0
	s_barrier
	s_add_i32 s0, s0, s47
	s_add_i32 m0, s0, 0xffffff80
	ds_read_b128 v[192:195], v161 offset:49152
	ds_read_b128 v[196:199], v161 offset:50176
	ds_read_b128 v[200:203], v161 offset:51200
	ds_read_b128 v[204:207], v161 offset:52224
	ds_read_b128 v[208:211], v161 offset:53248
	ds_read_b128 v[212:215], v161 offset:54272
	ds_read_b128 v[216:219], v161 offset:55296
	ds_read_b128 v[220:223], v161 offset:56320
	global_load_lds_dwordx4 v142, s[56:57] offset:128
	s_add_i32 m0, s0, 0x1f80
	s_add_i32 s0, s76, s47
	global_load_lds_dwordx4 v146, s[56:57] offset:128
	s_add_u32 s56, s56, 0x100080
	s_addc_u32 s57, s57, 0
	s_mov_b32 m0, s0
	s_nop 0
	global_load_lds_dwordx4 v142, s[56:57]
	s_add_i32 m0, s0, 0x2000
	s_nop 0
	global_load_lds_dwordx4 v146, s[56:57]
	s_add_i32 m0, s62, 0xffffff80
	s_nop 0
	global_load_lds_dwordx4 v140, s[58:59] offset:128
	s_add_i32 m0, s63, 0xffffff80
	s_nop 0
	global_load_lds_dwordx4 v144, s[58:59] offset:128
	s_waitcnt vmcnt(8)
	s_waitcnt lgkmcnt(0)
	s_setprio 1
	s_barrier
	v_mfma_f32_16x16x32_bf16 v[68:71], v[132:135], v[192:195], v[68:71]
	v_mfma_f32_16x16x32_bf16 v[68:71], v[164:167], v[196:199], v[68:71]
	v_mfma_f32_16x16x32_bf16 v[64:67], v[168:171], v[192:195], v[64:67]
	v_mfma_f32_16x16x32_bf16 v[64:67], v[172:175], v[196:199], v[64:67]
	v_mfma_f32_16x16x32_bf16 v[48:51], v[168:171], v[200:203], v[48:51]
	v_mfma_f32_16x16x32_bf16 v[48:51], v[172:175], v[204:207], v[48:51]
	v_mfma_f32_16x16x32_bf16 v[52:55], v[132:135], v[200:203], v[52:55]
	v_mfma_f32_16x16x32_bf16 v[52:55], v[164:167], v[204:207], v[52:55]
	v_mfma_f32_16x16x32_bf16 v[44:47], v[176:179], v[200:203], v[44:47]
	v_mfma_f32_16x16x32_bf16 v[44:47], v[180:183], v[204:207], v[44:47]
	v_mfma_f32_16x16x32_bf16 v[40:43], v[184:187], v[200:203], v[40:43]
	v_mfma_f32_16x16x32_bf16 v[40:43], v[188:191], v[204:207], v[40:43]
	v_mfma_f32_16x16x32_bf16 v[56:59], v[184:187], v[192:195], v[56:59]
	v_mfma_f32_16x16x32_bf16 v[56:59], v[188:191], v[196:199], v[56:59]
	v_mfma_f32_16x16x32_bf16 v[60:63], v[176:179], v[192:195], v[60:63]
	v_mfma_f32_16x16x32_bf16 v[60:63], v[180:183], v[196:199], v[60:63]
	v_mfma_f32_16x16x32_bf16 v[28:31], v[176:179], v[208:211], v[28:31]
	v_mfma_f32_16x16x32_bf16 v[28:31], v[180:183], v[212:215], v[28:31]
	v_mfma_f32_16x16x32_bf16 v[24:27], v[184:187], v[208:211], v[24:27]
	v_mfma_f32_16x16x32_bf16 v[24:27], v[188:191], v[212:215], v[24:27]
	v_mfma_f32_16x16x32_bf16 v[8:11], v[184:187], v[216:219], v[8:11]
	v_mfma_f32_16x16x32_bf16 v[8:11], v[188:191], v[220:223], v[8:11]
	v_mfma_f32_16x16x32_bf16 v[12:15], v[176:179], v[216:219], v[12:15]
	v_mfma_f32_16x16x32_bf16 v[12:15], v[180:183], v[220:223], v[12:15]
	v_mfma_f32_16x16x32_bf16 v[16:19], v[168:171], v[216:219], v[16:19]
	v_mfma_f32_16x16x32_bf16 v[16:19], v[172:175], v[220:223], v[16:19]
	v_mfma_f32_16x16x32_bf16 v[20:23], v[132:135], v[216:219], v[20:23]
	v_mfma_f32_16x16x32_bf16 v[20:23], v[164:167], v[220:223], v[20:23]
	v_mfma_f32_16x16x32_bf16 v[36:39], v[132:135], v[208:211], v[36:39]
	v_mfma_f32_16x16x32_bf16 v[36:39], v[164:167], v[212:215], v[36:39]
	v_mfma_f32_16x16x32_bf16 v[32:35], v[168:171], v[208:211], v[32:35]
	v_mfma_f32_16x16x32_bf16 v[32:35], v[172:175], v[212:215], v[32:35]
	s_setprio 0
	s_barrier
	s_add_i32 s75, s75, 2
	s_add_u32 s54, s54, 0x100
	s_addc_u32 s55, s55, 0
	s_add_u32 s73, s73, 0x100
	s_addc_u32 s74, s74, 0
	s_cmp_gt_u32 s75, 61
	s_cbranch_scc0 .LBB0_1503
	s_and_b64 vcc, exec, s[26:27]
	s_cbranch_vccz .LBB0_1506
	s_barrier

.LBB0_1672:
	ds_read_b128 v[132:135], v193
	ds_read_b128 v[136:139], v193 offset:1024
	ds_read_b128 v[140:143], v193 offset:2048
	ds_read_b128 v[144:147], v193 offset:3072
	ds_read_b128 v[148:151], v194
	ds_read_b128 v[152:155], v194 offset:1024
	ds_read_b128 v[172:175], v194 offset:2048
	ds_read_b128 v[176:179], v194 offset:3072
	s_add_u32 s0, s30, 0xffd50080
	s_addc_u32 s42, s31, -1
	s_cmpk_eq_i32 s66, 0xa8
	s_cselect_b32 s51, s7, s42
	s_cselect_b32 s50, s6, s0
	s_cselect_b32 s43, s29, s65
	s_cselect_b32 s42, s28, s64
	s_add_i32 m0, s46, 0xc000
	ds_read_b128 v[180:183], v195
	ds_read_b128 v[198:201], v195 offset:1024
	ds_read_b128 v[202:205], v195 offset:2048
	ds_read_b128 v[206:209], v195 offset:3072
	ds_read_b128 v[210:213], v195 offset:4096
	ds_read_b128 v[214:217], v195 offset:5120
	ds_read_b128 v[218:221], v195 offset:6144
	ds_read_b128 v[222:225], v195 offset:7168
	global_load_lds_dwordx4 v164, s[30:31]
	s_add_i32 m0, s46, 0xe000
	s_nop 0
	global_load_lds_dwordx4 v166, s[30:31]
	s_waitcnt vmcnt(8)
	s_waitcnt lgkmcnt(0)
	s_setprio 1
	s_barrier
	v_mfma_f32_16x16x32_bf16 v[128:131], v[132:135], v[180:183], v[128:131]
	v_mfma_f32_16x16x32_bf16 v[128:131], v[136:139], v[198:201], v[128:131]
	v_mfma_f32_16x16x32_bf16 v[124:127], v[140:143], v[180:183], v[124:127]
	v_mfma_f32_16x16x32_bf16 v[124:127], v[144:147], v[198:201], v[124:127]
	v_mfma_f32_16x16x32_bf16 v[108:111], v[140:143], v[202:205], v[108:111]
	v_mfma_f32_16x16x32_bf16 v[108:111], v[144:147], v[206:209], v[108:111]
	v_mfma_f32_16x16x32_bf16 v[112:115], v[132:135], v[202:205], v[112:115]
	v_mfma_f32_16x16x32_bf16 v[112:115], v[136:139], v[206:209], v[112:115]
	v_mfma_f32_16x16x32_bf16 v[104:107], v[148:151], v[202:205], v[104:107]
	v_mfma_f32_16x16x32_bf16 v[104:107], v[152:155], v[206:209], v[104:107]
	v_mfma_f32_16x16x32_bf16 v[100:103], v[172:175], v[202:205], v[100:103]
	v_mfma_f32_16x16x32_bf16 v[100:103], v[176:179], v[206:209], v[100:103]
	v_mfma_f32_16x16x32_bf16 v[116:119], v[172:175], v[180:183], v[116:119]
	v_mfma_f32_16x16x32_bf16 v[116:119], v[176:179], v[198:201], v[116:119]
	v_mfma_f32_16x16x32_bf16 v[120:123], v[148:151], v[180:183], v[120:123]
	v_mfma_f32_16x16x32_bf16 v[120:123], v[152:155], v[198:201], v[120:123]
	v_mfma_f32_16x16x32_bf16 v[88:91], v[148:151], v[210:213], v[88:91]
	v_mfma_f32_16x16x32_bf16 v[88:91], v[152:155], v[214:217], v[88:91]
	v_mfma_f32_16x16x32_bf16 v[84:87], v[172:175], v[210:213], v[84:87]
	v_mfma_f32_16x16x32_bf16 v[84:87], v[176:179], v[214:217], v[84:87]
	v_mfma_f32_16x16x32_bf16 v[68:71], v[172:175], v[218:221], v[68:71]
	v_mfma_f32_16x16x32_bf16 v[68:71], v[176:179], v[222:225], v[68:71]
	v_mfma_f32_16x16x32_bf16 v[72:75], v[148:151], v[218:221], v[72:75]
	v_mfma_f32_16x16x32_bf16 v[72:75], v[152:155], v[222:225], v[72:75]
	v_mfma_f32_16x16x32_bf16 v[76:79], v[140:143], v[218:221], v[76:79]
	v_mfma_f32_16x16x32_bf16 v[76:79], v[144:147], v[222:225], v[76:79]
	v_mfma_f32_16x16x32_bf16 v[80:83], v[132:135], v[218:221], v[80:83]
	v_mfma_f32_16x16x32_bf16 v[80:83], v[136:139], v[222:225], v[80:83]
	v_mfma_f32_16x16x32_bf16 v[96:99], v[132:135], v[210:213], v[96:99]
	v_mfma_f32_16x16x32_bf16 v[96:99], v[136:139], v[214:217], v[96:99]
	v_mfma_f32_16x16x32_bf16 v[92:95], v[140:143], v[210:213], v[92:95]
	v_mfma_f32_16x16x32_bf16 v[92:95], v[144:147], v[214:217], v[92:95]
	s_setprio 0
	s_barrier
	s_add_i32 s0, s57, s45
	s_mov_b32 m0, s0
	ds_read_b128 v[180:183], v195 offset:16384
	ds_read_b128 v[198:201], v195 offset:17408
	ds_read_b128 v[202:205], v195 offset:18432
	ds_read_b128 v[206:209], v195 offset:19456
	ds_read_b128 v[210:213], v195 offset:20480
	ds_read_b128 v[214:217], v195 offset:21504
	ds_read_b128 v[218:221], v195 offset:22528
	ds_read_b128 v[222:225], v195 offset:23552
	global_load_lds_dwordx4 v158, s[42:43]
	s_add_i32 m0, s0, 0x2000
	s_add_u32 s70, s42, 0x2b0000
	s_addc_u32 s71, s43, 0
	s_add_i32 s0, s58, s45
	global_load_lds_dwordx4 v162, s[42:43]
	s_mov_b32 m0, s0
	s_nop 0
	global_load_lds_dwordx4 v158, s[70:71]
	s_add_i32 m0, s0, 0x2000
	s_nop 0
	global_load_lds_dwordx4 v162, s[70:71]
	s_mov_b32 m0, s46
	s_nop 0
	global_load_lds_dwordx4 v156, s[50:51]
	s_mov_b32 m0, s47
	s_nop 0
	global_load_lds_dwordx4 v160, s[50:51]
	s_waitcnt vmcnt(8)
	s_waitcnt lgkmcnt(0)
	s_setprio 1
	s_barrier
	v_mfma_f32_16x16x32_bf16 v[64:67], v[132:135], v[180:183], v[64:67]
	v_mfma_f32_16x16x32_bf16 v[64:67], v[136:139], v[198:201], v[64:67]
	v_mfma_f32_16x16x32_bf16 v[60:63], v[140:143], v[180:183], v[60:63]
	v_mfma_f32_16x16x32_bf16 v[60:63], v[144:147], v[198:201], v[60:63]
	v_mfma_f32_16x16x32_bf16 v[44:47], v[140:143], v[202:205], v[44:47]
	v_mfma_f32_16x16x32_bf16 v[44:47], v[144:147], v[206:209], v[44:47]
	v_mfma_f32_16x16x32_bf16 v[48:51], v[132:135], v[202:205], v[48:51]
	v_mfma_f32_16x16x32_bf16 v[48:51], v[136:139], v[206:209], v[48:51]
	v_mfma_f32_16x16x32_bf16 v[40:43], v[148:151], v[202:205], v[40:43]
	v_mfma_f32_16x16x32_bf16 v[40:43], v[152:155], v[206:209], v[40:43]
	v_mfma_f32_16x16x32_bf16 v[36:39], v[172:175], v[202:205], v[36:39]
	v_mfma_f32_16x16x32_bf16 v[36:39], v[176:179], v[206:209], v[36:39]
	v_mfma_f32_16x16x32_bf16 v[52:55], v[172:175], v[180:183], v[52:55]
	v_mfma_f32_16x16x32_bf16 v[52:55], v[176:179], v[198:201], v[52:55]
	v_mfma_f32_16x16x32_bf16 v[56:59], v[148:151], v[180:183], v[56:59]
	v_mfma_f32_16x16x32_bf16 v[56:59], v[152:155], v[198:201], v[56:59]
	v_mfma_f32_16x16x32_bf16 v[24:27], v[148:151], v[210:213], v[24:27]
	v_mfma_f32_16x16x32_bf16 v[24:27], v[152:155], v[214:217], v[24:27]
	v_mfma_f32_16x16x32_bf16 v[20:23], v[172:175], v[210:213], v[20:23]
	v_mfma_f32_16x16x32_bf16 v[20:23], v[176:179], v[214:217], v[20:23]
	v_mfma_f32_16x16x32_bf16 v[4:7], v[172:175], v[218:221], v[4:7]
	v_mfma_f32_16x16x32_bf16 v[4:7], v[176:179], v[222:225], v[4:7]
	v_mfma_f32_16x16x32_bf16 v[8:11], v[148:151], v[218:221], v[8:11]
	v_mfma_f32_16x16x32_bf16 v[8:11], v[152:155], v[222:225], v[8:11]
	v_mfma_f32_16x16x32_bf16 v[12:15], v[140:143], v[218:221], v[12:15]
	v_mfma_f32_16x16x32_bf16 v[12:15], v[144:147], v[222:225], v[12:15]
	v_mfma_f32_16x16x32_bf16 v[16:19], v[132:135], v[218:221], v[16:19]
	v_mfma_f32_16x16x32_bf16 v[16:19], v[136:139], v[222:225], v[16:19]
	v_mfma_f32_16x16x32_bf16 v[32:35], v[132:135], v[210:213], v[32:35]
	v_mfma_f32_16x16x32_bf16 v[32:35], v[136:139], v[214:217], v[32:35]
	v_mfma_f32_16x16x32_bf16 v[28:31], v[140:143], v[210:213], v[28:31]
	v_mfma_f32_16x16x32_bf16 v[28:31], v[144:147], v[214:217], v[28:31]
	s_setprio 0
	s_barrier
	s_add_i32 s0, 0, 0x18000
	s_add_i32 s67, 0, 0x1c000
	v_add_u32_e32 v144, s0, v191
	v_add_u32_e32 v176, s67, v191
	ds_read_b128 v[132:135], v144
	ds_read_b128 v[136:139], v144 offset:1024
	ds_read_b128 v[140:143], v144 offset:2048
	ds_read_b128 v[144:147], v144 offset:3072
	ds_read_b128 v[148:151], v176
	ds_read_b128 v[152:155], v176 offset:1024
	ds_read_b128 v[172:175], v176 offset:2048
	ds_read_b128 v[176:179], v176 offset:3072
	s_add_u32 s98, s50, 0x2b0000
	s_addc_u32 s99, s51, 0
	s_mov_b32 m0, s48
	ds_read_b128 v[180:183], v195 offset:32768
	ds_read_b128 v[198:201], v195 offset:33792
	ds_read_b128 v[202:205], v195 offset:34816
	ds_read_b128 v[206:209], v195 offset:35840
	ds_read_b128 v[210:213], v195 offset:36864
	ds_read_b128 v[214:217], v195 offset:37888
	ds_read_b128 v[218:221], v195 offset:38912
	ds_read_b128 v[222:225], v195 offset:39936
	global_load_lds_dwordx4 v156, s[98:99]
	s_mov_b32 m0, s49
	s_nop 0
	global_load_lds_dwordx4 v160, s[98:99]
	s_waitcnt vmcnt(8)
	s_waitcnt lgkmcnt(0)
	s_setprio 1
	s_barrier
	v_mfma_f32_16x16x32_bf16 v[128:131], v[132:135], v[180:183], v[128:131]
	v_mfma_f32_16x16x32_bf16 v[128:131], v[136:139], v[198:201], v[128:131]
	v_mfma_f32_16x16x32_bf16 v[124:127], v[140:143], v[180:183], v[124:127]
	v_mfma_f32_16x16x32_bf16 v[124:127], v[144:147], v[198:201], v[124:127]
	v_mfma_f32_16x16x32_bf16 v[108:111], v[140:143], v[202:205], v[108:111]
	v_mfma_f32_16x16x32_bf16 v[108:111], v[144:147], v[206:209], v[108:111]
	v_mfma_f32_16x16x32_bf16 v[112:115], v[132:135], v[202:205], v[112:115]
	v_mfma_f32_16x16x32_bf16 v[112:115], v[136:139], v[206:209], v[112:115]
	v_mfma_f32_16x16x32_bf16 v[104:107], v[148:151], v[202:205], v[104:107]
	v_mfma_f32_16x16x32_bf16 v[104:107], v[152:155], v[206:209], v[104:107]
	v_mfma_f32_16x16x32_bf16 v[100:103], v[172:175], v[202:205], v[100:103]
	v_mfma_f32_16x16x32_bf16 v[100:103], v[176:179], v[206:209], v[100:103]
	v_mfma_f32_16x16x32_bf16 v[116:119], v[172:175], v[180:183], v[116:119]
	v_mfma_f32_16x16x32_bf16 v[116:119], v[176:179], v[198:201], v[116:119]
	v_mfma_f32_16x16x32_bf16 v[120:123], v[148:151], v[180:183], v[120:123]
	v_mfma_f32_16x16x32_bf16 v[120:123], v[152:155], v[198:201], v[120:123]
	v_mfma_f32_16x16x32_bf16 v[88:91], v[148:151], v[210:213], v[88:91]
	v_mfma_f32_16x16x32_bf16 v[88:91], v[152:155], v[214:217], v[88:91]
	v_mfma_f32_16x16x32_bf16 v[84:87], v[172:175], v[210:213], v[84:87]
	v_mfma_f32_16x16x32_bf16 v[84:87], v[176:179], v[214:217], v[84:87]
	v_mfma_f32_16x16x32_bf16 v[68:71], v[172:175], v[218:221], v[68:71]
	v_mfma_f32_16x16x32_bf16 v[68:71], v[176:179], v[222:225], v[68:71]
	v_mfma_f32_16x16x32_bf16 v[72:75], v[148:151], v[218:221], v[72:75]
	v_mfma_f32_16x16x32_bf16 v[72:75], v[152:155], v[222:225], v[72:75]
	v_mfma_f32_16x16x32_bf16 v[76:79], v[140:143], v[218:221], v[76:79]
	v_mfma_f32_16x16x32_bf16 v[76:79], v[144:147], v[222:225], v[76:79]
	v_mfma_f32_16x16x32_bf16 v[80:83], v[132:135], v[218:221], v[80:83]
	v_mfma_f32_16x16x32_bf16 v[80:83], v[136:139], v[222:225], v[80:83]
	v_mfma_f32_16x16x32_bf16 v[96:99], v[132:135], v[210:213], v[96:99]
	v_mfma_f32_16x16x32_bf16 v[96:99], v[136:139], v[214:217], v[96:99]
	v_mfma_f32_16x16x32_bf16 v[92:95], v[140:143], v[210:213], v[92:95]
	v_mfma_f32_16x16x32_bf16 v[92:95], v[144:147], v[214:217], v[92:95]
	s_setprio 0
	s_barrier
	s_add_i32 s0, s0, s45
	s_add_i32 m0, s0, 0xffffff80
	ds_read_b128 v[180:183], v195 offset:49152
	ds_read_b128 v[198:201], v195 offset:50176
	ds_read_b128 v[202:205], v195 offset:51200
	ds_read_b128 v[206:209], v195 offset:52224
	ds_read_b128 v[210:213], v195 offset:53248
	ds_read_b128 v[214:217], v195 offset:54272
	ds_read_b128 v[218:221], v195 offset:55296
	ds_read_b128 v[222:225], v195 offset:56320
	global_load_lds_dwordx4 v158, s[42:43] offset:128
	s_add_i32 m0, s0, 0x1f80
	s_add_i32 s0, s67, s45
	global_load_lds_dwordx4 v162, s[42:43] offset:128
	s_add_u32 s42, s42, 0x2b0080
	s_addc_u32 s43, s43, 0
	s_mov_b32 m0, s0
	s_nop 0
	global_load_lds_dwordx4 v158, s[42:43]
	s_add_i32 m0, s0, 0x2000
	s_nop 0
	global_load_lds_dwordx4 v162, s[42:43]
	s_add_i32 m0, s55, 0xffffff80
	s_nop 0
	global_load_lds_dwordx4 v156, s[50:51] offset:128
	s_add_i32 m0, s56, 0xffffff80
	s_nop 0
	global_load_lds_dwordx4 v160, s[50:51] offset:128
	s_waitcnt vmcnt(8)
	s_waitcnt lgkmcnt(0)
	s_setprio 1
	s_barrier
	v_mfma_f32_16x16x32_bf16 v[64:67], v[132:135], v[180:183], v[64:67]
	v_mfma_f32_16x16x32_bf16 v[64:67], v[136:139], v[198:201], v[64:67]
	v_mfma_f32_16x16x32_bf16 v[60:63], v[140:143], v[180:183], v[60:63]
	v_mfma_f32_16x16x32_bf16 v[60:63], v[144:147], v[198:201], v[60:63]
	v_mfma_f32_16x16x32_bf16 v[44:47], v[140:143], v[202:205], v[44:47]
	v_mfma_f32_16x16x32_bf16 v[44:47], v[144:147], v[206:209], v[44:47]
	v_mfma_f32_16x16x32_bf16 v[48:51], v[132:135], v[202:205], v[48:51]
	v_mfma_f32_16x16x32_bf16 v[48:51], v[136:139], v[206:209], v[48:51]
	v_mfma_f32_16x16x32_bf16 v[40:43], v[148:151], v[202:205], v[40:43]
	v_mfma_f32_16x16x32_bf16 v[40:43], v[152:155], v[206:209], v[40:43]
	v_mfma_f32_16x16x32_bf16 v[36:39], v[172:175], v[202:205], v[36:39]
	v_mfma_f32_16x16x32_bf16 v[36:39], v[176:179], v[206:209], v[36:39]
	v_mfma_f32_16x16x32_bf16 v[52:55], v[172:175], v[180:183], v[52:55]
	v_mfma_f32_16x16x32_bf16 v[52:55], v[176:179], v[198:201], v[52:55]
	v_mfma_f32_16x16x32_bf16 v[56:59], v[148:151], v[180:183], v[56:59]
	v_mfma_f32_16x16x32_bf16 v[56:59], v[152:155], v[198:201], v[56:59]
	v_mfma_f32_16x16x32_bf16 v[24:27], v[148:151], v[210:213], v[24:27]
	v_mfma_f32_16x16x32_bf16 v[24:27], v[152:155], v[214:217], v[24:27]
	v_mfma_f32_16x16x32_bf16 v[20:23], v[172:175], v[210:213], v[20:23]
	v_mfma_f32_16x16x32_bf16 v[20:23], v[176:179], v[214:217], v[20:23]
	v_mfma_f32_16x16x32_bf16 v[4:7], v[172:175], v[218:221], v[4:7]
	v_mfma_f32_16x16x32_bf16 v[4:7], v[176:179], v[222:225], v[4:7]
	v_mfma_f32_16x16x32_bf16 v[8:11], v[148:151], v[218:221], v[8:11]
	v_mfma_f32_16x16x32_bf16 v[8:11], v[152:155], v[222:225], v[8:11]
	v_mfma_f32_16x16x32_bf16 v[12:15], v[140:143], v[218:221], v[12:15]
	v_mfma_f32_16x16x32_bf16 v[12:15], v[144:147], v[222:225], v[12:15]
	v_mfma_f32_16x16x32_bf16 v[16:19], v[132:135], v[218:221], v[16:19]
	v_mfma_f32_16x16x32_bf16 v[16:19], v[136:139], v[222:225], v[16:19]
	v_mfma_f32_16x16x32_bf16 v[32:35], v[132:135], v[210:213], v[32:35]
	v_mfma_f32_16x16x32_bf16 v[32:35], v[136:139], v[214:217], v[32:35]
	v_mfma_f32_16x16x32_bf16 v[28:31], v[140:143], v[210:213], v[28:31]
	v_mfma_f32_16x16x32_bf16 v[28:31], v[144:147], v[214:217], v[28:31]
	s_setprio 0
	s_barrier
	s_add_i32 s66, s66, 2
	s_add_u32 s30, s30, 0x100
	s_addc_u32 s31, s31, 0
	s_add_u32 s64, s64, 0x100
	s_addc_u32 s65, s65, 0
	s_cmpk_gt_u32 s66, 0xa9
	s_cbranch_scc0 .LBB0_1672
	s_and_b64 vcc, exec, s[24:25]
	s_cbranch_vccz .LBB0_1675
	s_barrier

.LBB0_1703:
	ds_read_b128 v[136:139], v196
	ds_read_b128 v[140:143], v196 offset:1024
	ds_read_b128 v[144:147], v196 offset:2048
	ds_read_b128 v[148:151], v196 offset:3072
	ds_read_b128 v[152:155], v197
	ds_read_b128 v[176:179], v197 offset:1024
	ds_read_b128 v[180:183], v197 offset:2048
	ds_read_b128 v[184:187], v197 offset:3072
	s_add_u32 s8, s6, 0x100
	s_addc_u32 s9, s7, 0
	s_add_u32 s0, s65, s6
	s_addc_u32 s40, s66, s7
	s_cmpk_eq_i32 s67, 0xa8
	s_cselect_b32 s43, s50, s40
	s_cselect_b32 s40, 0, s8
	s_cselect_b32 s42, s51, s0
	s_cselect_b32 s0, 0, s9
	s_add_u32 s40, s16, s40
	s_addc_u32 s41, s17, s0
	s_mov_b32 m0, s58
	v_lshl_add_u64 v[226:227], v[132:133], 0, s[6:7]
	ds_read_b128 v[188:191], v198
	ds_read_b128 v[192:195], v198 offset:1024
	ds_read_b128 v[202:205], v198 offset:2048
	ds_read_b128 v[206:209], v198 offset:3072
	ds_read_b128 v[210:213], v198 offset:4096
	ds_read_b128 v[214:217], v198 offset:5120
	ds_read_b128 v[218:221], v198 offset:6144
	ds_read_b128 v[222:225], v198 offset:7168
	global_load_lds_dwordx4 v[226:227], off
	v_lshl_add_u64 v[226:227], v[134:135], 0, s[6:7]
	s_mov_b32 m0, s59
	s_nop 0
	global_load_lds_dwordx4 v[226:227], off
	s_waitcnt vmcnt(8)
	s_waitcnt lgkmcnt(0)
	s_setprio 1
	s_barrier
	v_mfma_f32_16x16x32_bf16 v[128:131], v[136:139], v[188:191], v[128:131]
	v_mfma_f32_16x16x32_bf16 v[128:131], v[140:143], v[192:195], v[128:131]
	v_mfma_f32_16x16x32_bf16 v[124:127], v[144:147], v[188:191], v[124:127]
	v_mfma_f32_16x16x32_bf16 v[124:127], v[148:151], v[192:195], v[124:127]
	v_mfma_f32_16x16x32_bf16 v[108:111], v[144:147], v[202:205], v[108:111]
	v_mfma_f32_16x16x32_bf16 v[108:111], v[148:151], v[206:209], v[108:111]
	v_mfma_f32_16x16x32_bf16 v[112:115], v[136:139], v[202:205], v[112:115]
	v_mfma_f32_16x16x32_bf16 v[112:115], v[140:143], v[206:209], v[112:115]
	v_mfma_f32_16x16x32_bf16 v[104:107], v[152:155], v[202:205], v[104:107]
	v_mfma_f32_16x16x32_bf16 v[104:107], v[176:179], v[206:209], v[104:107]
	v_mfma_f32_16x16x32_bf16 v[100:103], v[180:183], v[202:205], v[100:103]
	v_mfma_f32_16x16x32_bf16 v[100:103], v[184:187], v[206:209], v[100:103]
	v_mfma_f32_16x16x32_bf16 v[116:119], v[180:183], v[188:191], v[116:119]
	v_mfma_f32_16x16x32_bf16 v[116:119], v[184:187], v[192:195], v[116:119]
	v_mfma_f32_16x16x32_bf16 v[120:123], v[152:155], v[188:191], v[120:123]
	v_mfma_f32_16x16x32_bf16 v[120:123], v[176:179], v[192:195], v[120:123]
	v_mfma_f32_16x16x32_bf16 v[88:91], v[152:155], v[210:213], v[88:91]
	v_mfma_f32_16x16x32_bf16 v[88:91], v[176:179], v[214:217], v[88:91]
	v_mfma_f32_16x16x32_bf16 v[84:87], v[180:183], v[210:213], v[84:87]
	v_mfma_f32_16x16x32_bf16 v[84:87], v[184:187], v[214:217], v[84:87]
	v_mfma_f32_16x16x32_bf16 v[68:71], v[180:183], v[218:221], v[68:71]
	v_mfma_f32_16x16x32_bf16 v[68:71], v[184:187], v[222:225], v[68:71]
	v_mfma_f32_16x16x32_bf16 v[72:75], v[152:155], v[218:221], v[72:75]
	v_mfma_f32_16x16x32_bf16 v[72:75], v[176:179], v[222:225], v[72:75]
	v_mfma_f32_16x16x32_bf16 v[76:79], v[144:147], v[218:221], v[76:79]
	v_mfma_f32_16x16x32_bf16 v[76:79], v[148:151], v[222:225], v[76:79]
	v_mfma_f32_16x16x32_bf16 v[80:83], v[136:139], v[218:221], v[80:83]
	v_mfma_f32_16x16x32_bf16 v[80:83], v[140:143], v[222:225], v[80:83]
	v_mfma_f32_16x16x32_bf16 v[96:99], v[136:139], v[210:213], v[96:99]
	v_mfma_f32_16x16x32_bf16 v[96:99], v[140:143], v[214:217], v[96:99]
	v_mfma_f32_16x16x32_bf16 v[92:95], v[144:147], v[210:213], v[92:95]
	v_mfma_f32_16x16x32_bf16 v[92:95], v[148:151], v[214:217], v[92:95]
	s_setprio 0
	s_barrier
	s_mov_b32 m0, s60
	v_lshl_add_u64 v[226:227], s[40:41], 0, v[158:159]
	s_add_u32 s6, s40, 0x2b0000
	ds_read_b128 v[188:191], v198 offset:16384
	ds_read_b128 v[192:195], v198 offset:17408
	ds_read_b128 v[202:205], v198 offset:18432
	ds_read_b128 v[206:209], v198 offset:19456
	ds_read_b128 v[210:213], v198 offset:20480
	ds_read_b128 v[214:217], v198 offset:21504
	ds_read_b128 v[218:221], v198 offset:22528
	ds_read_b128 v[222:225], v198 offset:23552
	global_load_lds_dwordx4 v[226:227], off
	v_lshl_add_u64 v[228:229], s[40:41], 0, v[162:163]
	s_mov_b32 m0, s61
	s_addc_u32 s7, s41, 0
	global_load_lds_dwordx4 v[228:229], off
	v_lshl_add_u64 v[230:231], s[6:7], 0, v[158:159]
	s_mov_b32 m0, s62
	v_lshl_add_u64 v[232:233], s[42:43], 0, v[160:161]
	global_load_lds_dwordx4 v[230:231], off
	v_lshl_add_u64 v[230:231], s[6:7], 0, v[162:163]
	s_mov_b32 m0, s63
	s_nop 0
	global_load_lds_dwordx4 v[230:231], off
	v_lshl_add_u64 v[230:231], s[42:43], 0, v[156:157]
	s_mov_b32 m0, s46
	s_nop 0
	global_load_lds_dwordx4 v[230:231], off
	s_mov_b32 m0, s47
	s_nop 0
	global_load_lds_dwordx4 v[232:233], off
	s_waitcnt vmcnt(8)
	s_waitcnt lgkmcnt(0)
	s_setprio 1
	s_barrier
	v_mfma_f32_16x16x32_bf16 v[64:67], v[136:139], v[188:191], v[64:67]
	v_mfma_f32_16x16x32_bf16 v[64:67], v[140:143], v[192:195], v[64:67]
	v_mfma_f32_16x16x32_bf16 v[60:63], v[144:147], v[188:191], v[60:63]
	v_mfma_f32_16x16x32_bf16 v[60:63], v[148:151], v[192:195], v[60:63]
	v_mfma_f32_16x16x32_bf16 v[44:47], v[144:147], v[202:205], v[44:47]
	v_mfma_f32_16x16x32_bf16 v[44:47], v[148:151], v[206:209], v[44:47]
	v_mfma_f32_16x16x32_bf16 v[48:51], v[136:139], v[202:205], v[48:51]
	v_mfma_f32_16x16x32_bf16 v[48:51], v[140:143], v[206:209], v[48:51]
	v_mfma_f32_16x16x32_bf16 v[40:43], v[152:155], v[202:205], v[40:43]
	v_mfma_f32_16x16x32_bf16 v[40:43], v[176:179], v[206:209], v[40:43]
	v_mfma_f32_16x16x32_bf16 v[36:39], v[180:183], v[202:205], v[36:39]
	v_mfma_f32_16x16x32_bf16 v[36:39], v[184:187], v[206:209], v[36:39]
	v_mfma_f32_16x16x32_bf16 v[52:55], v[180:183], v[188:191], v[52:55]
	v_mfma_f32_16x16x32_bf16 v[52:55], v[184:187], v[192:195], v[52:55]
	v_mfma_f32_16x16x32_bf16 v[56:59], v[152:155], v[188:191], v[56:59]
	v_mfma_f32_16x16x32_bf16 v[56:59], v[176:179], v[192:195], v[56:59]
	v_mfma_f32_16x16x32_bf16 v[24:27], v[152:155], v[210:213], v[24:27]
	v_mfma_f32_16x16x32_bf16 v[24:27], v[176:179], v[214:217], v[24:27]
	v_mfma_f32_16x16x32_bf16 v[20:23], v[180:183], v[210:213], v[20:23]
	v_mfma_f32_16x16x32_bf16 v[20:23], v[184:187], v[214:217], v[20:23]
	v_mfma_f32_16x16x32_bf16 v[4:7], v[180:183], v[218:221], v[4:7]
	v_mfma_f32_16x16x32_bf16 v[4:7], v[184:187], v[222:225], v[4:7]
	v_mfma_f32_16x16x32_bf16 v[8:11], v[152:155], v[218:221], v[8:11]
	v_mfma_f32_16x16x32_bf16 v[8:11], v[176:179], v[222:225], v[8:11]
	v_mfma_f32_16x16x32_bf16 v[12:15], v[144:147], v[218:221], v[12:15]
	v_mfma_f32_16x16x32_bf16 v[12:15], v[148:151], v[222:225], v[12:15]
	v_mfma_f32_16x16x32_bf16 v[16:19], v[136:139], v[218:221], v[16:19]
	v_mfma_f32_16x16x32_bf16 v[16:19], v[140:143], v[222:225], v[16:19]
	v_mfma_f32_16x16x32_bf16 v[32:35], v[136:139], v[210:213], v[32:35]
	v_mfma_f32_16x16x32_bf16 v[32:35], v[140:143], v[214:217], v[32:35]
	v_mfma_f32_16x16x32_bf16 v[28:31], v[144:147], v[210:213], v[28:31]
	v_mfma_f32_16x16x32_bf16 v[28:31], v[148:151], v[214:217], v[28:31]
	s_setprio 0
	s_barrier
	s_add_i32 s0, 0, 0x18000
	s_add_i32 s68, 0, 0x1c000
	v_add_u32_e32 v148, s0, v3
	v_add_u32_e32 v170, s68, v3
	ds_read_b128 v[136:139], v148
	ds_read_b128 v[140:143], v148 offset:1024
	ds_read_b128 v[144:147], v148 offset:2048
	ds_read_b128 v[148:151], v148 offset:3072
	ds_read_b128 v[152:155], v170
	ds_read_b128 v[176:179], v170 offset:1024
	ds_read_b128 v[180:183], v170 offset:2048
	ds_read_b128 v[184:187], v170 offset:3072
	s_add_u32 s6, s42, 0x2b0000
	s_addc_u32 s7, s43, 0
	s_mov_b32 m0, s48
	v_lshl_add_u64 v[234:235], s[6:7], 0, v[156:157]
	ds_read_b128 v[188:191], v198 offset:32768
	ds_read_b128 v[192:195], v198 offset:33792
	ds_read_b128 v[202:205], v198 offset:34816
	ds_read_b128 v[206:209], v198 offset:35840
	ds_read_b128 v[210:213], v198 offset:36864
	ds_read_b128 v[214:217], v198 offset:37888
	ds_read_b128 v[218:221], v198 offset:38912
	ds_read_b128 v[222:225], v198 offset:39936
	global_load_lds_dwordx4 v[234:235], off
	v_lshl_add_u64 v[234:235], s[6:7], 0, v[160:161]
	s_mov_b32 m0, s49
	s_nop 0
	global_load_lds_dwordx4 v[234:235], off
	s_waitcnt vmcnt(8)
	s_waitcnt lgkmcnt(0)
	s_setprio 1
	s_barrier
	v_mfma_f32_16x16x32_bf16 v[128:131], v[136:139], v[188:191], v[128:131]
	v_mfma_f32_16x16x32_bf16 v[128:131], v[140:143], v[192:195], v[128:131]
	v_mfma_f32_16x16x32_bf16 v[124:127], v[144:147], v[188:191], v[124:127]
	v_mfma_f32_16x16x32_bf16 v[124:127], v[148:151], v[192:195], v[124:127]
	v_mfma_f32_16x16x32_bf16 v[108:111], v[144:147], v[202:205], v[108:111]
	v_mfma_f32_16x16x32_bf16 v[108:111], v[148:151], v[206:209], v[108:111]
	v_mfma_f32_16x16x32_bf16 v[112:115], v[136:139], v[202:205], v[112:115]
	v_mfma_f32_16x16x32_bf16 v[112:115], v[140:143], v[206:209], v[112:115]
	v_mfma_f32_16x16x32_bf16 v[104:107], v[152:155], v[202:205], v[104:107]
	v_mfma_f32_16x16x32_bf16 v[104:107], v[176:179], v[206:209], v[104:107]
	v_mfma_f32_16x16x32_bf16 v[100:103], v[180:183], v[202:205], v[100:103]
	v_mfma_f32_16x16x32_bf16 v[100:103], v[184:187], v[206:209], v[100:103]
	v_mfma_f32_16x16x32_bf16 v[116:119], v[180:183], v[188:191], v[116:119]
	v_mfma_f32_16x16x32_bf16 v[116:119], v[184:187], v[192:195], v[116:119]
	v_mfma_f32_16x16x32_bf16 v[120:123], v[152:155], v[188:191], v[120:123]
	v_mfma_f32_16x16x32_bf16 v[120:123], v[176:179], v[192:195], v[120:123]
	v_mfma_f32_16x16x32_bf16 v[88:91], v[152:155], v[210:213], v[88:91]
	v_mfma_f32_16x16x32_bf16 v[88:91], v[176:179], v[214:217], v[88:91]
	v_mfma_f32_16x16x32_bf16 v[84:87], v[180:183], v[210:213], v[84:87]
	v_mfma_f32_16x16x32_bf16 v[84:87], v[184:187], v[214:217], v[84:87]
	v_mfma_f32_16x16x32_bf16 v[68:71], v[180:183], v[218:221], v[68:71]
	v_mfma_f32_16x16x32_bf16 v[68:71], v[184:187], v[222:225], v[68:71]
	v_mfma_f32_16x16x32_bf16 v[72:75], v[152:155], v[218:221], v[72:75]
	v_mfma_f32_16x16x32_bf16 v[72:75], v[176:179], v[222:225], v[72:75]
	v_mfma_f32_16x16x32_bf16 v[76:79], v[144:147], v[218:221], v[76:79]
	v_mfma_f32_16x16x32_bf16 v[76:79], v[148:151], v[222:225], v[76:79]
	v_mfma_f32_16x16x32_bf16 v[80:83], v[136:139], v[218:221], v[80:83]
	v_mfma_f32_16x16x32_bf16 v[80:83], v[140:143], v[222:225], v[80:83]
	v_mfma_f32_16x16x32_bf16 v[96:99], v[136:139], v[210:213], v[96:99]
	v_mfma_f32_16x16x32_bf16 v[96:99], v[140:143], v[214:217], v[96:99]
	v_mfma_f32_16x16x32_bf16 v[92:95], v[144:147], v[210:213], v[92:95]
	v_mfma_f32_16x16x32_bf16 v[92:95], v[148:151], v[214:217], v[92:95]
	s_setprio 0
	s_barrier
	s_add_i32 s0, s0, s45
	v_lshl_add_u64 v[226:227], v[226:227], 0, s[28:29]
	s_mov_b32 m0, s0
	ds_read_b128 v[188:191], v198 offset:49152
	ds_read_b128 v[192:195], v198 offset:50176
	ds_read_b128 v[202:205], v198 offset:51200
	ds_read_b128 v[206:209], v198 offset:52224
	ds_read_b128 v[210:213], v198 offset:53248
	ds_read_b128 v[214:217], v198 offset:54272
	ds_read_b128 v[218:221], v198 offset:55296
	ds_read_b128 v[222:225], v198 offset:56320
	global_load_lds_dwordx4 v[226:227], off
	s_add_i32 m0, s0, 0x2000
	s_add_u32 s6, s40, 0x2b0080
	v_lshl_add_u64 v[226:227], v[228:229], 0, s[28:29]
	s_addc_u32 s7, s41, 0
	s_add_i32 s0, s68, s45
	global_load_lds_dwordx4 v[226:227], off
	v_lshl_add_u64 v[226:227], s[6:7], 0, v[158:159]
	s_mov_b32 m0, s0
	s_nop 0
	global_load_lds_dwordx4 v[226:227], off
	v_lshl_add_u64 v[226:227], s[6:7], 0, v[162:163]
	s_add_i32 m0, s0, 0x2000
	s_nop 0
	global_load_lds_dwordx4 v[226:227], off
	v_lshl_add_u64 v[226:227], v[230:231], 0, s[28:29]
	s_mov_b32 m0, s54
	s_nop 0
	global_load_lds_dwordx4 v[226:227], off
	v_lshl_add_u64 v[226:227], v[232:233], 0, s[28:29]
	s_mov_b32 m0, s55
	s_nop 0
	global_load_lds_dwordx4 v[226:227], off
	s_waitcnt vmcnt(8)
	s_waitcnt lgkmcnt(0)
	s_setprio 1
	s_barrier
	v_mfma_f32_16x16x32_bf16 v[64:67], v[136:139], v[188:191], v[64:67]
	v_mfma_f32_16x16x32_bf16 v[64:67], v[140:143], v[192:195], v[64:67]
	v_mfma_f32_16x16x32_bf16 v[60:63], v[144:147], v[188:191], v[60:63]
	v_mfma_f32_16x16x32_bf16 v[60:63], v[148:151], v[192:195], v[60:63]
	v_mfma_f32_16x16x32_bf16 v[44:47], v[144:147], v[202:205], v[44:47]
	v_mfma_f32_16x16x32_bf16 v[44:47], v[148:151], v[206:209], v[44:47]
	v_mfma_f32_16x16x32_bf16 v[48:51], v[136:139], v[202:205], v[48:51]
	v_mfma_f32_16x16x32_bf16 v[48:51], v[140:143], v[206:209], v[48:51]
	v_mfma_f32_16x16x32_bf16 v[40:43], v[152:155], v[202:205], v[40:43]
	v_mfma_f32_16x16x32_bf16 v[40:43], v[176:179], v[206:209], v[40:43]
	v_mfma_f32_16x16x32_bf16 v[36:39], v[180:183], v[202:205], v[36:39]
	v_mfma_f32_16x16x32_bf16 v[36:39], v[184:187], v[206:209], v[36:39]
	v_mfma_f32_16x16x32_bf16 v[52:55], v[180:183], v[188:191], v[52:55]
	v_mfma_f32_16x16x32_bf16 v[52:55], v[184:187], v[192:195], v[52:55]
	v_mfma_f32_16x16x32_bf16 v[56:59], v[152:155], v[188:191], v[56:59]
	v_mfma_f32_16x16x32_bf16 v[56:59], v[176:179], v[192:195], v[56:59]
	v_mfma_f32_16x16x32_bf16 v[24:27], v[152:155], v[210:213], v[24:27]
	v_mfma_f32_16x16x32_bf16 v[24:27], v[176:179], v[214:217], v[24:27]
	v_mfma_f32_16x16x32_bf16 v[20:23], v[180:183], v[210:213], v[20:23]
	v_mfma_f32_16x16x32_bf16 v[20:23], v[184:187], v[214:217], v[20:23]
	v_mfma_f32_16x16x32_bf16 v[4:7], v[180:183], v[218:221], v[4:7]
	v_mfma_f32_16x16x32_bf16 v[4:7], v[184:187], v[222:225], v[4:7]
	v_mfma_f32_16x16x32_bf16 v[8:11], v[152:155], v[218:221], v[8:11]
	v_mfma_f32_16x16x32_bf16 v[8:11], v[176:179], v[222:225], v[8:11]
	v_mfma_f32_16x16x32_bf16 v[12:15], v[144:147], v[218:221], v[12:15]
	v_mfma_f32_16x16x32_bf16 v[12:15], v[148:151], v[222:225], v[12:15]
	v_mfma_f32_16x16x32_bf16 v[16:19], v[136:139], v[218:221], v[16:19]
	v_mfma_f32_16x16x32_bf16 v[16:19], v[140:143], v[222:225], v[16:19]
	v_mfma_f32_16x16x32_bf16 v[32:35], v[136:139], v[210:213], v[32:35]
	v_mfma_f32_16x16x32_bf16 v[32:35], v[140:143], v[214:217], v[32:35]
	v_mfma_f32_16x16x32_bf16 v[28:31], v[144:147], v[210:213], v[28:31]
	v_mfma_f32_16x16x32_bf16 v[28:31], v[148:151], v[214:217], v[28:31]
	s_setprio 0
	s_barrier
	s_add_i32 s67, s67, 2
	s_cmpk_gt_u32 s67, 0xa9
	s_mov_b64 s[6:7], s[8:9]
	s_cbranch_scc0 .LBB0_1703
	s_and_b64 vcc, exec, s[30:31]
	s_cbranch_vccz .LBB0_1706
	s_barrier
